# ssd_sample state loop hand-scheduled: 32 row loads issued up front, lane reductions 16 at a time
# speedup vs baseline: 1.0205x; 1.0205x over previous
; __device__ __forceinline__ void phaseA(const Params& p, const int wv, const int rep) {
;     ...
;   for (int i = blockIdx.x * NTHREADS + tid; i < 128 * 3072; i += gridDim.x * NTHREADS) {
;     int b = i / 3072, rem = i - b * 3072;
;     p.out[O_CONVS + (size_t)b * 4608 + rem] = p.in[5][(size_t)b * 4608 + 1536 + rem];
;   }
.LBB0_118:
	s_or_b64 exec, exec, s[0:1]
	s_mov_b32 s0, 0x60000
	v_cmp_gt_i32_e32 vcc, s0, v6
	s_and_saveexec_b64 s[0:1], vcc
	v_readlane_b32 s56, v251, 6
	v_readlane_b32 s66, v251, 16
	v_readlane_b32 s67, v251, 17
	v_readlane_b32 s57, v251, 7
	v_readlane_b32 s58, v251, 8
	v_readlane_b32 s59, v251, 9
	v_readlane_b32 s60, v251, 10
	v_readlane_b32 s61, v251, 11
	v_readlane_b32 s62, v251, 12
	v_readlane_b32 s63, v251, 13
	v_readlane_b32 s64, v251, 14
	v_readlane_b32 s65, v251, 15
	v_readlane_b32 s68, v251, 18
	v_readlane_b32 s69, v251, 19
	v_readlane_b32 s70, v251, 20
	v_readlane_b32 s71, v251, 21
	s_cbranch_execz .LBB0_121
	v_readlane_b32 s8, v251, 1
	s_lshl_b32 s10, s8, 9
	s_mov_b64 s[8:9], 0
	s_mov_b32 s11, 0x2aaaaaab
	s_movk_i32 s12, 0xf400
	s_movk_i32 s13, 0x1000
	s_mov_b32 s14, 0x5ffff
	s_cmp_lg_u32 s10, 0x20000
	s_cbranch_scc1 .LBB0_120
	v_mov_b32_e32 v100, v6
	v_mul_hi_i32 v102, v100, s11
	v_lshrrev_b32_e32 v103, 31, v102
	v_ashrrev_i32_e32 v102, 9, v102
	v_add_u32_e32 v103, v102, v103
	v_mad_i32_i24 v102, v103, s12, v100
	v_mul_hi_i32_i24_e32 v105, 0x1200, v103
	v_mul_i32_i24_e32 v104, 0x1200, v103
	v_ashrrev_i32_e32 v103, 31, v102
	v_lshlrev_b64 v[104:105], 2, v[104:105]
	v_lshl_add_u64 v[106:107], s[66:67], 0, v[104:105]
	v_lshlrev_b64 v[102:103], 2, v[102:103]
	v_lshl_add_u64 v[106:107], v[106:107], 0, v[102:103]
	v_add_co_u32_e32 v106, vcc, s13, v106
	s_nop 1
	v_addc_co_u32_e32 v107, vcc, 0, v107, vcc
	global_load_dword v101, v[106:107], off offset:2048
	v_lshl_add_u64 v[104:105], s[48:49], 0, v[104:105]
	v_lshl_add_u64 v[102:103], v[104:105], 0, v[102:103]
	v_add_co_u32_e32 v102, vcc, 0x4ca4000, v102
	s_nop 1
	v_addc_co_u32_e32 v103, vcc, 0, v103, vcc
	v_add_u32_e32 v110, 0x20000, v6
	v_mul_hi_i32 v112, v110, s11
	v_lshrrev_b32_e32 v113, 31, v112
	v_ashrrev_i32_e32 v112, 9, v112
	v_add_u32_e32 v113, v112, v113
	v_mad_i32_i24 v112, v113, s12, v110
	v_mul_hi_i32_i24_e32 v115, 0x1200, v113
	v_mul_i32_i24_e32 v114, 0x1200, v113
	v_ashrrev_i32_e32 v113, 31, v112
	v_lshlrev_b64 v[114:115], 2, v[114:115]
	v_lshl_add_u64 v[116:117], s[66:67], 0, v[114:115]
	v_lshlrev_b64 v[112:113], 2, v[112:113]
	v_lshl_add_u64 v[116:117], v[116:117], 0, v[112:113]
	v_add_co_u32_e32 v116, vcc, s13, v116
	s_nop 1
	v_addc_co_u32_e32 v117, vcc, 0, v117, vcc
	global_load_dword v111, v[116:117], off offset:2048
	v_lshl_add_u64 v[114:115], s[48:49], 0, v[114:115]
	v_lshl_add_u64 v[112:113], v[114:115], 0, v[112:113]
	v_add_co_u32_e32 v112, vcc, 0x4ca4000, v112
	s_nop 1
	v_addc_co_u32_e32 v113, vcc, 0, v113, vcc
	v_add_u32_e32 v120, 0x40000, v6
	v_mul_hi_i32 v122, v120, s11
	v_lshrrev_b32_e32 v123, 31, v122
	v_ashrrev_i32_e32 v122, 9, v122
	v_add_u32_e32 v123, v122, v123
	v_mad_i32_i24 v122, v123, s12, v120
	v_mul_hi_i32_i24_e32 v125, 0x1200, v123
	v_mul_i32_i24_e32 v124, 0x1200, v123
	v_ashrrev_i32_e32 v123, 31, v122
	v_lshlrev_b64 v[124:125], 2, v[124:125]
	v_lshl_add_u64 v[126:127], s[66:67], 0, v[124:125]
	v_lshlrev_b64 v[122:123], 2, v[122:123]
	v_lshl_add_u64 v[126:127], v[126:127], 0, v[122:123]
	v_add_co_u32_e32 v126, vcc, s13, v126
	s_nop 1
	v_addc_co_u32_e32 v127, vcc, 0, v127, vcc
	global_load_dword v121, v[126:127], off offset:2048
	v_lshl_add_u64 v[124:125], s[48:49], 0, v[124:125]
	v_lshl_add_u64 v[122:123], v[124:125], 0, v[122:123]
	v_add_co_u32_e32 v122, vcc, 0x4ca4000, v122
	s_nop 1
	v_addc_co_u32_e32 v123, vcc, 0, v123, vcc
	s_waitcnt vmcnt(2)
	global_store_dword v[102:103], v101, off
	s_waitcnt vmcnt(1)
	global_store_dword v[112:113], v111, off
	s_waitcnt vmcnt(0)
	global_store_dword v[122:123], v121, off
	s_branch .LBB0_121

; __device__ __forceinline__ float shfl_idx_f(float v, int src) { return __int_as_float(__builtin_amdgcn_ds_bpermute(src << 2, __float_as_int(v))); }
; __device__ __forceinline__ void ssd_sample_item(const Params& p, int item, const int wv) {
;     ...
; #pragma unroll 8
;   for (int r = 0; r < 32; ++r) {
;     const int pp = 2 * r + hf;
;     f32x4 hv = *(const f32x4*)(st + (size_t)pp * 128 + n4);
;     const float xp = shfl_idx_f(x, pp) * dt;
;     f32x4 hn;
;     float yp = 0.f;
; #pragma unroll
;     for (int e = 0; e < 4; ++e) { hn[e] = dA * hv[e] + xp * Bv[e]; yp += hn[e] * Cv[e]; }
;     *(f32x4*)(so + (size_t)pp * 128 + n4) = hn;
.LBB0_457:
	v_subrev_u32_e32 v65, 56, v32
	v_mbcnt_lo_u32_b32 v3, -1, 0
	v_mbcnt_hi_u32_b32 v3, -1, v3
	v_lshlrev_b32_e32 v3, 2, v3
	v_xor_b32_e32 v22, 64, v3
	v_xor_b32_e32 v23, 32, v3
	v_xor_b32_e32 v24, 16, v3
	v_xor_b32_e32 v25, 8, v3
	v_xor_b32_e32 v26, 4, v3
	s_mov_b64 s[12:13], 0x0
	v_lshl_add_u64 v[66:67], v[18:19], 0, s[12:13]
	global_load_dwordx4 v[84:87], v[66:67], off
	global_load_dwordx4 v[88:91], v[66:67], off offset:1024
	global_load_dwordx4 v[92:95], v[66:67], off offset:2048
	global_load_dwordx4 v[96:99], v[66:67], off offset:3072
	s_mov_b64 s[12:13], 0x1000
	v_lshl_add_u64 v[66:67], v[18:19], 0, s[12:13]
	global_load_dwordx4 v[100:103], v[66:67], off
	global_load_dwordx4 v[104:107], v[66:67], off offset:1024
	global_load_dwordx4 v[108:111], v[66:67], off offset:2048
	global_load_dwordx4 v[112:115], v[66:67], off offset:3072
	s_mov_b64 s[12:13], 0x2000
	v_lshl_add_u64 v[66:67], v[18:19], 0, s[12:13]
	global_load_dwordx4 v[116:119], v[66:67], off
	global_load_dwordx4 v[120:123], v[66:67], off offset:1024
	global_load_dwordx4 v[124:127], v[66:67], off offset:2048
	global_load_dwordx4 v[128:131], v[66:67], off offset:3072
	s_mov_b64 s[12:13], 0x3000
	v_lshl_add_u64 v[66:67], v[18:19], 0, s[12:13]
	global_load_dwordx4 v[132:135], v[66:67], off
	global_load_dwordx4 v[136:139], v[66:67], off offset:1024
	global_load_dwordx4 v[140:143], v[66:67], off offset:2048
	global_load_dwordx4 v[144:147], v[66:67], off offset:3072
	s_mov_b64 s[12:13], 0x4000
	v_lshl_add_u64 v[66:67], v[18:19], 0, s[12:13]
	global_load_dwordx4 v[148:151], v[66:67], off
	global_load_dwordx4 v[152:155], v[66:67], off offset:1024
	global_load_dwordx4 v[156:159], v[66:67], off offset:2048
	global_load_dwordx4 v[164:167], v[66:67], off offset:3072
	s_mov_b64 s[12:13], 0x5000
	v_lshl_add_u64 v[66:67], v[18:19], 0, s[12:13]
	global_load_dwordx4 v[168:171], v[66:67], off
	global_load_dwordx4 v[172:175], v[66:67], off offset:1024
	global_load_dwordx4 v[176:179], v[66:67], off offset:2048
	global_load_dwordx4 v[180:183], v[66:67], off offset:3072
	s_mov_b64 s[12:13], 0x6000
	v_lshl_add_u64 v[66:67], v[18:19], 0, s[12:13]
	global_load_dwordx4 v[184:187], v[66:67], off
	global_load_dwordx4 v[188:191], v[66:67], off offset:1024
	global_load_dwordx4 v[192:195], v[66:67], off offset:2048
	global_load_dwordx4 v[196:199], v[66:67], off offset:3072
	s_mov_b64 s[12:13], 0x7000
	v_lshl_add_u64 v[66:67], v[18:19], 0, s[12:13]
	global_load_dwordx4 v[200:203], v[66:67], off
	global_load_dwordx4 v[204:207], v[66:67], off offset:1024
	global_load_dwordx4 v[208:211], v[66:67], off offset:2048
	global_load_dwordx4 v[212:215], v[66:67], off offset:3072
	ds_bpermute_b32 v33, v65, v31
	ds_bpermute_b32 v34, v65, v31 offset:8
	ds_bpermute_b32 v35, v65, v31 offset:16
	ds_bpermute_b32 v36, v65, v31 offset:24
	ds_bpermute_b32 v37, v65, v31 offset:32
	ds_bpermute_b32 v38, v65, v31 offset:40
	ds_bpermute_b32 v39, v65, v31 offset:48
	ds_bpermute_b32 v40, v65, v31 offset:56
	ds_bpermute_b32 v41, v65, v31 offset:64
	ds_bpermute_b32 v42, v65, v31 offset:72
	ds_bpermute_b32 v43, v65, v31 offset:80
	ds_bpermute_b32 v44, v65, v31 offset:88
	ds_bpermute_b32 v45, v65, v31 offset:96
	ds_bpermute_b32 v46, v65, v31 offset:104
	ds_bpermute_b32 v47, v65, v31 offset:112
	ds_bpermute_b32 v48, v65, v31 offset:120
	s_waitcnt lgkmcnt(0)
	ds_bpermute_b32 v49, v65, v31 offset:128
	ds_bpermute_b32 v50, v65, v31 offset:136
	ds_bpermute_b32 v51, v65, v31 offset:144
	ds_bpermute_b32 v52, v65, v31 offset:152
	ds_bpermute_b32 v53, v65, v31 offset:160
	ds_bpermute_b32 v54, v65, v31 offset:168
	ds_bpermute_b32 v55, v65, v31 offset:176
	ds_bpermute_b32 v56, v65, v31 offset:184
	ds_bpermute_b32 v57, v65, v31 offset:192
	ds_bpermute_b32 v58, v65, v31 offset:200
	ds_bpermute_b32 v59, v65, v31 offset:208
	ds_bpermute_b32 v60, v65, v31 offset:216
	ds_bpermute_b32 v61, v65, v31 offset:224
	ds_bpermute_b32 v62, v65, v31 offset:232
	ds_bpermute_b32 v63, v65, v31 offset:240
	ds_bpermute_b32 v64, v65, v31 offset:248
	s_waitcnt lgkmcnt(0)
	v_mul_f32_e32 v33, v30, v33
	v_mul_f32_e32 v34, v30, v34
	v_mul_f32_e32 v35, v30, v35
	v_mul_f32_e32 v36, v30, v36
	v_mul_f32_e32 v37, v30, v37
	v_mul_f32_e32 v38, v30, v38
	v_mul_f32_e32 v39, v30, v39
	v_mul_f32_e32 v40, v30, v40
	v_mul_f32_e32 v41, v30, v41
	v_mul_f32_e32 v42, v30, v42
	v_mul_f32_e32 v43, v30, v43
	v_mul_f32_e32 v44, v30, v44
	v_mul_f32_e32 v45, v30, v45
	v_mul_f32_e32 v46, v30, v46
	v_mul_f32_e32 v47, v30, v47
	v_mul_f32_e32 v48, v30, v48
	v_mul_f32_e32 v49, v30, v49
	v_mul_f32_e32 v50, v30, v50
	v_mul_f32_e32 v51, v30, v51
	v_mul_f32_e32 v52, v30, v52
	v_mul_f32_e32 v53, v30, v53
	v_mul_f32_e32 v54, v30, v54
	v_mul_f32_e32 v55, v30, v55
	v_mul_f32_e32 v56, v30, v56
	v_mul_f32_e32 v57, v30, v57
	v_mul_f32_e32 v58, v30, v58
	v_mul_f32_e32 v59, v30, v59
	v_mul_f32_e32 v60, v30, v60
	v_mul_f32_e32 v61, v30, v61
	v_mul_f32_e32 v62, v30, v62
	v_mul_f32_e32 v63, v30, v63
	v_mul_f32_e32 v64, v30, v64
	s_mov_b64 s[12:13], 0x4ee4000
	v_lshl_add_u64 v[68:69], v[20:21], 0, s[12:13]
	s_waitcnt vmcnt(31)
	v_mul_f32_e32 v216, v6, v33
	v_mul_f32_e32 v217, v7, v33
	v_mul_f32_e32 v218, v10, v33
	v_mul_f32_e32 v219, v11, v33
	v_fma_f32 v84, v12, v84, v216
	v_fma_f32 v85, v12, v85, v217
	v_fma_f32 v86, v12, v86, v218
	v_fma_f32 v87, v12, v87, v219
	global_store_dwordx4 v[68:69], v[84:87], off
	v_mul_f32_e32 v216, v8, v84
	v_mul_f32_e32 v217, v9, v85
	v_mul_f32_e32 v218, v14, v86
	v_mul_f32_e32 v219, v15, v87
	v_add_f32_e32 v33, 0, v216
	v_add_f32_e32 v33, v217, v33
	v_add_f32_e32 v33, v218, v33
	v_add_f32_e32 v33, v219, v33
	s_waitcnt vmcnt(31)
; __device__ __forceinline__ float shfl_idx_f(float v, int src) { return __int_as_float(__builtin_amdgcn_ds_bpermute(src << 2, __float_as_int(v))); }
; __device__ __forceinline__ void ssd_sample_item(const Params& p, int item, const int wv) {
;     ...
;   for (int r = 0; r < 32; ++r) {
;     const int pp = 2 * r + hf;
;     f32x4 hv = *(const f32x4*)(st + (size_t)pp * 128 + n4);
;     const float xp = shfl_idx_f(x, pp) * dt;
;     f32x4 hn;
;     float yp = 0.f;
; #pragma unroll
;     for (int e = 0; e < 4; ++e) { hn[e] = dA * hv[e] + xp * Bv[e]; yp += hn[e] * Cv[e]; }
;     *(f32x4*)(so + (size_t)pp * 128 + n4) = hn;
	v_mul_f32_e32 v216, v6, v34
	v_mul_f32_e32 v217, v7, v34
	v_mul_f32_e32 v218, v10, v34
	v_mul_f32_e32 v219, v11, v34
	v_fma_f32 v88, v12, v88, v216
	v_fma_f32 v89, v12, v89, v217
	v_fma_f32 v90, v12, v90, v218
	v_fma_f32 v91, v12, v91, v219
	global_store_dwordx4 v[68:69], v[88:91], off offset:1024
	v_mul_f32_e32 v216, v8, v88
	v_mul_f32_e32 v217, v9, v89
	v_mul_f32_e32 v218, v14, v90
	v_mul_f32_e32 v219, v15, v91
	v_add_f32_e32 v34, 0, v216
	v_add_f32_e32 v34, v217, v34
	v_add_f32_e32 v34, v218, v34
	v_add_f32_e32 v34, v219, v34
	s_waitcnt vmcnt(31)
	v_mul_f32_e32 v216, v6, v35
	v_mul_f32_e32 v217, v7, v35
	v_mul_f32_e32 v218, v10, v35
	v_mul_f32_e32 v219, v11, v35
	v_fma_f32 v92, v12, v92, v216
	v_fma_f32 v93, v12, v93, v217
	v_fma_f32 v94, v12, v94, v218
	v_fma_f32 v95, v12, v95, v219
	global_store_dwordx4 v[68:69], v[92:95], off offset:2048
	v_mul_f32_e32 v216, v8, v92
	v_mul_f32_e32 v217, v9, v93
	v_mul_f32_e32 v218, v14, v94
	v_mul_f32_e32 v219, v15, v95
	v_add_f32_e32 v35, 0, v216
	v_add_f32_e32 v35, v217, v35
	v_add_f32_e32 v35, v218, v35
	v_add_f32_e32 v35, v219, v35
	s_waitcnt vmcnt(31)
	v_mul_f32_e32 v216, v6, v36
	v_mul_f32_e32 v217, v7, v36
	v_mul_f32_e32 v218, v10, v36
	v_mul_f32_e32 v219, v11, v36
	v_fma_f32 v96, v12, v96, v216
	v_fma_f32 v97, v12, v97, v217
	v_fma_f32 v98, v12, v98, v218
	v_fma_f32 v99, v12, v99, v219
	global_store_dwordx4 v[68:69], v[96:99], off offset:3072
	v_mul_f32_e32 v216, v8, v96
	v_mul_f32_e32 v217, v9, v97
	v_mul_f32_e32 v218, v14, v98
	v_mul_f32_e32 v219, v15, v99
	v_add_f32_e32 v36, 0, v216
	v_add_f32_e32 v36, v217, v36
	v_add_f32_e32 v36, v218, v36
	v_add_f32_e32 v36, v219, v36
	s_mov_b64 s[12:13], 0x4ee5000
	v_lshl_add_u64 v[68:69], v[20:21], 0, s[12:13]
	s_waitcnt vmcnt(31)
	v_mul_f32_e32 v216, v6, v37
	v_mul_f32_e32 v217, v7, v37
	v_mul_f32_e32 v218, v10, v37
	v_mul_f32_e32 v219, v11, v37
	v_fma_f32 v100, v12, v100, v216
	v_fma_f32 v101, v12, v101, v217
	v_fma_f32 v102, v12, v102, v218
	v_fma_f32 v103, v12, v103, v219
	global_store_dwordx4 v[68:69], v[100:103], off
	v_mul_f32_e32 v216, v8, v100
	v_mul_f32_e32 v217, v9, v101
	v_mul_f32_e32 v218, v14, v102
	v_mul_f32_e32 v219, v15, v103
	v_add_f32_e32 v37, 0, v216
	v_add_f32_e32 v37, v217, v37
	v_add_f32_e32 v37, v218, v37
	v_add_f32_e32 v37, v219, v37
	s_waitcnt vmcnt(31)
	v_mul_f32_e32 v216, v6, v38
	v_mul_f32_e32 v217, v7, v38
	v_mul_f32_e32 v218, v10, v38
	v_mul_f32_e32 v219, v11, v38
	v_fma_f32 v104, v12, v104, v216
	v_fma_f32 v105, v12, v105, v217
	v_fma_f32 v106, v12, v106, v218
	v_fma_f32 v107, v12, v107, v219
	global_store_dwordx4 v[68:69], v[104:107], off offset:1024
	v_mul_f32_e32 v216, v8, v104
	v_mul_f32_e32 v217, v9, v105
	v_mul_f32_e32 v218, v14, v106
	v_mul_f32_e32 v219, v15, v107
	v_add_f32_e32 v38, 0, v216
	v_add_f32_e32 v38, v217, v38
	v_add_f32_e32 v38, v218, v38
	v_add_f32_e32 v38, v219, v38
	s_waitcnt vmcnt(31)
	v_mul_f32_e32 v216, v6, v39
	v_mul_f32_e32 v217, v7, v39
	v_mul_f32_e32 v218, v10, v39
	v_mul_f32_e32 v219, v11, v39
	v_fma_f32 v108, v12, v108, v216
	v_fma_f32 v109, v12, v109, v217
	v_fma_f32 v110, v12, v110, v218
	v_fma_f32 v111, v12, v111, v219
	global_store_dwordx4 v[68:69], v[108:111], off offset:2048
	v_mul_f32_e32 v216, v8, v108
	v_mul_f32_e32 v217, v9, v109
	v_mul_f32_e32 v218, v14, v110
	v_mul_f32_e32 v219, v15, v111
	v_add_f32_e32 v39, 0, v216
	v_add_f32_e32 v39, v217, v39
	v_add_f32_e32 v39, v218, v39
	v_add_f32_e32 v39, v219, v39
	s_waitcnt vmcnt(31)
	v_mul_f32_e32 v216, v6, v40
	v_mul_f32_e32 v217, v7, v40
	v_mul_f32_e32 v218, v10, v40
	v_mul_f32_e32 v219, v11, v40
	v_fma_f32 v112, v12, v112, v216
	v_fma_f32 v113, v12, v113, v217
	v_fma_f32 v114, v12, v114, v218
	v_fma_f32 v115, v12, v115, v219
	global_store_dwordx4 v[68:69], v[112:115], off offset:3072
	v_mul_f32_e32 v216, v8, v112
	v_mul_f32_e32 v217, v9, v113
	v_mul_f32_e32 v218, v14, v114
	v_mul_f32_e32 v219, v15, v115
	v_add_f32_e32 v40, 0, v216
	v_add_f32_e32 v40, v217, v40
	v_add_f32_e32 v40, v218, v40
	v_add_f32_e32 v40, v219, v40
	s_mov_b64 s[12:13], 0x4ee6000
	v_lshl_add_u64 v[68:69], v[20:21], 0, s[12:13]
	s_waitcnt vmcnt(31)
	v_mul_f32_e32 v216, v6, v41
	v_mul_f32_e32 v217, v7, v41
	v_mul_f32_e32 v218, v10, v41
	v_mul_f32_e32 v219, v11, v41
	v_fma_f32 v116, v12, v116, v216
	v_fma_f32 v117, v12, v117, v217
	v_fma_f32 v118, v12, v118, v218
	v_fma_f32 v119, v12, v119, v219
	global_store_dwordx4 v[68:69], v[116:119], off
	v_mul_f32_e32 v216, v8, v116
	v_mul_f32_e32 v217, v9, v117
	v_mul_f32_e32 v218, v14, v118
	v_mul_f32_e32 v219, v15, v119
	v_add_f32_e32 v41, 0, v216
	v_add_f32_e32 v41, v217, v41
	v_add_f32_e32 v41, v218, v41
	v_add_f32_e32 v41, v219, v41
	s_waitcnt vmcnt(31)
	v_mul_f32_e32 v216, v6, v42
	v_mul_f32_e32 v217, v7, v42
	v_mul_f32_e32 v218, v10, v42
	v_mul_f32_e32 v219, v11, v42
	v_fma_f32 v120, v12, v120, v216
	v_fma_f32 v121, v12, v121, v217
	v_fma_f32 v122, v12, v122, v218
	v_fma_f32 v123, v12, v123, v219
	global_store_dwordx4 v[68:69], v[120:123], off offset:1024
	v_mul_f32_e32 v216, v8, v120
	v_mul_f32_e32 v217, v9, v121
	v_mul_f32_e32 v218, v14, v122
	v_mul_f32_e32 v219, v15, v123
	v_add_f32_e32 v42, 0, v216
	v_add_f32_e32 v42, v217, v42
	v_add_f32_e32 v42, v218, v42
	v_add_f32_e32 v42, v219, v42
	s_waitcnt vmcnt(31)
	v_mul_f32_e32 v216, v6, v43
	v_mul_f32_e32 v217, v7, v43
	v_mul_f32_e32 v218, v10, v43
	v_mul_f32_e32 v219, v11, v43
	v_fma_f32 v124, v12, v124, v216
	v_fma_f32 v125, v12, v125, v217
	v_fma_f32 v126, v12, v126, v218
	v_fma_f32 v127, v12, v127, v219
	global_store_dwordx4 v[68:69], v[124:127], off offset:2048
	v_mul_f32_e32 v216, v8, v124
	v_mul_f32_e32 v217, v9, v125
	v_mul_f32_e32 v218, v14, v126
	v_mul_f32_e32 v219, v15, v127
	v_add_f32_e32 v43, 0, v216
	v_add_f32_e32 v43, v217, v43
	v_add_f32_e32 v43, v218, v43
	v_add_f32_e32 v43, v219, v43
	s_waitcnt vmcnt(31)
; __device__ __forceinline__ float shfl_idx_f(float v, int src) { return __int_as_float(__builtin_amdgcn_ds_bpermute(src << 2, __float_as_int(v))); }
; __device__ __forceinline__ void ssd_sample_item(const Params& p, int item, const int wv) {
;     ...
;   for (int r = 0; r < 32; ++r) {
;     const int pp = 2 * r + hf;
;     f32x4 hv = *(const f32x4*)(st + (size_t)pp * 128 + n4);
;     const float xp = shfl_idx_f(x, pp) * dt;
;     f32x4 hn;
;     float yp = 0.f;
; #pragma unroll
;     for (int e = 0; e < 4; ++e) { hn[e] = dA * hv[e] + xp * Bv[e]; yp += hn[e] * Cv[e]; }
;     *(f32x4*)(so + (size_t)pp * 128 + n4) = hn;
	v_mul_f32_e32 v216, v6, v44
	v_mul_f32_e32 v217, v7, v44
	v_mul_f32_e32 v218, v10, v44
	v_mul_f32_e32 v219, v11, v44
	v_fma_f32 v128, v12, v128, v216
	v_fma_f32 v129, v12, v129, v217
	v_fma_f32 v130, v12, v130, v218
	v_fma_f32 v131, v12, v131, v219
	global_store_dwordx4 v[68:69], v[128:131], off offset:3072
	v_mul_f32_e32 v216, v8, v128
	v_mul_f32_e32 v217, v9, v129
	v_mul_f32_e32 v218, v14, v130
	v_mul_f32_e32 v219, v15, v131
	v_add_f32_e32 v44, 0, v216
	v_add_f32_e32 v44, v217, v44
	v_add_f32_e32 v44, v218, v44
	v_add_f32_e32 v44, v219, v44
	s_mov_b64 s[12:13], 0x4ee7000
	v_lshl_add_u64 v[68:69], v[20:21], 0, s[12:13]
	s_waitcnt vmcnt(31)
	v_mul_f32_e32 v216, v6, v45
	v_mul_f32_e32 v217, v7, v45
	v_mul_f32_e32 v218, v10, v45
	v_mul_f32_e32 v219, v11, v45
	v_fma_f32 v132, v12, v132, v216
	v_fma_f32 v133, v12, v133, v217
	v_fma_f32 v134, v12, v134, v218
	v_fma_f32 v135, v12, v135, v219
	global_store_dwordx4 v[68:69], v[132:135], off
	v_mul_f32_e32 v216, v8, v132
	v_mul_f32_e32 v217, v9, v133
	v_mul_f32_e32 v218, v14, v134
	v_mul_f32_e32 v219, v15, v135
	v_add_f32_e32 v45, 0, v216
	v_add_f32_e32 v45, v217, v45
	v_add_f32_e32 v45, v218, v45
	v_add_f32_e32 v45, v219, v45
	s_waitcnt vmcnt(31)
	v_mul_f32_e32 v216, v6, v46
	v_mul_f32_e32 v217, v7, v46
	v_mul_f32_e32 v218, v10, v46
	v_mul_f32_e32 v219, v11, v46
	v_fma_f32 v136, v12, v136, v216
	v_fma_f32 v137, v12, v137, v217
	v_fma_f32 v138, v12, v138, v218
	v_fma_f32 v139, v12, v139, v219
	global_store_dwordx4 v[68:69], v[136:139], off offset:1024
	v_mul_f32_e32 v216, v8, v136
	v_mul_f32_e32 v217, v9, v137
	v_mul_f32_e32 v218, v14, v138
	v_mul_f32_e32 v219, v15, v139
	v_add_f32_e32 v46, 0, v216
	v_add_f32_e32 v46, v217, v46
	v_add_f32_e32 v46, v218, v46
	v_add_f32_e32 v46, v219, v46
	s_waitcnt vmcnt(31)
	v_mul_f32_e32 v216, v6, v47
	v_mul_f32_e32 v217, v7, v47
	v_mul_f32_e32 v218, v10, v47
	v_mul_f32_e32 v219, v11, v47
	v_fma_f32 v140, v12, v140, v216
	v_fma_f32 v141, v12, v141, v217
	v_fma_f32 v142, v12, v142, v218
	v_fma_f32 v143, v12, v143, v219
	global_store_dwordx4 v[68:69], v[140:143], off offset:2048
	v_mul_f32_e32 v216, v8, v140
	v_mul_f32_e32 v217, v9, v141
	v_mul_f32_e32 v218, v14, v142
	v_mul_f32_e32 v219, v15, v143
	v_add_f32_e32 v47, 0, v216
	v_add_f32_e32 v47, v217, v47
	v_add_f32_e32 v47, v218, v47
	v_add_f32_e32 v47, v219, v47
	s_waitcnt vmcnt(31)
	v_mul_f32_e32 v216, v6, v48
	v_mul_f32_e32 v217, v7, v48
	v_mul_f32_e32 v218, v10, v48
	v_mul_f32_e32 v219, v11, v48
	v_fma_f32 v144, v12, v144, v216
	v_fma_f32 v145, v12, v145, v217
	v_fma_f32 v146, v12, v146, v218
	v_fma_f32 v147, v12, v147, v219
	global_store_dwordx4 v[68:69], v[144:147], off offset:3072
	v_mul_f32_e32 v216, v8, v144
	v_mul_f32_e32 v217, v9, v145
	v_mul_f32_e32 v218, v14, v146
	v_mul_f32_e32 v219, v15, v147
	v_add_f32_e32 v48, 0, v216
	v_add_f32_e32 v48, v217, v48
	v_add_f32_e32 v48, v218, v48
	v_add_f32_e32 v48, v219, v48
	s_mov_b64 s[12:13], 0x4ee8000
	v_lshl_add_u64 v[68:69], v[20:21], 0, s[12:13]
	s_waitcnt vmcnt(31)
	v_mul_f32_e32 v216, v6, v49
	v_mul_f32_e32 v217, v7, v49
	v_mul_f32_e32 v218, v10, v49
	v_mul_f32_e32 v219, v11, v49
	v_fma_f32 v148, v12, v148, v216
	v_fma_f32 v149, v12, v149, v217
	v_fma_f32 v150, v12, v150, v218
	v_fma_f32 v151, v12, v151, v219
	global_store_dwordx4 v[68:69], v[148:151], off
	v_mul_f32_e32 v216, v8, v148
	v_mul_f32_e32 v217, v9, v149
	v_mul_f32_e32 v218, v14, v150
	v_mul_f32_e32 v219, v15, v151
	v_add_f32_e32 v49, 0, v216
	v_add_f32_e32 v49, v217, v49
	v_add_f32_e32 v49, v218, v49
	v_add_f32_e32 v49, v219, v49
	s_waitcnt vmcnt(31)
	v_mul_f32_e32 v216, v6, v50
	v_mul_f32_e32 v217, v7, v50
	v_mul_f32_e32 v218, v10, v50
	v_mul_f32_e32 v219, v11, v50
	v_fma_f32 v152, v12, v152, v216
	v_fma_f32 v153, v12, v153, v217
	v_fma_f32 v154, v12, v154, v218
	v_fma_f32 v155, v12, v155, v219
	global_store_dwordx4 v[68:69], v[152:155], off offset:1024
	v_mul_f32_e32 v216, v8, v152
	v_mul_f32_e32 v217, v9, v153
	v_mul_f32_e32 v218, v14, v154
	v_mul_f32_e32 v219, v15, v155
	v_add_f32_e32 v50, 0, v216
	v_add_f32_e32 v50, v217, v50
	v_add_f32_e32 v50, v218, v50
	v_add_f32_e32 v50, v219, v50
	s_waitcnt vmcnt(31)
	v_mul_f32_e32 v216, v6, v51
	v_mul_f32_e32 v217, v7, v51
	v_mul_f32_e32 v218, v10, v51
	v_mul_f32_e32 v219, v11, v51
	v_fma_f32 v156, v12, v156, v216
	v_fma_f32 v157, v12, v157, v217
	v_fma_f32 v158, v12, v158, v218
	v_fma_f32 v159, v12, v159, v219
	global_store_dwordx4 v[68:69], v[156:159], off offset:2048
	v_mul_f32_e32 v216, v8, v156
	v_mul_f32_e32 v217, v9, v157
	v_mul_f32_e32 v218, v14, v158
	v_mul_f32_e32 v219, v15, v159
	v_add_f32_e32 v51, 0, v216
	v_add_f32_e32 v51, v217, v51
	v_add_f32_e32 v51, v218, v51
	v_add_f32_e32 v51, v219, v51
	s_waitcnt vmcnt(31)
	v_mul_f32_e32 v216, v6, v52
	v_mul_f32_e32 v217, v7, v52
	v_mul_f32_e32 v218, v10, v52
	v_mul_f32_e32 v219, v11, v52
	v_fma_f32 v164, v12, v164, v216
	v_fma_f32 v165, v12, v165, v217
	v_fma_f32 v166, v12, v166, v218
	v_fma_f32 v167, v12, v167, v219
	global_store_dwordx4 v[68:69], v[164:167], off offset:3072
	v_mul_f32_e32 v216, v8, v164
	v_mul_f32_e32 v217, v9, v165
	v_mul_f32_e32 v218, v14, v166
	v_mul_f32_e32 v219, v15, v167
	v_add_f32_e32 v52, 0, v216
	v_add_f32_e32 v52, v217, v52
	v_add_f32_e32 v52, v218, v52
	v_add_f32_e32 v52, v219, v52
	s_mov_b64 s[12:13], 0x4ee9000
	v_lshl_add_u64 v[68:69], v[20:21], 0, s[12:13]
	s_waitcnt vmcnt(31)
	v_mul_f32_e32 v216, v6, v53
	v_mul_f32_e32 v217, v7, v53
	v_mul_f32_e32 v218, v10, v53
	v_mul_f32_e32 v219, v11, v53
	v_fma_f32 v168, v12, v168, v216
	v_fma_f32 v169, v12, v169, v217
	v_fma_f32 v170, v12, v170, v218
	v_fma_f32 v171, v12, v171, v219
	global_store_dwordx4 v[68:69], v[168:171], off
	v_mul_f32_e32 v216, v8, v168
	v_mul_f32_e32 v217, v9, v169
	v_mul_f32_e32 v218, v14, v170
	v_mul_f32_e32 v219, v15, v171
	v_add_f32_e32 v53, 0, v216
	v_add_f32_e32 v53, v217, v53
	v_add_f32_e32 v53, v218, v53
	v_add_f32_e32 v53, v219, v53
	s_waitcnt vmcnt(31)
; __device__ __forceinline__ float shfl_idx_f(float v, int src) { return __int_as_float(__builtin_amdgcn_ds_bpermute(src << 2, __float_as_int(v))); }
; __device__ __forceinline__ void ssd_sample_item(const Params& p, int item, const int wv) {
;     ...
;   for (int r = 0; r < 32; ++r) {
;     const int pp = 2 * r + hf;
;     f32x4 hv = *(const f32x4*)(st + (size_t)pp * 128 + n4);
;     const float xp = shfl_idx_f(x, pp) * dt;
;     f32x4 hn;
;     float yp = 0.f;
; #pragma unroll
;     for (int e = 0; e < 4; ++e) { hn[e] = dA * hv[e] + xp * Bv[e]; yp += hn[e] * Cv[e]; }
;     *(f32x4*)(so + (size_t)pp * 128 + n4) = hn;
	v_mul_f32_e32 v216, v6, v54
	v_mul_f32_e32 v217, v7, v54
	v_mul_f32_e32 v218, v10, v54
	v_mul_f32_e32 v219, v11, v54
	v_fma_f32 v172, v12, v172, v216
	v_fma_f32 v173, v12, v173, v217
	v_fma_f32 v174, v12, v174, v218
	v_fma_f32 v175, v12, v175, v219
	global_store_dwordx4 v[68:69], v[172:175], off offset:1024
	v_mul_f32_e32 v216, v8, v172
	v_mul_f32_e32 v217, v9, v173
	v_mul_f32_e32 v218, v14, v174
	v_mul_f32_e32 v219, v15, v175
	v_add_f32_e32 v54, 0, v216
	v_add_f32_e32 v54, v217, v54
	v_add_f32_e32 v54, v218, v54
	v_add_f32_e32 v54, v219, v54
	s_waitcnt vmcnt(31)
	v_mul_f32_e32 v216, v6, v55
	v_mul_f32_e32 v217, v7, v55
	v_mul_f32_e32 v218, v10, v55
	v_mul_f32_e32 v219, v11, v55
	v_fma_f32 v176, v12, v176, v216
	v_fma_f32 v177, v12, v177, v217
	v_fma_f32 v178, v12, v178, v218
	v_fma_f32 v179, v12, v179, v219
	global_store_dwordx4 v[68:69], v[176:179], off offset:2048
	v_mul_f32_e32 v216, v8, v176
	v_mul_f32_e32 v217, v9, v177
	v_mul_f32_e32 v218, v14, v178
	v_mul_f32_e32 v219, v15, v179
	v_add_f32_e32 v55, 0, v216
	v_add_f32_e32 v55, v217, v55
	v_add_f32_e32 v55, v218, v55
	v_add_f32_e32 v55, v219, v55
	s_waitcnt vmcnt(31)
	v_mul_f32_e32 v216, v6, v56
	v_mul_f32_e32 v217, v7, v56
	v_mul_f32_e32 v218, v10, v56
	v_mul_f32_e32 v219, v11, v56
	v_fma_f32 v180, v12, v180, v216
	v_fma_f32 v181, v12, v181, v217
	v_fma_f32 v182, v12, v182, v218
	v_fma_f32 v183, v12, v183, v219
	global_store_dwordx4 v[68:69], v[180:183], off offset:3072
	v_mul_f32_e32 v216, v8, v180
	v_mul_f32_e32 v217, v9, v181
	v_mul_f32_e32 v218, v14, v182
	v_mul_f32_e32 v219, v15, v183
	v_add_f32_e32 v56, 0, v216
	v_add_f32_e32 v56, v217, v56
	v_add_f32_e32 v56, v218, v56
	v_add_f32_e32 v56, v219, v56
	s_mov_b64 s[12:13], 0x4eea000
	v_lshl_add_u64 v[68:69], v[20:21], 0, s[12:13]
	s_waitcnt vmcnt(31)
	v_mul_f32_e32 v216, v6, v57
	v_mul_f32_e32 v217, v7, v57
	v_mul_f32_e32 v218, v10, v57
	v_mul_f32_e32 v219, v11, v57
	v_fma_f32 v184, v12, v184, v216
	v_fma_f32 v185, v12, v185, v217
	v_fma_f32 v186, v12, v186, v218
	v_fma_f32 v187, v12, v187, v219
	global_store_dwordx4 v[68:69], v[184:187], off
	v_mul_f32_e32 v216, v8, v184
	v_mul_f32_e32 v217, v9, v185
	v_mul_f32_e32 v218, v14, v186
	v_mul_f32_e32 v219, v15, v187
	v_add_f32_e32 v57, 0, v216
	v_add_f32_e32 v57, v217, v57
	v_add_f32_e32 v57, v218, v57
	v_add_f32_e32 v57, v219, v57
	s_waitcnt vmcnt(31)
	v_mul_f32_e32 v216, v6, v58
	v_mul_f32_e32 v217, v7, v58
	v_mul_f32_e32 v218, v10, v58
	v_mul_f32_e32 v219, v11, v58
	v_fma_f32 v188, v12, v188, v216
	v_fma_f32 v189, v12, v189, v217
	v_fma_f32 v190, v12, v190, v218
	v_fma_f32 v191, v12, v191, v219
	global_store_dwordx4 v[68:69], v[188:191], off offset:1024
	v_mul_f32_e32 v216, v8, v188
	v_mul_f32_e32 v217, v9, v189
	v_mul_f32_e32 v218, v14, v190
	v_mul_f32_e32 v219, v15, v191
	v_add_f32_e32 v58, 0, v216
	v_add_f32_e32 v58, v217, v58
	v_add_f32_e32 v58, v218, v58
	v_add_f32_e32 v58, v219, v58
	s_waitcnt vmcnt(31)
	v_mul_f32_e32 v216, v6, v59
	v_mul_f32_e32 v217, v7, v59
	v_mul_f32_e32 v218, v10, v59
	v_mul_f32_e32 v219, v11, v59
	v_fma_f32 v192, v12, v192, v216
	v_fma_f32 v193, v12, v193, v217
	v_fma_f32 v194, v12, v194, v218
	v_fma_f32 v195, v12, v195, v219
	global_store_dwordx4 v[68:69], v[192:195], off offset:2048
	v_mul_f32_e32 v216, v8, v192
	v_mul_f32_e32 v217, v9, v193
	v_mul_f32_e32 v218, v14, v194
	v_mul_f32_e32 v219, v15, v195
	v_add_f32_e32 v59, 0, v216
	v_add_f32_e32 v59, v217, v59
	v_add_f32_e32 v59, v218, v59
	v_add_f32_e32 v59, v219, v59
	s_waitcnt vmcnt(31)
	v_mul_f32_e32 v216, v6, v60
	v_mul_f32_e32 v217, v7, v60
	v_mul_f32_e32 v218, v10, v60
	v_mul_f32_e32 v219, v11, v60
	v_fma_f32 v196, v12, v196, v216
	v_fma_f32 v197, v12, v197, v217
	v_fma_f32 v198, v12, v198, v218
	v_fma_f32 v199, v12, v199, v219
	global_store_dwordx4 v[68:69], v[196:199], off offset:3072
	v_mul_f32_e32 v216, v8, v196
	v_mul_f32_e32 v217, v9, v197
	v_mul_f32_e32 v218, v14, v198
	v_mul_f32_e32 v219, v15, v199
	v_add_f32_e32 v60, 0, v216
	v_add_f32_e32 v60, v217, v60
	v_add_f32_e32 v60, v218, v60
	v_add_f32_e32 v60, v219, v60
	s_mov_b64 s[12:13], 0x4eeb000
	v_lshl_add_u64 v[68:69], v[20:21], 0, s[12:13]
	s_waitcnt vmcnt(31)
	v_mul_f32_e32 v216, v6, v61
	v_mul_f32_e32 v217, v7, v61
	v_mul_f32_e32 v218, v10, v61
	v_mul_f32_e32 v219, v11, v61
	v_fma_f32 v200, v12, v200, v216
	v_fma_f32 v201, v12, v201, v217
	v_fma_f32 v202, v12, v202, v218
	v_fma_f32 v203, v12, v203, v219
	global_store_dwordx4 v[68:69], v[200:203], off
	v_mul_f32_e32 v216, v8, v200
	v_mul_f32_e32 v217, v9, v201
	v_mul_f32_e32 v218, v14, v202
	v_mul_f32_e32 v219, v15, v203
	v_add_f32_e32 v61, 0, v216
	v_add_f32_e32 v61, v217, v61
	v_add_f32_e32 v61, v218, v61
	v_add_f32_e32 v61, v219, v61
	s_waitcnt vmcnt(31)
	v_mul_f32_e32 v216, v6, v62
	v_mul_f32_e32 v217, v7, v62
	v_mul_f32_e32 v218, v10, v62
	v_mul_f32_e32 v219, v11, v62
	v_fma_f32 v204, v12, v204, v216
	v_fma_f32 v205, v12, v205, v217
	v_fma_f32 v206, v12, v206, v218
	v_fma_f32 v207, v12, v207, v219
	global_store_dwordx4 v[68:69], v[204:207], off offset:1024
	v_mul_f32_e32 v216, v8, v204
	v_mul_f32_e32 v217, v9, v205
	v_mul_f32_e32 v218, v14, v206
	v_mul_f32_e32 v219, v15, v207
	v_add_f32_e32 v62, 0, v216
	v_add_f32_e32 v62, v217, v62
	v_add_f32_e32 v62, v218, v62
	v_add_f32_e32 v62, v219, v62
	s_waitcnt vmcnt(31)
	v_mul_f32_e32 v216, v6, v63
	v_mul_f32_e32 v217, v7, v63
	v_mul_f32_e32 v218, v10, v63
	v_mul_f32_e32 v219, v11, v63
	v_fma_f32 v208, v12, v208, v216
	v_fma_f32 v209, v12, v209, v217
	v_fma_f32 v210, v12, v210, v218
	v_fma_f32 v211, v12, v211, v219
	global_store_dwordx4 v[68:69], v[208:211], off offset:2048
	v_mul_f32_e32 v216, v8, v208
	v_mul_f32_e32 v217, v9, v209
	v_mul_f32_e32 v218, v14, v210
	v_mul_f32_e32 v219, v15, v211
	v_add_f32_e32 v63, 0, v216
	v_add_f32_e32 v63, v217, v63
	v_add_f32_e32 v63, v218, v63
	v_add_f32_e32 v63, v219, v63
	s_waitcnt vmcnt(31)
; __device__ __forceinline__ float shfl_xor_f(float v, int mask) { const int l = lane_fresh(); return __int_as_float(__builtin_amdgcn_ds_bpermute((l ^ mask) << 2, __float_as_int(v))); }
; __device__ __forceinline__ void ssd_sample_item(const Params& p, int item, const int wv) {
;     ...
;     for (int e = 0; e < 4; ++e) { hn[e] = dA * hv[e] + xp * Bv[e]; yp += hn[e] * Cv[e]; }
;     *(f32x4*)(so + (size_t)pp * 128 + n4) = hn;
; #pragma unroll
;     for (int o = 16; o >= 1; o >>= 1) yp += shfl_xor_f(yp, o);
	v_mul_f32_e32 v216, v6, v64
	v_mul_f32_e32 v217, v7, v64
	v_mul_f32_e32 v218, v10, v64
	v_mul_f32_e32 v219, v11, v64
	v_fma_f32 v212, v12, v212, v216
	v_fma_f32 v213, v12, v213, v217
	v_fma_f32 v214, v12, v214, v218
	v_fma_f32 v215, v12, v215, v219
	global_store_dwordx4 v[68:69], v[212:215], off offset:3072
	v_mul_f32_e32 v216, v8, v212
	v_mul_f32_e32 v217, v9, v213
	v_mul_f32_e32 v218, v14, v214
	v_mul_f32_e32 v219, v15, v215
	v_add_f32_e32 v64, 0, v216
	v_add_f32_e32 v64, v217, v64
	v_add_f32_e32 v64, v218, v64
	v_add_f32_e32 v64, v219, v64
	ds_bpermute_b32 v66, v22, v33
	ds_bpermute_b32 v67, v22, v34
	ds_bpermute_b32 v68, v22, v35
	ds_bpermute_b32 v69, v22, v36
	ds_bpermute_b32 v70, v22, v37
	ds_bpermute_b32 v71, v22, v38
	ds_bpermute_b32 v72, v22, v39
	ds_bpermute_b32 v73, v22, v40
	ds_bpermute_b32 v74, v22, v41
	ds_bpermute_b32 v75, v22, v42
	ds_bpermute_b32 v76, v22, v43
	ds_bpermute_b32 v77, v22, v44
	ds_bpermute_b32 v78, v22, v45
	ds_bpermute_b32 v0, v22, v46
	ds_bpermute_b32 v1, v22, v47
	ds_bpermute_b32 v2, v22, v48
	s_waitcnt lgkmcnt(15)
	v_add_f32_e32 v33, v33, v66
	s_waitcnt lgkmcnt(14)
	v_add_f32_e32 v34, v34, v67
	s_waitcnt lgkmcnt(13)
	v_add_f32_e32 v35, v35, v68
	s_waitcnt lgkmcnt(12)
	v_add_f32_e32 v36, v36, v69
	s_waitcnt lgkmcnt(11)
	v_add_f32_e32 v37, v37, v70
	s_waitcnt lgkmcnt(10)
	v_add_f32_e32 v38, v38, v71
	s_waitcnt lgkmcnt(9)
	v_add_f32_e32 v39, v39, v72
	s_waitcnt lgkmcnt(8)
	v_add_f32_e32 v40, v40, v73
	s_waitcnt lgkmcnt(7)
	v_add_f32_e32 v41, v41, v74
	s_waitcnt lgkmcnt(6)
	v_add_f32_e32 v42, v42, v75
	s_waitcnt lgkmcnt(5)
	v_add_f32_e32 v43, v43, v76
	s_waitcnt lgkmcnt(4)
	v_add_f32_e32 v44, v44, v77
	s_waitcnt lgkmcnt(3)
	v_add_f32_e32 v45, v45, v78
	s_waitcnt lgkmcnt(2)
	v_add_f32_e32 v46, v46, v0
	s_waitcnt lgkmcnt(1)
	v_add_f32_e32 v47, v47, v1
	s_waitcnt lgkmcnt(0)
	v_add_f32_e32 v48, v48, v2
	ds_bpermute_b32 v66, v23, v33
	ds_bpermute_b32 v67, v23, v34
	ds_bpermute_b32 v68, v23, v35
	ds_bpermute_b32 v69, v23, v36
	ds_bpermute_b32 v70, v23, v37
	ds_bpermute_b32 v71, v23, v38
	ds_bpermute_b32 v72, v23, v39
	ds_bpermute_b32 v73, v23, v40
	ds_bpermute_b32 v74, v23, v41
	ds_bpermute_b32 v75, v23, v42
	ds_bpermute_b32 v76, v23, v43
	ds_bpermute_b32 v77, v23, v44
	ds_bpermute_b32 v78, v23, v45
	ds_bpermute_b32 v0, v23, v46
	ds_bpermute_b32 v1, v23, v47
	ds_bpermute_b32 v2, v23, v48
	s_waitcnt lgkmcnt(15)
	v_add_f32_e32 v33, v33, v66
	s_waitcnt lgkmcnt(14)
	v_add_f32_e32 v34, v34, v67
	s_waitcnt lgkmcnt(13)
	v_add_f32_e32 v35, v35, v68
	s_waitcnt lgkmcnt(12)
	v_add_f32_e32 v36, v36, v69
	s_waitcnt lgkmcnt(11)
	v_add_f32_e32 v37, v37, v70
	s_waitcnt lgkmcnt(10)
	v_add_f32_e32 v38, v38, v71
	s_waitcnt lgkmcnt(9)
	v_add_f32_e32 v39, v39, v72
	s_waitcnt lgkmcnt(8)
	v_add_f32_e32 v40, v40, v73
	s_waitcnt lgkmcnt(7)
	v_add_f32_e32 v41, v41, v74
	s_waitcnt lgkmcnt(6)
	v_add_f32_e32 v42, v42, v75
	s_waitcnt lgkmcnt(5)
	v_add_f32_e32 v43, v43, v76
	s_waitcnt lgkmcnt(4)
	v_add_f32_e32 v44, v44, v77
	s_waitcnt lgkmcnt(3)
	v_add_f32_e32 v45, v45, v78
	s_waitcnt lgkmcnt(2)
	v_add_f32_e32 v46, v46, v0
	s_waitcnt lgkmcnt(1)
	v_add_f32_e32 v47, v47, v1
	s_waitcnt lgkmcnt(0)
	v_add_f32_e32 v48, v48, v2
	ds_bpermute_b32 v66, v24, v33
	ds_bpermute_b32 v67, v24, v34
	ds_bpermute_b32 v68, v24, v35
	ds_bpermute_b32 v69, v24, v36
	ds_bpermute_b32 v70, v24, v37
	ds_bpermute_b32 v71, v24, v38
	ds_bpermute_b32 v72, v24, v39
	ds_bpermute_b32 v73, v24, v40
	ds_bpermute_b32 v74, v24, v41
	ds_bpermute_b32 v75, v24, v42
	ds_bpermute_b32 v76, v24, v43
	ds_bpermute_b32 v77, v24, v44
	ds_bpermute_b32 v78, v24, v45
	ds_bpermute_b32 v0, v24, v46
	ds_bpermute_b32 v1, v24, v47
	ds_bpermute_b32 v2, v24, v48
	s_waitcnt lgkmcnt(15)
	v_add_f32_e32 v33, v33, v66
	s_waitcnt lgkmcnt(14)
	v_add_f32_e32 v34, v34, v67
	s_waitcnt lgkmcnt(13)
	v_add_f32_e32 v35, v35, v68
	s_waitcnt lgkmcnt(12)
	v_add_f32_e32 v36, v36, v69
	s_waitcnt lgkmcnt(11)
	v_add_f32_e32 v37, v37, v70
	s_waitcnt lgkmcnt(10)
	v_add_f32_e32 v38, v38, v71
	s_waitcnt lgkmcnt(9)
	v_add_f32_e32 v39, v39, v72
	s_waitcnt lgkmcnt(8)
	v_add_f32_e32 v40, v40, v73
	s_waitcnt lgkmcnt(7)
	v_add_f32_e32 v41, v41, v74
	s_waitcnt lgkmcnt(6)
	v_add_f32_e32 v42, v42, v75
	s_waitcnt lgkmcnt(5)
	v_add_f32_e32 v43, v43, v76
	s_waitcnt lgkmcnt(4)
	v_add_f32_e32 v44, v44, v77
	s_waitcnt lgkmcnt(3)
	v_add_f32_e32 v45, v45, v78
	s_waitcnt lgkmcnt(2)
	v_add_f32_e32 v46, v46, v0
	s_waitcnt lgkmcnt(1)
	v_add_f32_e32 v47, v47, v1
	s_waitcnt lgkmcnt(0)
	v_add_f32_e32 v48, v48, v2
	ds_bpermute_b32 v66, v25, v33
	ds_bpermute_b32 v67, v25, v34
	ds_bpermute_b32 v68, v25, v35
	ds_bpermute_b32 v69, v25, v36
	ds_bpermute_b32 v70, v25, v37
	ds_bpermute_b32 v71, v25, v38
	ds_bpermute_b32 v72, v25, v39
	ds_bpermute_b32 v73, v25, v40
	ds_bpermute_b32 v74, v25, v41
	ds_bpermute_b32 v75, v25, v42
	ds_bpermute_b32 v76, v25, v43
	ds_bpermute_b32 v77, v25, v44
	ds_bpermute_b32 v78, v25, v45
	ds_bpermute_b32 v0, v25, v46
	ds_bpermute_b32 v1, v25, v47
	ds_bpermute_b32 v2, v25, v48
	s_waitcnt lgkmcnt(15)
	v_add_f32_e32 v33, v33, v66
	s_waitcnt lgkmcnt(14)
	v_add_f32_e32 v34, v34, v67
	s_waitcnt lgkmcnt(13)
	v_add_f32_e32 v35, v35, v68
	s_waitcnt lgkmcnt(12)
	v_add_f32_e32 v36, v36, v69
	s_waitcnt lgkmcnt(11)
	v_add_f32_e32 v37, v37, v70
	s_waitcnt lgkmcnt(10)
	v_add_f32_e32 v38, v38, v71
	s_waitcnt lgkmcnt(9)
	v_add_f32_e32 v39, v39, v72
	s_waitcnt lgkmcnt(8)
	v_add_f32_e32 v40, v40, v73
	s_waitcnt lgkmcnt(7)
	v_add_f32_e32 v41, v41, v74
	s_waitcnt lgkmcnt(6)
	v_add_f32_e32 v42, v42, v75
	s_waitcnt lgkmcnt(5)
	v_add_f32_e32 v43, v43, v76
	s_waitcnt lgkmcnt(4)
	v_add_f32_e32 v44, v44, v77
	s_waitcnt lgkmcnt(3)
; __device__ __forceinline__ float shfl_xor_f(float v, int mask) { const int l = lane_fresh(); return __int_as_float(__builtin_amdgcn_ds_bpermute((l ^ mask) << 2, __float_as_int(v))); }
; __device__ __forceinline__ void ssd_sample_item(const Params& p, int item, const int wv) {
;     ...
;     for (int o = 16; o >= 1; o >>= 1) yp += shfl_xor_f(yp, o);
	v_add_f32_e32 v45, v45, v78
	s_waitcnt lgkmcnt(2)
	v_add_f32_e32 v46, v46, v0
	s_waitcnt lgkmcnt(1)
	v_add_f32_e32 v47, v47, v1
	s_waitcnt lgkmcnt(0)
	v_add_f32_e32 v48, v48, v2
	ds_bpermute_b32 v66, v26, v33
	ds_bpermute_b32 v67, v26, v34
	ds_bpermute_b32 v68, v26, v35
	ds_bpermute_b32 v69, v26, v36
	ds_bpermute_b32 v70, v26, v37
	ds_bpermute_b32 v71, v26, v38
	ds_bpermute_b32 v72, v26, v39
	ds_bpermute_b32 v73, v26, v40
	ds_bpermute_b32 v74, v26, v41
	ds_bpermute_b32 v75, v26, v42
	ds_bpermute_b32 v76, v26, v43
	ds_bpermute_b32 v77, v26, v44
	ds_bpermute_b32 v78, v26, v45
	ds_bpermute_b32 v0, v26, v46
	ds_bpermute_b32 v1, v26, v47
	ds_bpermute_b32 v2, v26, v48
	s_waitcnt lgkmcnt(15)
	v_add_f32_e32 v33, v33, v66
	s_waitcnt lgkmcnt(14)
	v_add_f32_e32 v34, v34, v67
	s_waitcnt lgkmcnt(13)
	v_add_f32_e32 v35, v35, v68
	s_waitcnt lgkmcnt(12)
	v_add_f32_e32 v36, v36, v69
	s_waitcnt lgkmcnt(11)
	v_add_f32_e32 v37, v37, v70
	s_waitcnt lgkmcnt(10)
	v_add_f32_e32 v38, v38, v71
	s_waitcnt lgkmcnt(9)
	v_add_f32_e32 v39, v39, v72
	s_waitcnt lgkmcnt(8)
	v_add_f32_e32 v40, v40, v73
	s_waitcnt lgkmcnt(7)
	v_add_f32_e32 v41, v41, v74
	s_waitcnt lgkmcnt(6)
	v_add_f32_e32 v42, v42, v75
	s_waitcnt lgkmcnt(5)
	v_add_f32_e32 v43, v43, v76
	s_waitcnt lgkmcnt(4)
	v_add_f32_e32 v44, v44, v77
	s_waitcnt lgkmcnt(3)
	v_add_f32_e32 v45, v45, v78
	s_waitcnt lgkmcnt(2)
	v_add_f32_e32 v46, v46, v0
	s_waitcnt lgkmcnt(1)
	v_add_f32_e32 v47, v47, v1
	s_waitcnt lgkmcnt(0)
	v_add_f32_e32 v48, v48, v2
	ds_bpermute_b32 v66, v22, v49
	ds_bpermute_b32 v67, v22, v50
	ds_bpermute_b32 v68, v22, v51
	ds_bpermute_b32 v69, v22, v52
	ds_bpermute_b32 v70, v22, v53
	ds_bpermute_b32 v71, v22, v54
	ds_bpermute_b32 v72, v22, v55
	ds_bpermute_b32 v73, v22, v56
	ds_bpermute_b32 v74, v22, v57
	ds_bpermute_b32 v75, v22, v58
	ds_bpermute_b32 v76, v22, v59
	ds_bpermute_b32 v77, v22, v60
	ds_bpermute_b32 v78, v22, v61
	ds_bpermute_b32 v0, v22, v62
	ds_bpermute_b32 v1, v22, v63
	ds_bpermute_b32 v2, v22, v64
	s_waitcnt lgkmcnt(15)
	v_add_f32_e32 v49, v49, v66
	s_waitcnt lgkmcnt(14)
	v_add_f32_e32 v50, v50, v67
	s_waitcnt lgkmcnt(13)
	v_add_f32_e32 v51, v51, v68
	s_waitcnt lgkmcnt(12)
	v_add_f32_e32 v52, v52, v69
	s_waitcnt lgkmcnt(11)
	v_add_f32_e32 v53, v53, v70
	s_waitcnt lgkmcnt(10)
	v_add_f32_e32 v54, v54, v71
	s_waitcnt lgkmcnt(9)
	v_add_f32_e32 v55, v55, v72
	s_waitcnt lgkmcnt(8)
	v_add_f32_e32 v56, v56, v73
	s_waitcnt lgkmcnt(7)
	v_add_f32_e32 v57, v57, v74
	s_waitcnt lgkmcnt(6)
	v_add_f32_e32 v58, v58, v75
	s_waitcnt lgkmcnt(5)
	v_add_f32_e32 v59, v59, v76
	s_waitcnt lgkmcnt(4)
	v_add_f32_e32 v60, v60, v77
	s_waitcnt lgkmcnt(3)
	v_add_f32_e32 v61, v61, v78
	s_waitcnt lgkmcnt(2)
	v_add_f32_e32 v62, v62, v0
	s_waitcnt lgkmcnt(1)
	v_add_f32_e32 v63, v63, v1
	s_waitcnt lgkmcnt(0)
	v_add_f32_e32 v64, v64, v2
	ds_bpermute_b32 v66, v23, v49
	ds_bpermute_b32 v67, v23, v50
	ds_bpermute_b32 v68, v23, v51
	ds_bpermute_b32 v69, v23, v52
	ds_bpermute_b32 v70, v23, v53
	ds_bpermute_b32 v71, v23, v54
	ds_bpermute_b32 v72, v23, v55
	ds_bpermute_b32 v73, v23, v56
	ds_bpermute_b32 v74, v23, v57
	ds_bpermute_b32 v75, v23, v58
	ds_bpermute_b32 v76, v23, v59
	ds_bpermute_b32 v77, v23, v60
	ds_bpermute_b32 v78, v23, v61
	ds_bpermute_b32 v0, v23, v62
	ds_bpermute_b32 v1, v23, v63
	ds_bpermute_b32 v2, v23, v64
	s_waitcnt lgkmcnt(15)
	v_add_f32_e32 v49, v49, v66
	s_waitcnt lgkmcnt(14)
	v_add_f32_e32 v50, v50, v67
	s_waitcnt lgkmcnt(13)
	v_add_f32_e32 v51, v51, v68
	s_waitcnt lgkmcnt(12)
	v_add_f32_e32 v52, v52, v69
	s_waitcnt lgkmcnt(11)
	v_add_f32_e32 v53, v53, v70
	s_waitcnt lgkmcnt(10)
	v_add_f32_e32 v54, v54, v71
	s_waitcnt lgkmcnt(9)
	v_add_f32_e32 v55, v55, v72
	s_waitcnt lgkmcnt(8)
	v_add_f32_e32 v56, v56, v73
	s_waitcnt lgkmcnt(7)
	v_add_f32_e32 v57, v57, v74
	s_waitcnt lgkmcnt(6)
	v_add_f32_e32 v58, v58, v75
	s_waitcnt lgkmcnt(5)
	v_add_f32_e32 v59, v59, v76
	s_waitcnt lgkmcnt(4)
	v_add_f32_e32 v60, v60, v77
	s_waitcnt lgkmcnt(3)
	v_add_f32_e32 v61, v61, v78
	s_waitcnt lgkmcnt(2)
	v_add_f32_e32 v62, v62, v0
	s_waitcnt lgkmcnt(1)
	v_add_f32_e32 v63, v63, v1
	s_waitcnt lgkmcnt(0)
	v_add_f32_e32 v64, v64, v2
	ds_bpermute_b32 v66, v24, v49
	ds_bpermute_b32 v67, v24, v50
	ds_bpermute_b32 v68, v24, v51
	ds_bpermute_b32 v69, v24, v52
	ds_bpermute_b32 v70, v24, v53
	ds_bpermute_b32 v71, v24, v54
	ds_bpermute_b32 v72, v24, v55
	ds_bpermute_b32 v73, v24, v56
	ds_bpermute_b32 v74, v24, v57
	ds_bpermute_b32 v75, v24, v58
	ds_bpermute_b32 v76, v24, v59
	ds_bpermute_b32 v77, v24, v60
	ds_bpermute_b32 v78, v24, v61
	ds_bpermute_b32 v0, v24, v62
	ds_bpermute_b32 v1, v24, v63
	ds_bpermute_b32 v2, v24, v64
	s_waitcnt lgkmcnt(15)
	v_add_f32_e32 v49, v49, v66
	s_waitcnt lgkmcnt(14)
	v_add_f32_e32 v50, v50, v67
	s_waitcnt lgkmcnt(13)
	v_add_f32_e32 v51, v51, v68
	s_waitcnt lgkmcnt(12)
	v_add_f32_e32 v52, v52, v69
	s_waitcnt lgkmcnt(11)
	v_add_f32_e32 v53, v53, v70
	s_waitcnt lgkmcnt(10)
	v_add_f32_e32 v54, v54, v71
	s_waitcnt lgkmcnt(9)
	v_add_f32_e32 v55, v55, v72
	s_waitcnt lgkmcnt(8)
	v_add_f32_e32 v56, v56, v73
	s_waitcnt lgkmcnt(7)
	v_add_f32_e32 v57, v57, v74
	s_waitcnt lgkmcnt(6)
	v_add_f32_e32 v58, v58, v75
	s_waitcnt lgkmcnt(5)
	v_add_f32_e32 v59, v59, v76
	s_waitcnt lgkmcnt(4)
	v_add_f32_e32 v60, v60, v77
	s_waitcnt lgkmcnt(3)
	v_add_f32_e32 v61, v61, v78
	s_waitcnt lgkmcnt(2)
	v_add_f32_e32 v62, v62, v0
	s_waitcnt lgkmcnt(1)
	v_add_f32_e32 v63, v63, v1
	s_waitcnt lgkmcnt(0)
; __device__ __forceinline__ float shfl_xor_f(float v, int mask) { const int l = lane_fresh(); return __int_as_float(__builtin_amdgcn_ds_bpermute((l ^ mask) << 2, __float_as_int(v))); }
; __device__ __forceinline__ float shfl_idx_f(float v, int src) { return __int_as_float(__builtin_amdgcn_ds_bpermute(src << 2, __float_as_int(v))); }
; __device__ __forceinline__ void ssd_sample_item(const Params& p, int item, const int wv) {
;     ...
;   for (int r = 0; r < 32; ++r) {
;     const int pp = 2 * r + hf;
;     f32x4 hv = *(const f32x4*)(st + (size_t)pp * 128 + n4);
;     const float xp = shfl_idx_f(x, pp) * dt;
;     f32x4 hn;
;     float yp = 0.f;
; #pragma unroll
;     for (int e = 0; e < 4; ++e) { hn[e] = dA * hv[e] + xp * Bv[e]; yp += hn[e] * Cv[e]; }
;     *(f32x4*)(so + (size_t)pp * 128 + n4) = hn;
; #pragma unroll
;     for (int o = 16; o >= 1; o >>= 1) yp += shfl_xor_f(yp, o);
;     if ((lane & 31) == r) ymine = yp;
;   }
	v_add_f32_e32 v64, v64, v2
	ds_bpermute_b32 v66, v25, v49
	ds_bpermute_b32 v67, v25, v50
	ds_bpermute_b32 v68, v25, v51
	ds_bpermute_b32 v69, v25, v52
	ds_bpermute_b32 v70, v25, v53
	ds_bpermute_b32 v71, v25, v54
	ds_bpermute_b32 v72, v25, v55
	ds_bpermute_b32 v73, v25, v56
	ds_bpermute_b32 v74, v25, v57
	ds_bpermute_b32 v75, v25, v58
	ds_bpermute_b32 v76, v25, v59
	ds_bpermute_b32 v77, v25, v60
	ds_bpermute_b32 v78, v25, v61
	ds_bpermute_b32 v0, v25, v62
	ds_bpermute_b32 v1, v25, v63
	ds_bpermute_b32 v2, v25, v64
	s_waitcnt lgkmcnt(15)
	v_add_f32_e32 v49, v49, v66
	s_waitcnt lgkmcnt(14)
	v_add_f32_e32 v50, v50, v67
	s_waitcnt lgkmcnt(13)
	v_add_f32_e32 v51, v51, v68
	s_waitcnt lgkmcnt(12)
	v_add_f32_e32 v52, v52, v69
	s_waitcnt lgkmcnt(11)
	v_add_f32_e32 v53, v53, v70
	s_waitcnt lgkmcnt(10)
	v_add_f32_e32 v54, v54, v71
	s_waitcnt lgkmcnt(9)
	v_add_f32_e32 v55, v55, v72
	s_waitcnt lgkmcnt(8)
	v_add_f32_e32 v56, v56, v73
	s_waitcnt lgkmcnt(7)
	v_add_f32_e32 v57, v57, v74
	s_waitcnt lgkmcnt(6)
	v_add_f32_e32 v58, v58, v75
	s_waitcnt lgkmcnt(5)
	v_add_f32_e32 v59, v59, v76
	s_waitcnt lgkmcnt(4)
	v_add_f32_e32 v60, v60, v77
	s_waitcnt lgkmcnt(3)
	v_add_f32_e32 v61, v61, v78
	s_waitcnt lgkmcnt(2)
	v_add_f32_e32 v62, v62, v0
	s_waitcnt lgkmcnt(1)
	v_add_f32_e32 v63, v63, v1
	s_waitcnt lgkmcnt(0)
	v_add_f32_e32 v64, v64, v2
	ds_bpermute_b32 v66, v26, v49
	ds_bpermute_b32 v67, v26, v50
	ds_bpermute_b32 v68, v26, v51
	ds_bpermute_b32 v69, v26, v52
	ds_bpermute_b32 v70, v26, v53
	ds_bpermute_b32 v71, v26, v54
	ds_bpermute_b32 v72, v26, v55
	ds_bpermute_b32 v73, v26, v56
	ds_bpermute_b32 v74, v26, v57
	ds_bpermute_b32 v75, v26, v58
	ds_bpermute_b32 v76, v26, v59
	ds_bpermute_b32 v77, v26, v60
	ds_bpermute_b32 v78, v26, v61
	ds_bpermute_b32 v0, v26, v62
	ds_bpermute_b32 v1, v26, v63
	ds_bpermute_b32 v2, v26, v64
	s_waitcnt lgkmcnt(15)
	v_add_f32_e32 v49, v49, v66
	s_waitcnt lgkmcnt(14)
	v_add_f32_e32 v50, v50, v67
	s_waitcnt lgkmcnt(13)
	v_add_f32_e32 v51, v51, v68
	s_waitcnt lgkmcnt(12)
	v_add_f32_e32 v52, v52, v69
	s_waitcnt lgkmcnt(11)
	v_add_f32_e32 v53, v53, v70
	s_waitcnt lgkmcnt(10)
	v_add_f32_e32 v54, v54, v71
	s_waitcnt lgkmcnt(9)
	v_add_f32_e32 v55, v55, v72
	s_waitcnt lgkmcnt(8)
	v_add_f32_e32 v56, v56, v73
	s_waitcnt lgkmcnt(7)
	v_add_f32_e32 v57, v57, v74
	s_waitcnt lgkmcnt(6)
	v_add_f32_e32 v58, v58, v75
	s_waitcnt lgkmcnt(5)
	v_add_f32_e32 v59, v59, v76
	s_waitcnt lgkmcnt(4)
	v_add_f32_e32 v60, v60, v77
	s_waitcnt lgkmcnt(3)
	v_add_f32_e32 v61, v61, v78
	s_waitcnt lgkmcnt(2)
	v_add_f32_e32 v62, v62, v0
	s_waitcnt lgkmcnt(1)
	v_add_f32_e32 v63, v63, v1
	s_waitcnt lgkmcnt(0)
; __device__ __forceinline__ u16 f2bf(float f) { return (u16)(cvt_pk(f, 0.f) & 0xffffu); }
; __device__ __forceinline__ float bf2f(u16 h) { return __uint_as_float(((unsigned)h) << 16); }
; __device__ __forceinline__ float shfl_xor_f(float v, int mask) { const int l = lane_fresh(); return __int_as_float(__builtin_amdgcn_ds_bpermute((l ^ mask) << 2, __float_as_int(v))); }
; __device__ __forceinline__ float shfl_idx_f(float v, int src) { return __int_as_float(__builtin_amdgcn_ds_bpermute(src << 2, __float_as_int(v))); }
; __device__ __forceinline__ void ssd_sample_item(const Params& p, int item, const int wv) {
;     ...
;   for (int r = 0; r < 32; ++r) {
;     const int pp = 2 * r + hf;
;     f32x4 hv = *(const f32x4*)(st + (size_t)pp * 128 + n4);
;     const float xp = shfl_idx_f(x, pp) * dt;
;     f32x4 hn;
;     float yp = 0.f;
; #pragma unroll
;     for (int e = 0; e < 4; ++e) { hn[e] = dA * hv[e] + xp * Bv[e]; yp += hn[e] * Cv[e]; }
;     *(f32x4*)(so + (size_t)pp * 128 + n4) = hn;
; #pragma unroll
;     for (int o = 16; o >= 1; o >>= 1) yp += shfl_xor_f(yp, o);
;     if ((lane & 31) == r) ymine = yp;
;   }
;   const int pm = 2 * (lane & 31) + hf;
;   const float xm = shfl_idx_f(x, pm);
;   const float zs = bf2f(ZS[(size_t)tok * 1024 + h * 64 + pm]);
;   const float yg = (ymine + xm * p.in[17][h]) * zs;
;   float ss = wave_sum(yg * yg);
;   Y[(size_t)tok * 1024 + h * 64 + pm] = f2bf(yg);
;   if (lane == 0) { YPS[(size_t)tok * 32 + g * 16 + (h & 7) * 2] = ss; YPS[(size_t)tok * 32 + g * 16 + (h & 7) * 2 + 1] = 0.f; }
	v_add_f32_e32 v64, v64, v2
	v_cmp_eq_u32_e64 s[36:37], 0, v29
	v_cmp_eq_u32_e64 s[38:39], 1, v29
	v_cmp_eq_u32_e64 s[40:41], 2, v29
	v_cndmask_b32_e64 v17, v17, v33, s[36:37]
	v_cmp_eq_u32_e64 s[36:37], 3, v29
	v_cndmask_b32_e64 v17, v17, v34, s[38:39]
	v_cmp_eq_u32_e64 s[38:39], 4, v29
	v_cndmask_b32_e64 v17, v17, v35, s[40:41]
	v_cmp_eq_u32_e64 s[40:41], 5, v29
	v_cndmask_b32_e64 v17, v17, v36, s[36:37]
	v_cmp_eq_u32_e64 s[36:37], 6, v29
	v_cndmask_b32_e64 v17, v17, v37, s[38:39]
	v_cmp_eq_u32_e64 s[38:39], 7, v29
	v_cndmask_b32_e64 v17, v17, v38, s[40:41]
	v_cmp_eq_u32_e64 s[40:41], 8, v29
	v_cndmask_b32_e64 v17, v17, v39, s[36:37]
	v_cmp_eq_u32_e64 s[36:37], 9, v29
	v_cndmask_b32_e64 v17, v17, v40, s[38:39]
	v_cmp_eq_u32_e64 s[38:39], 10, v29
	v_cndmask_b32_e64 v17, v17, v41, s[40:41]
	v_cmp_eq_u32_e64 s[40:41], 11, v29
	v_cndmask_b32_e64 v17, v17, v42, s[36:37]
	v_cmp_eq_u32_e64 s[36:37], 12, v29
	v_cndmask_b32_e64 v17, v17, v43, s[38:39]
	v_cmp_eq_u32_e64 s[38:39], 13, v29
	v_cndmask_b32_e64 v17, v17, v44, s[40:41]
	v_cmp_eq_u32_e64 s[40:41], 14, v29
	v_cndmask_b32_e64 v17, v17, v45, s[36:37]
	v_cmp_eq_u32_e64 s[36:37], 15, v29
	v_cndmask_b32_e64 v17, v17, v46, s[38:39]
	v_cmp_eq_u32_e64 s[38:39], 16, v29
	v_cndmask_b32_e64 v17, v17, v47, s[40:41]
	v_cmp_eq_u32_e64 s[40:41], 17, v29
	v_cndmask_b32_e64 v17, v17, v48, s[36:37]
	v_cmp_eq_u32_e64 s[36:37], 18, v29
	v_cndmask_b32_e64 v17, v17, v49, s[38:39]
	v_cmp_eq_u32_e64 s[38:39], 19, v29
	v_cndmask_b32_e64 v17, v17, v50, s[40:41]
	v_cmp_eq_u32_e64 s[40:41], 20, v29
	v_cndmask_b32_e64 v17, v17, v51, s[36:37]
	v_cmp_eq_u32_e64 s[36:37], 21, v29
	v_cndmask_b32_e64 v17, v17, v52, s[38:39]
	v_cmp_eq_u32_e64 s[38:39], 22, v29
	v_cndmask_b32_e64 v17, v17, v53, s[40:41]
	v_cmp_eq_u32_e64 s[40:41], 23, v29
	v_cndmask_b32_e64 v17, v17, v54, s[36:37]
	v_cmp_eq_u32_e64 s[36:37], 24, v29
	v_cndmask_b32_e64 v17, v17, v55, s[38:39]
	v_cmp_eq_u32_e64 s[38:39], 25, v29
	v_cndmask_b32_e64 v17, v17, v56, s[40:41]
	v_cmp_eq_u32_e64 s[40:41], 26, v29
	v_cndmask_b32_e64 v17, v17, v57, s[36:37]
	v_cmp_eq_u32_e64 s[36:37], 27, v29
	v_cndmask_b32_e64 v17, v17, v58, s[38:39]
	v_cmp_eq_u32_e64 s[38:39], 28, v29
	v_cndmask_b32_e64 v17, v17, v59, s[40:41]
	v_cmp_eq_u32_e64 s[40:41], 29, v29
	v_cndmask_b32_e64 v17, v17, v60, s[36:37]
	v_cmp_eq_u32_e64 s[36:37], 30, v29
	v_cndmask_b32_e64 v17, v17, v61, s[38:39]
	v_cmp_eq_u32_e64 s[38:39], 31, v29
	v_cndmask_b32_e64 v17, v17, v62, s[40:41]
	s_nop 1
	v_cndmask_b32_e64 v17, v17, v63, s[36:37]
	v_cndmask_b32_e64 v17, v17, v64, s[38:39]
	v_add_u32_e32 v32, 0x100, v32
	s_mov_b32 s10, 32
	s_mov_b64 s[12:13], 0x8000
	s_lshl_b32 s10, s31, 11
	s_add_u32 s0, s17, s10
	v_lshl_add_u32 v0, v29, 1, v16
	s_addc_u32 s1, s18, 0
	s_lshl_b32 s12, s34, 1
	v_ashrrev_i32_e32 v1, 31, v0
	s_add_u32 s0, s0, s12
	s_addc_u32 s1, s1, 0
	v_lshlrev_b64 v[2:3], 1, v[0:1]
	v_lshl_add_u64 v[6:7], s[0:1], 0, v[2:3]
	s_lshl_b32 s0, s33, 2
	v_readlane_b32 s60, v251, 22
	v_mov_b32_e32 v4, s0
	v_readlane_b32 s62, v251, 24
	v_readlane_b32 s63, v251, 25
	global_load_ushort v1, v[6:7], off
	v_lshlrev_b32_e32 v0, 2, v0
	ds_bpermute_b32 v0, v0, v31
	s_add_u32 s0, s48, s10
	s_addc_u32 s1, s49, 0
	global_load_dword v4, v4, s[62:63]
	v_mbcnt_lo_u32_b32 v6, -1, 0
	v_mbcnt_hi_u32_b32 v6, -1, v6
	v_cmp_eq_u32_e32 vcc, 0, v28
	v_lshlrev_b32_e32 v6, 2, v6
	v_xor_b32_e32 v6, 0x80, v6
	v_readlane_b32 s61, v251, 23
	v_readlane_b32 s64, v251, 26
	v_readlane_b32 s65, v251, 27
	v_readlane_b32 s66, v251, 28
	v_readlane_b32 s67, v251, 29
	v_readlane_b32 s68, v251, 30
	v_readlane_b32 s69, v251, 31
	v_readlane_b32 s70, v251, 32
	v_readlane_b32 s71, v251, 33
	v_readlane_b32 s72, v251, 34
	v_readlane_b32 s73, v251, 35
	v_readlane_b32 s74, v251, 36
	v_readlane_b32 s75, v251, 37
	s_waitcnt vmcnt(1)
	v_lshlrev_b32_e32 v1, 16, v1
	s_waitcnt vmcnt(0) lgkmcnt(0)
	v_fmac_f32_e32 v17, v4, v0
	v_mul_f32_e32 v0, v17, v1
	v_mul_f32_e32 v1, v0, v0
	ds_bpermute_b32 v1, v6, v1
	v_mbcnt_lo_u32_b32 v4, -1, 0
	v_mbcnt_hi_u32_b32 v4, -1, v4
	v_mbcnt_lo_u32_b32 v6, -1, 0
	v_mbcnt_hi_u32_b32 v6, -1, v6
	s_waitcnt lgkmcnt(0)
	v_fmac_f32_e32 v1, v0, v0
	v_lshlrev_b32_e32 v4, 2, v4
	v_xor_b32_e32 v4, 64, v4
	ds_bpermute_b32 v4, v4, v1
	v_lshlrev_b32_e32 v6, 2, v6
	v_xor_b32_e32 v6, 32, v6
	s_waitcnt lgkmcnt(0)
	v_add_f32_e32 v1, v1, v4
	ds_bpermute_b32 v4, v6, v1
	v_mbcnt_lo_u32_b32 v6, -1, 0
	v_mbcnt_hi_u32_b32 v6, -1, v6
	s_waitcnt lgkmcnt(0)
	v_add_f32_e32 v1, v1, v4
	v_lshlrev_b32_e32 v6, 2, v6
	v_xor_b32_e32 v6, 16, v6
	ds_bpermute_b32 v4, v6, v1
	v_mbcnt_lo_u32_b32 v6, -1, 0
	v_mbcnt_hi_u32_b32 v6, -1, v6
	v_mbcnt_lo_u32_b32 v7, -1, 0
	v_mbcnt_hi_u32_b32 v7, -1, v7
	s_waitcnt lgkmcnt(0)
	v_add_f32_e32 v1, v1, v4
	v_lshlrev_b32_e32 v6, 2, v6
	v_xor_b32_e32 v6, 8, v6
	ds_bpermute_b32 v4, v6, v1
	v_lshlrev_b32_e32 v6, 2, v7
	v_xor_b32_e32 v6, 4, v6
	v_cvt_pk_bf16_f32 v7, v0, s0
	s_add_u32 s0, s0, s12
	s_waitcnt lgkmcnt(0)
	v_add_f32_e32 v0, v1, v4
	ds_bpermute_b32 v1, v6, v0
	s_addc_u32 s1, s1, 0
	v_lshl_add_u64 v[2:3], s[0:1], 0, v[2:3]
	global_store_short v[2:3], v7, off
	s_and_saveexec_b64 s[0:1], vcc
	s_cbranch_execz .LBB0_455
	s_lshl_b32 s10, s31, 7
	s_add_u32 s10, s19, s10
	s_addc_u32 s13, s20, 0
	s_lshl_b32 s12, s30, 6
	s_add_u32 s12, s10, s12
	s_addc_u32 s13, s13, 0
	s_lshl_b32 s10, s29, 3
	s_and_b32 s10, s10, 56
	s_waitcnt lgkmcnt(0)
	v_add_f32_e32 v4, v0, v1
	v_mov_b32_e32 v0, s10
	global_store_dwordx2 v0, v[4:5], s[12:13]
	s_branch .LBB0_455

; __device__ __forceinline__ u32x2 pack4(f32x4 v) { u32x2 r; r.x = cvt_pk(v[0], v[1]); r.y = cvt_pk(v[2], v[3]); return r; }
; __device__ __forceinline__ f32x4 unpack4(u32x2 w) { return (f32x4){bflo(w.x), bfhi(w.x), bflo(w.y), bfhi(w.y)}; }
; __device__ __forceinline__ void phaseD(const Params& p, const int wv, const int rep) {
;     ...
;       for (int g = 0; g < 8; ++g) {
;         __builtin_amdgcn_sched_barrier(0);
;         const int ai = g >> 2, m = g & 3, rrow = ai * 128 + wr * 64 + m * 16 + fr, row_ = brow + rrow;
;         const float rs0 = rs_l[rrow * 2], rs1 = rs_l[rrow * 2 + 1];
;         const float rsc = (br == 0) ? __builtin_amdgcn_rcpf(rs0) : (br == 1) ? rs0 * __builtin_amdgcn_rcpf(rs1) : (br == 2) ? rs1 : 1.f;
; #pragma unroll
;         for (int bj = 0; bj < 2; ++bj) {
;           u32x2 gnp[2], gdp[2];
;           unpair16(gw[g & 3][bj], gnp[0], gnp[1]); unpair16(dw[g & 3][bj], gdp[0], gdp[1]);
; #pragma unroll
;           for (int n = 0; n < 2; ++n) {
;             const f32x4 gn = unpack4(gnp[n]), gd = unpack4(gdp[n]);
;             f32x4 sc;
; #pragma unroll
;             for (int e = 0; e < 4; ++e) sc[e] = gn[e] * rsc * __builtin_amdgcn_rcpf(fmaxf(gd[e], 1e-30f));
;             acc[ai][bj][m][n] = acc[ai][bj][m][n] * sc;
;           }
;         }
;         if (br == 3) {
;           u16* mrow = MERGED + (size_t)row_ * 1024 + bcol + wc * 32;
;           store_pair16(mrow, pack4(acc[ai][0][m][0]), pack4(acc[ai][0][m][1]), fq);
;           store_pair16(mrow + 128, pack4(acc[ai][1][m][0]), pack4(acc[ai][1][m][1]), fq);
;         }
.LBB0_783:
	v_permlane16_swap_b32_e32 v199, v150
	v_lshlrev_b32_e32 v140, 16, v199
	v_max_f32_e32 v140, v140, v140
	v_and_b32_e32 v157, 0xffff0000, v199
	v_max_f32_e32 v140, 0xda24260, v140
	v_permlane16_swap_b32_e32 v198, v151
	v_rcp_f32_e32 v156, v140
	v_max_f32_e32 v140, v157, v157
	v_lshlrev_b32_e32 v199, 16, v198
	v_max_f32_e32 v140, 0xda24260, v140
	v_permlane16_swap_b32_e32 v200, v145
	v_rcp_f32_e32 v157, v140
	v_max_f32_e32 v140, v199, v199
	v_lshlrev_b32_e32 v134, 16, v200
	v_and_b32_e32 v135, 0xffff0000, v200
	v_and_b32_e32 v200, 0xffff0000, v198
	v_max_f32_e32 v140, 0xda24260, v140
	v_rcp_f32_e32 v198, v140
	v_max_f32_e32 v140, v200, v200
	v_max_f32_e32 v140, 0xda24260, v140
	v_rcp_f32_e32 v199, v140
	v_permlane16_swap_b32_e32 v207, v144
	s_waitcnt lgkmcnt(0)
	v_lshlrev_b32_e32 v130, 16, v207
	v_and_b32_e32 v131, 0xffff0000, v207
	v_pk_mul_f32 v[134:135], v[0:1], v[134:135] op_sel_hi:[0,1]
	v_lshlrev_b32_e32 v140, 16, v150
	v_pk_mul_f32 v[130:131], v[0:1], v[130:131] op_sel_hi:[0,1]
	v_pk_mul_f32 v[134:135], v[134:135], v[198:199]
	v_max_f32_e32 v140, v140, v140
	v_pk_mul_f32 v[130:131], v[130:131], v[156:157]
	v_pk_mul_f32 v[32:33], v[32:33], v[134:135]
	v_lshlrev_b32_e32 v134, 16, v145
	v_and_b32_e32 v135, 0xffff0000, v145
	v_and_b32_e32 v145, 0xffff0000, v150
	v_max_f32_e32 v140, 0xda24260, v140
	v_pk_mul_f32 v[30:31], v[30:31], v[130:131]
	v_lshlrev_b32_e32 v130, 16, v144
	v_and_b32_e32 v131, 0xffff0000, v144
	v_rcp_f32_e32 v144, v140
	v_max_f32_e32 v140, v145, v145
	v_lshlrev_b32_e32 v150, 16, v151
	v_max_f32_e32 v140, 0xda24260, v140
	v_rcp_f32_e32 v145, v140
	v_max_f32_e32 v140, v150, v150
	v_and_b32_e32 v151, 0xffff0000, v151
	v_max_f32_e32 v140, 0xda24260, v140
	v_rcp_f32_e32 v150, v140
	v_max_f32_e32 v140, v151, v151
	v_max_f32_e32 v140, 0xda24260, v140
	s_waitcnt vmcnt(0)
	v_permlane16_swap_b32_e32 v152, v154
	v_rcp_f32_e32 v151, v140
	v_lshlrev_b32_e32 v140, 16, v152
	v_pk_mul_f32 v[130:131], v[0:1], v[130:131] op_sel_hi:[0,1]
	v_max_f32_e32 v140, v140, v140
	v_pk_mul_f32 v[130:131], v[130:131], v[144:145]
	v_and_b32_e32 v145, 0xffff0000, v152
	v_max_f32_e32 v140, 0xda24260, v140
	v_permlane16_swap_b32_e32 v146, v148
	v_permlane16_swap_b32_e32 v153, v155
	v_rcp_f32_e32 v144, v140
	v_max_f32_e32 v140, v145, v145
	v_pk_mul_f32 v[134:135], v[0:1], v[134:135] op_sel_hi:[0,1]
	v_pk_mul_f32 v[38:39], v[38:39], v[130:131]
	v_lshlrev_b32_e32 v130, 16, v146
	v_and_b32_e32 v131, 0xffff0000, v146
	v_lshlrev_b32_e32 v146, 16, v153
	v_max_f32_e32 v140, 0xda24260, v140
	v_pk_mul_f32 v[134:135], v[134:135], v[150:151]
	v_permlane16_swap_b32_e32 v147, v149
	v_rcp_f32_e32 v145, v140
	v_max_f32_e32 v140, v146, v146
	v_pk_mul_f32 v[40:41], v[40:41], v[134:135]
	v_lshlrev_b32_e32 v134, 16, v147
	v_and_b32_e32 v135, 0xffff0000, v147
	v_and_b32_e32 v147, 0xffff0000, v153
	v_max_f32_e32 v140, 0xda24260, v140
	v_rcp_f32_e32 v146, v140
	v_max_f32_e32 v140, v147, v147
	v_max_f32_e32 v140, 0xda24260, v140
	v_rcp_f32_e32 v147, v140
	v_lshlrev_b32_e32 v140, 16, v154
	v_pk_mul_f32 v[130:131], v[0:1], v[130:131] op_sel_hi:[0,1]
	v_max_f32_e32 v140, v140, v140
	v_pk_mul_f32 v[130:131], v[130:131], v[144:145]
	v_and_b32_e32 v145, 0xffff0000, v154
	v_max_f32_e32 v140, 0xda24260, v140
	v_pk_mul_f32 v[134:135], v[0:1], v[134:135] op_sel_hi:[0,1]
	v_rcp_f32_e32 v144, v140
	v_max_f32_e32 v140, v145, v145
	v_pk_mul_f32 v[134:135], v[134:135], v[146:147]
	v_lshlrev_b32_e32 v146, 16, v155
	v_max_f32_e32 v140, 0xda24260, v140
	v_rcp_f32_e32 v145, v140
	v_max_f32_e32 v140, v146, v146
	v_and_b32_e32 v147, 0xffff0000, v155
	v_max_f32_e32 v140, 0xda24260, v140
	v_rcp_f32_e32 v146, v140
	v_max_f32_e32 v140, v147, v147
	v_max_f32_e32 v140, 0xda24260, v140
	v_rcp_f32_e32 v147, v140
	v_pk_mul_f32 v[44:45], v[44:45], v[134:135]
	v_pk_mul_f32 v[42:43], v[42:43], v[130:131]
	v_lshlrev_b32_e32 v130, 16, v148
	v_and_b32_e32 v131, 0xffff0000, v148
	v_lshlrev_b32_e32 v134, 16, v149
	v_and_b32_e32 v135, 0xffff0000, v149
	v_pk_mul_f32 v[134:135], v[0:1], v[134:135] op_sel_hi:[0,1]
	v_pk_mul_f32 v[130:131], v[0:1], v[130:131] op_sel_hi:[0,1]
	v_pk_mul_f32 v[130:131], v[130:131], v[144:145]
	v_pk_mul_f32 v[134:135], v[134:135], v[146:147]
	v_cndmask_b32_e64 v0, 0, 1, s[8:9]
	v_pk_mul_f32 v[48:49], v[48:49], v[134:135]
	v_cmp_ne_u32_e64 s[6:7], 1, v0
	s_andn2_b64 vcc, exec, s[8:9]
	v_pk_mul_f32 v[46:47], v[46:47], v[130:131]
	s_cbranch_vccnz .LBB0_785
	v_add_u32_e32 v0, s90, v141
	v_lshlrev_b64 v[130:131], 11, v[0:1]
	v_lshl_add_u64 v[130:131], s[54:55], 0, v[130:131]
	v_cvt_pk_bf16_f32 v144, v30, v31
	v_cvt_pk_bf16_f32 v145, v32, v33
	v_cvt_pk_bf16_f32 v146, v38, v39
	v_cvt_pk_bf16_f32 v147, v40, v41
	s_nop 0
	v_permlane16_swap_b32_e32 v144, v146
	v_permlane16_swap_b32_e32 v145, v147
	v_lshl_add_u64 v[130:131], v[184:185], 1, v[130:131]
	global_store_dwordx4 v[130:131], v[144:147], off sc1
	s_nop 1
	v_cvt_pk_bf16_f32 v144, v42, v43
	v_cvt_pk_bf16_f32 v145, v44, v45
	v_cvt_pk_bf16_f32 v146, v46, v47
	v_cvt_pk_bf16_f32 v147, v48, v49
	s_nop 0
	v_permlane16_swap_b32_e32 v144, v146
	v_permlane16_swap_b32_e32 v145, v147
	global_store_dwordx4 v[130:131], v[144:147], off offset:256 sc1

; __device__ __forceinline__ u32x2 pack4(f32x4 v) { u32x2 r; r.x = cvt_pk(v[0], v[1]); r.y = cvt_pk(v[2], v[3]); return r; }
; __device__ __forceinline__ f32x4 unpack4(u32x2 w) { return (f32x4){bflo(w.x), bfhi(w.x), bflo(w.y), bfhi(w.y)}; }
; __device__ __forceinline__ void phaseD(const Params& p, const int wv, const int rep) {
;     ...
;       for (int g = 0; g < 8; ++g) {
;         __builtin_amdgcn_sched_barrier(0);
;         const int ai = g >> 2, m = g & 3, rrow = ai * 128 + wr * 64 + m * 16 + fr, row_ = brow + rrow;
;         const float rs0 = rs_l[rrow * 2], rs1 = rs_l[rrow * 2 + 1];
;         const float rsc = (br == 0) ? __builtin_amdgcn_rcpf(rs0) : (br == 1) ? rs0 * __builtin_amdgcn_rcpf(rs1) : (br == 2) ? rs1 : 1.f;
; #pragma unroll
;         for (int bj = 0; bj < 2; ++bj) {
;           u32x2 gnp[2], gdp[2];
;           unpair16(gw[g & 3][bj], gnp[0], gnp[1]); unpair16(dw[g & 3][bj], gdp[0], gdp[1]);
; #pragma unroll
;           for (int n = 0; n < 2; ++n) {
;             const f32x4 gn = unpack4(gnp[n]), gd = unpack4(gdp[n]);
;             f32x4 sc;
; #pragma unroll
;             for (int e = 0; e < 4; ++e) sc[e] = gn[e] * rsc * __builtin_amdgcn_rcpf(fmaxf(gd[e], 1e-30f));
;             acc[ai][bj][m][n] = acc[ai][bj][m][n] * sc;
;           }
;         }
;         if (br == 3) {
;           u16* mrow = MERGED + (size_t)row_ * 1024 + bcol + wc * 32;
;           store_pair16(mrow, pack4(acc[ai][0][m][0]), pack4(acc[ai][0][m][1]), fq);
;           store_pair16(mrow + 128, pack4(acc[ai][1][m][0]), pack4(acc[ai][1][m][1]), fq);
;         }
.LBB0_808:
	v_permlane16_swap_b32_e32 v183, v176
	v_lshlrev_b32_e32 v155, 16, v183
	v_max_f32_e32 v155, v155, v155
	v_permlane16_swap_b32_e32 v206, v170
	v_permlane16_swap_b32_e32 v205, v171
	v_permlane16_swap_b32_e32 v182, v177
	v_and_b32_e32 v183, 0xffff0000, v183
	v_max_f32_e32 v155, 0xda24260, v155
	s_waitcnt lgkmcnt(0)
	v_lshlrev_b32_e32 v134, 16, v206
	v_and_b32_e32 v135, 0xffff0000, v206
	v_lshlrev_b32_e32 v206, 16, v205
	v_and_b32_e32 v207, 0xffff0000, v205
	v_lshlrev_b32_e32 v205, 16, v182
	v_and_b32_e32 v209, 0xffff0000, v182
	v_rcp_f32_e32 v182, v155
	v_max_f32_e32 v155, v183, v183
	v_max_f32_e32 v155, 0xda24260, v155
	v_rcp_f32_e32 v183, v155
	v_max_f32_e32 v155, v205, v205
	v_max_f32_e32 v155, 0xda24260, v155
	v_rcp_f32_e32 v208, v155
	v_max_f32_e32 v155, v209, v209
	v_max_f32_e32 v155, 0xda24260, v155
	v_rcp_f32_e32 v209, v155
	v_pk_mul_f32 v[206:207], v[0:1], v[206:207] op_sel_hi:[0,1]
	v_pk_mul_f32 v[134:135], v[0:1], v[134:135] op_sel_hi:[0,1]
	v_lshlrev_b32_e32 v155, 16, v176
	v_pk_mul_f32 v[134:135], v[134:135], v[182:183]
	v_pk_mul_f32 v[182:183], v[206:207], v[208:209]
	v_max_f32_e32 v155, v155, v155
	v_pk_mul_f32 v[72:73], v[72:73], v[182:183]
	v_and_b32_e32 v182, 0xffff0000, v176
	v_max_f32_e32 v155, 0xda24260, v155
	v_rcp_f32_e32 v176, v155
	v_max_f32_e32 v155, v182, v182
	v_lshlrev_b32_e32 v183, 16, v177
	v_max_f32_e32 v155, 0xda24260, v155
	v_and_b32_e32 v205, 0xffff0000, v177
	v_rcp_f32_e32 v177, v155
	v_max_f32_e32 v155, v183, v183
	v_max_f32_e32 v155, 0xda24260, v155
	v_rcp_f32_e32 v182, v155
	v_max_f32_e32 v155, v205, v205
	v_max_f32_e32 v155, 0xda24260, v155
	v_rcp_f32_e32 v183, v155
	v_pk_mul_f32 v[70:71], v[70:71], v[134:135]
	v_lshlrev_b32_e32 v134, 16, v170
	v_and_b32_e32 v135, 0xffff0000, v170
	v_lshlrev_b32_e32 v170, 16, v171
	v_and_b32_e32 v171, 0xffff0000, v171
	v_permlane16_swap_b32_e32 v178, v180
	v_pk_mul_f32 v[170:171], v[0:1], v[170:171] op_sel_hi:[0,1]
	v_lshlrev_b32_e32 v155, 16, v178
	v_pk_mul_f32 v[134:135], v[0:1], v[134:135] op_sel_hi:[0,1]
	v_pk_mul_f32 v[170:171], v[170:171], v[182:183]
	v_permlane16_swap_b32_e32 v173, v175
	v_max_f32_e32 v155, v155, v155
	v_pk_mul_f32 v[134:135], v[134:135], v[176:177]
	v_pk_mul_f32 v[80:81], v[80:81], v[170:171]
	v_permlane16_swap_b32_e32 v172, v174
	v_lshlrev_b32_e32 v170, 16, v173
	v_and_b32_e32 v171, 0xffff0000, v173
	v_and_b32_e32 v173, 0xffff0000, v178
	v_max_f32_e32 v155, 0xda24260, v155
	v_pk_mul_f32 v[78:79], v[78:79], v[134:135]
	v_permlane16_swap_b32_e32 v179, v181
	v_lshlrev_b32_e32 v134, 16, v172
	v_and_b32_e32 v135, 0xffff0000, v172
	v_rcp_f32_e32 v172, v155
	v_max_f32_e32 v155, v173, v173
	v_lshlrev_b32_e32 v176, 16, v179
	v_max_f32_e32 v155, 0xda24260, v155
	v_rcp_f32_e32 v173, v155
	v_max_f32_e32 v155, v176, v176
	v_and_b32_e32 v177, 0xffff0000, v179
	v_max_f32_e32 v155, 0xda24260, v155
	v_rcp_f32_e32 v176, v155
	v_max_f32_e32 v155, v177, v177
	v_max_f32_e32 v155, 0xda24260, v155
	v_rcp_f32_e32 v177, v155
	v_lshlrev_b32_e32 v155, 16, v180
	v_pk_mul_f32 v[134:135], v[0:1], v[134:135] op_sel_hi:[0,1]
	v_max_f32_e32 v155, v155, v155
	v_pk_mul_f32 v[134:135], v[134:135], v[172:173]
	v_and_b32_e32 v173, 0xffff0000, v180
	v_max_f32_e32 v155, 0xda24260, v155
	v_rcp_f32_e32 v172, v155
	v_max_f32_e32 v155, v173, v173
	v_pk_mul_f32 v[170:171], v[0:1], v[170:171] op_sel_hi:[0,1]
	v_pk_mul_f32 v[82:83], v[82:83], v[134:135]
	v_lshlrev_b32_e32 v134, 16, v174
	v_and_b32_e32 v135, 0xffff0000, v174
	v_lshlrev_b32_e32 v174, 16, v181
	v_max_f32_e32 v155, 0xda24260, v155
	v_pk_mul_f32 v[170:171], v[170:171], v[176:177]
	v_rcp_f32_e32 v173, v155
	v_max_f32_e32 v155, v174, v174
	v_pk_mul_f32 v[84:85], v[84:85], v[170:171]
	v_lshlrev_b32_e32 v170, 16, v175
	v_and_b32_e32 v171, 0xffff0000, v175
	v_and_b32_e32 v175, 0xffff0000, v181
	v_max_f32_e32 v155, 0xda24260, v155
	v_rcp_f32_e32 v174, v155
	v_max_f32_e32 v155, v175, v175
	v_max_f32_e32 v155, 0xda24260, v155
	v_rcp_f32_e32 v175, v155
	v_pk_mul_f32 v[170:171], v[0:1], v[170:171] op_sel_hi:[0,1]
	v_pk_mul_f32 v[134:135], v[0:1], v[134:135] op_sel_hi:[0,1]
	v_pk_mul_f32 v[134:135], v[134:135], v[172:173]
	v_pk_mul_f32 v[170:171], v[170:171], v[174:175]
	s_and_b64 vcc, exec, s[6:7]
	v_pk_mul_f32 v[92:93], v[92:93], v[170:171]
	v_pk_mul_f32 v[90:91], v[90:91], v[134:135]
	s_cbranch_vccnz .LBB0_810
	v_add_u32_e32 v0, s90, v154
	v_lshlrev_b64 v[134:135], 11, v[0:1]
	v_lshl_add_u64 v[134:135], s[54:55], 0, v[134:135]
	v_cvt_pk_bf16_f32 v170, v70, v71
	v_cvt_pk_bf16_f32 v171, v72, v73
	v_cvt_pk_bf16_f32 v172, v78, v79
	v_cvt_pk_bf16_f32 v173, v80, v81
	s_nop 0
	v_permlane16_swap_b32_e32 v170, v172
	v_permlane16_swap_b32_e32 v171, v173
	v_lshl_add_u64 v[134:135], v[184:185], 1, v[134:135]
	global_store_dwordx4 v[134:135], v[170:173], off sc1
	s_nop 1
	v_cvt_pk_bf16_f32 v170, v82, v83
	v_cvt_pk_bf16_f32 v171, v84, v85
	v_cvt_pk_bf16_f32 v172, v90, v91
	v_cvt_pk_bf16_f32 v173, v92, v93
	s_nop 0
	v_permlane16_swap_b32_e32 v170, v172
	v_permlane16_swap_b32_e32 v171, v173
	global_store_dwordx4 v[134:135], v[170:173], off offset:256 sc1

; __device__ __forceinline__ u32x2 pack4(f32x4 v) { u32x2 r; r.x = cvt_pk(v[0], v[1]); r.y = cvt_pk(v[2], v[3]); return r; }
; __device__ __forceinline__ f32x4 unpack4(u32x2 w) { return (f32x4){bflo(w.x), bfhi(w.x), bflo(w.y), bfhi(w.y)}; }
; __device__ __forceinline__ void phaseD(const Params& p, const int wv, const int rep) {
;     ...
;       for (int g = 0; g < 8; ++g) {
;         __builtin_amdgcn_sched_barrier(0);
;         const int ai = g >> 2, m = g & 3, rrow = ai * 128 + wr * 64 + m * 16 + fr, row_ = brow + rrow;
;         const float rs0 = rs_l[rrow * 2], rs1 = rs_l[rrow * 2 + 1];
;         const float rsc = (br == 0) ? __builtin_amdgcn_rcpf(rs0) : (br == 1) ? rs0 * __builtin_amdgcn_rcpf(rs1) : (br == 2) ? rs1 : 1.f;
; #pragma unroll
;         for (int bj = 0; bj < 2; ++bj) {
;           u32x2 gnp[2], gdp[2];
;           unpair16(gw[g & 3][bj], gnp[0], gnp[1]); unpair16(dw[g & 3][bj], gdp[0], gdp[1]);
; #pragma unroll
;           for (int n = 0; n < 2; ++n) {
;             const f32x4 gn = unpack4(gnp[n]), gd = unpack4(gdp[n]);
;             f32x4 sc;
; #pragma unroll
;             for (int e = 0; e < 4; ++e) sc[e] = gn[e] * rsc * __builtin_amdgcn_rcpf(fmaxf(gd[e], 1e-30f));
;             acc[ai][bj][m][n] = acc[ai][bj][m][n] * sc;
;           }
;         }
;         if (br == 3) {
;           u16* mrow = MERGED + (size_t)row_ * 1024 + bcol + wc * 32;
;           store_pair16(mrow, pack4(acc[ai][0][m][0]), pack4(acc[ai][0][m][1]), fq);
;           store_pair16(mrow + 128, pack4(acc[ai][1][m][0]), pack4(acc[ai][1][m][1]), fq);
;         }
.LBB0_833:
	v_permlane16_swap_b32_e32 v204, v158
	v_permlane16_swap_b32_e32 v203, v159
	v_permlane16_swap_b32_e32 v202, v164
	v_permlane16_swap_b32_e32 v201, v165
	s_waitcnt lgkmcnt(0)
	v_lshlrev_b32_e32 v134, 16, v204
	v_and_b32_e32 v135, 0xffff0000, v204
	v_lshlrev_b32_e32 v170, 16, v203
	v_and_b32_e32 v171, 0xffff0000, v203
	v_lshlrev_b32_e32 v203, 16, v202
	v_and_b32_e32 v204, 0xffff0000, v202
	v_lshlrev_b32_e32 v207, 16, v201
	v_and_b32_e32 v201, 0xffff0000, v201
	v_max_f32_e32 v202, v203, v203
	v_max_f32_e32 v203, v204, v204
	v_max_f32_e32 v204, v207, v207
	v_max_f32_e32 v201, v201, v201
	v_max_f32_e32 v204, 0xda24260, v204
	v_max_f32_e32 v201, 0xda24260, v201
	v_max_f32_e32 v202, 0xda24260, v202
	v_max_f32_e32 v203, 0xda24260, v203
	v_rcp_f32_e32 v208, v204
	v_rcp_f32_e32 v209, v201
	v_rcp_f32_e32 v202, v202
	v_rcp_f32_e32 v203, v203
	v_pk_mul_f32 v[170:171], v[0:1], v[170:171] op_sel_hi:[0,1]
	v_pk_mul_f32 v[134:135], v[0:1], v[134:135] op_sel_hi:[0,1]
	v_pk_mul_f32 v[170:171], v[170:171], v[208:209]
	v_pk_mul_f32 v[134:135], v[134:135], v[202:203]
	v_pk_mul_f32 v[108:109], v[108:109], v[170:171]
	v_lshlrev_b32_e32 v170, 16, v164
	v_and_b32_e32 v171, 0xffff0000, v164
	v_lshlrev_b32_e32 v201, 16, v165
	v_and_b32_e32 v202, 0xffff0000, v165
	v_max_f32_e32 v164, v170, v170
	v_max_f32_e32 v165, v171, v171
	v_max_f32_e32 v170, v201, v201
	v_max_f32_e32 v171, v202, v202
	v_max_f32_e32 v164, 0xda24260, v164
	v_max_f32_e32 v165, 0xda24260, v165
	v_max_f32_e32 v170, 0xda24260, v170
	v_max_f32_e32 v171, 0xda24260, v171
	v_rcp_f32_e32 v164, v164
	v_rcp_f32_e32 v165, v165
	v_rcp_f32_e32 v170, v170
	v_rcp_f32_e32 v171, v171
	v_pk_mul_f32 v[106:107], v[106:107], v[134:135]
	v_lshlrev_b32_e32 v134, 16, v158
	v_and_b32_e32 v135, 0xffff0000, v158
	v_lshlrev_b32_e32 v158, 16, v159
	v_and_b32_e32 v159, 0xffff0000, v159
	v_pk_mul_f32 v[158:159], v[0:1], v[158:159] op_sel_hi:[0,1]
	v_pk_mul_f32 v[134:135], v[0:1], v[134:135] op_sel_hi:[0,1]
	v_pk_mul_f32 v[134:135], v[134:135], v[164:165]
	v_pk_mul_f32 v[158:159], v[158:159], v[170:171]
	v_permlane16_swap_b32_e32 v160, v162
	v_permlane16_swap_b32_e32 v161, v163
	v_permlane16_swap_b32_e32 v166, v168
	v_permlane16_swap_b32_e32 v167, v169
	v_pk_mul_f32 v[116:117], v[116:117], v[158:159]
	v_pk_mul_f32 v[114:115], v[114:115], v[134:135]
	v_lshlrev_b32_e32 v134, 16, v160
	v_and_b32_e32 v135, 0xffff0000, v160
	v_lshlrev_b32_e32 v158, 16, v161
	v_and_b32_e32 v159, 0xffff0000, v161
	v_lshlrev_b32_e32 v160, 16, v166
	v_and_b32_e32 v161, 0xffff0000, v166
	v_lshlrev_b32_e32 v164, 16, v167
	v_and_b32_e32 v165, 0xffff0000, v167
	v_max_f32_e32 v160, v160, v160
	v_max_f32_e32 v161, v161, v161
	v_max_f32_e32 v164, v164, v164
	v_max_f32_e32 v165, v165, v165
	v_max_f32_e32 v160, 0xda24260, v160
	v_max_f32_e32 v161, 0xda24260, v161
	v_max_f32_e32 v164, 0xda24260, v164
	v_max_f32_e32 v165, 0xda24260, v165
	v_rcp_f32_e32 v160, v160
	v_rcp_f32_e32 v161, v161
	v_rcp_f32_e32 v164, v164
	v_rcp_f32_e32 v165, v165
	v_pk_mul_f32 v[158:159], v[0:1], v[158:159] op_sel_hi:[0,1]
	v_pk_mul_f32 v[134:135], v[0:1], v[134:135] op_sel_hi:[0,1]
	v_pk_mul_f32 v[134:135], v[134:135], v[160:161]
	v_pk_mul_f32 v[158:159], v[158:159], v[164:165]
	v_pk_mul_f32 v[118:119], v[118:119], v[134:135]
	v_pk_mul_f32 v[120:121], v[120:121], v[158:159]
	v_lshlrev_b32_e32 v134, 16, v162
	v_and_b32_e32 v135, 0xffff0000, v162
	v_lshlrev_b32_e32 v158, 16, v163
	v_and_b32_e32 v159, 0xffff0000, v163
	v_lshlrev_b32_e32 v160, 16, v168
	v_and_b32_e32 v161, 0xffff0000, v168
	v_lshlrev_b32_e32 v162, 16, v169
	v_and_b32_e32 v163, 0xffff0000, v169
	v_max_f32_e32 v160, v160, v160
	v_max_f32_e32 v161, v161, v161
	v_max_f32_e32 v162, v162, v162
	v_max_f32_e32 v163, v163, v163
	v_max_f32_e32 v160, 0xda24260, v160
	v_max_f32_e32 v161, 0xda24260, v161
	v_max_f32_e32 v162, 0xda24260, v162
	v_max_f32_e32 v163, 0xda24260, v163
	v_rcp_f32_e32 v160, v160
	v_rcp_f32_e32 v161, v161
	v_rcp_f32_e32 v162, v162
	v_rcp_f32_e32 v163, v163
	v_pk_mul_f32 v[158:159], v[0:1], v[158:159] op_sel_hi:[0,1]
	v_pk_mul_f32 v[134:135], v[0:1], v[134:135] op_sel_hi:[0,1]
	v_pk_mul_f32 v[134:135], v[134:135], v[160:161]
	v_pk_mul_f32 v[158:159], v[158:159], v[162:163]
	s_and_b64 vcc, exec, s[6:7]
	v_pk_mul_f32 v[128:129], v[128:129], v[158:159]
	v_pk_mul_f32 v[126:127], v[126:127], v[134:135]
	s_cbranch_vccnz .LBB0_835
	v_add_u32_e32 v0, s90, v141
	v_lshlrev_b64 v[134:135], 11, v[0:1]
	v_lshl_add_u64 v[134:135], s[54:55], 0, v[134:135]
	v_cvt_pk_bf16_f32 v158, v106, v107
	v_cvt_pk_bf16_f32 v159, v108, v109
	v_cvt_pk_bf16_f32 v160, v114, v115
	v_cvt_pk_bf16_f32 v161, v116, v117
	s_nop 0
	v_permlane16_swap_b32_e32 v158, v160
	v_permlane16_swap_b32_e32 v159, v161
	v_lshl_add_u64 v[134:135], v[184:185], 1, v[134:135]
	global_store_dwordx4 v[134:135], v[158:161], off sc1
	s_nop 1
	v_cvt_pk_bf16_f32 v158, v118, v119
	v_cvt_pk_bf16_f32 v159, v120, v121
	v_cvt_pk_bf16_f32 v160, v126, v127
	v_cvt_pk_bf16_f32 v161, v128, v129
	s_nop 0
	v_permlane16_swap_b32_e32 v158, v160
	v_permlane16_swap_b32_e32 v159, v161
	global_store_dwordx4 v[134:135], v[158:161], off offset:256 sc1

; __device__ __forceinline__ u32x2 pack4(f32x4 v) { u32x2 r; r.x = cvt_pk(v[0], v[1]); r.y = cvt_pk(v[2], v[3]); return r; }
; __device__ __forceinline__ f32x4 unpack4(u32x2 w) { return (f32x4){bflo(w.x), bfhi(w.x), bflo(w.y), bfhi(w.y)}; }
; __device__ __forceinline__ void phaseD(const Params& p, const int wv, const int rep) {
;     ...
;       for (int g = 0; g < 8; ++g) {
;         __builtin_amdgcn_sched_barrier(0);
;         const int ai = g >> 2, m = g & 3, rrow = ai * 128 + wr * 64 + m * 16 + fr, row_ = brow + rrow;
;         const float rs0 = rs_l[rrow * 2], rs1 = rs_l[rrow * 2 + 1];
;         const float rsc = (br == 0) ? __builtin_amdgcn_rcpf(rs0) : (br == 1) ? rs0 * __builtin_amdgcn_rcpf(rs1) : (br == 2) ? rs1 : 1.f;
; #pragma unroll
;         for (int bj = 0; bj < 2; ++bj) {
;           u32x2 gnp[2], gdp[2];
;           unpair16(gw[g & 3][bj], gnp[0], gnp[1]); unpair16(dw[g & 3][bj], gdp[0], gdp[1]);
; #pragma unroll
;           for (int n = 0; n < 2; ++n) {
;             const f32x4 gn = unpack4(gnp[n]), gd = unpack4(gdp[n]);
;             f32x4 sc;
; #pragma unroll
;             for (int e = 0; e < 4; ++e) sc[e] = gn[e] * rsc * __builtin_amdgcn_rcpf(fmaxf(gd[e], 1e-30f));
;             acc[ai][bj][m][n] = acc[ai][bj][m][n] * sc;
;           }
;         }
;         if (br == 3) {
;           u16* mrow = MERGED + (size_t)row_ * 1024 + bcol + wc * 32;
;           store_pair16(mrow, pack4(acc[ai][0][m][0]), pack4(acc[ai][0][m][1]), fq);
;           store_pair16(mrow + 128, pack4(acc[ai][1][m][0]), pack4(acc[ai][1][m][1]), fq);
;         }
.LBB0_858:
	v_permlane16_swap_b32_e32 v193, v133
	v_permlane16_swap_b32_e32 v190, v138
	v_lshlrev_b32_e32 v168, 16, v193
	v_and_b32_e32 v169, 0xffff0000, v193
	v_lshlrev_b32_e32 v193, 16, v190
	v_and_b32_e32 v190, 0xffff0000, v190
	v_permlane16_swap_b32_e32 v194, v132
	v_permlane16_swap_b32_e32 v189, v139
	v_max_f32_e32 v190, v190, v190
	s_waitcnt lgkmcnt(0)
	v_lshlrev_b32_e32 v134, 16, v194
	v_and_b32_e32 v135, 0xffff0000, v194
	v_lshlrev_b32_e32 v194, 16, v189
	v_and_b32_e32 v189, 0xffff0000, v189
	v_max_f32_e32 v190, 0xda24260, v190
	v_rcp_f32_e32 v209, v190
	v_max_f32_e32 v190, v194, v194
	v_max_f32_e32 v189, v189, v189
	v_max_f32_e32 v190, 0xda24260, v190
	v_max_f32_e32 v189, 0xda24260, v189
	v_rcp_f32_e32 v210, v190
	v_rcp_f32_e32 v211, v189
	v_max_f32_e32 v193, v193, v193
	v_pk_mul_f32 v[168:169], v[0:1], v[168:169] op_sel_hi:[0,1]
	v_max_f32_e32 v193, 0xda24260, v193
	v_pk_mul_f32 v[168:169], v[168:169], v[210:211]
	v_rcp_f32_e32 v208, v193
	v_pk_mul_f32 v[124:125], v[124:125], v[168:169]
	v_lshlrev_b32_e32 v168, 16, v138
	v_and_b32_e32 v169, 0xffff0000, v138
	v_lshlrev_b32_e32 v189, 16, v139
	v_and_b32_e32 v190, 0xffff0000, v139
	v_max_f32_e32 v138, v168, v168
	v_max_f32_e32 v139, v169, v169
	v_max_f32_e32 v168, v189, v189
	v_max_f32_e32 v169, v190, v190
	v_max_f32_e32 v138, 0xda24260, v138
	v_max_f32_e32 v139, 0xda24260, v139
	v_max_f32_e32 v168, 0xda24260, v168
	v_max_f32_e32 v169, 0xda24260, v169
	v_pk_mul_f32 v[134:135], v[0:1], v[134:135] op_sel_hi:[0,1]
	v_rcp_f32_e32 v138, v138
	v_rcp_f32_e32 v139, v139
	v_rcp_f32_e32 v168, v168
	v_rcp_f32_e32 v169, v169
	v_pk_mul_f32 v[134:135], v[134:135], v[208:209]
	v_permlane16_swap_b32_e32 v192, v142
	v_pk_mul_f32 v[122:123], v[122:123], v[134:135]
	v_lshlrev_b32_e32 v134, 16, v132
	v_and_b32_e32 v135, 0xffff0000, v132
	v_lshlrev_b32_e32 v132, 16, v133
	v_and_b32_e32 v133, 0xffff0000, v133
	v_pk_mul_f32 v[132:133], v[0:1], v[132:133] op_sel_hi:[0,1]
	v_pk_mul_f32 v[134:135], v[0:1], v[134:135] op_sel_hi:[0,1]
	v_permlane16_swap_b32_e32 v191, v143
	v_pk_mul_f32 v[134:135], v[134:135], v[138:139]
	v_pk_mul_f32 v[132:133], v[132:133], v[168:169]
	v_lshlrev_b32_e32 v138, 16, v192
	v_and_b32_e32 v139, 0xffff0000, v192
	v_lshlrev_b32_e32 v168, 16, v191
	v_and_b32_e32 v169, 0xffff0000, v191
	v_max_f32_e32 v138, v138, v138
	v_max_f32_e32 v139, v139, v139
	v_max_f32_e32 v168, v168, v168
	v_max_f32_e32 v169, v169, v169
	v_max_f32_e32 v138, 0xda24260, v138
	v_max_f32_e32 v139, 0xda24260, v139
	v_max_f32_e32 v168, 0xda24260, v168
	v_max_f32_e32 v169, 0xda24260, v169
	v_rcp_f32_e32 v138, v138
	v_rcp_f32_e32 v139, v139
	v_rcp_f32_e32 v168, v168
	v_rcp_f32_e32 v169, v169
	v_permlane16_swap_b32_e32 v196, v136
	v_permlane16_swap_b32_e32 v195, v137
	v_pk_mul_f32 v[112:113], v[112:113], v[132:133]
	v_pk_mul_f32 v[110:111], v[110:111], v[134:135]
	v_lshlrev_b32_e32 v132, 16, v196
	v_and_b32_e32 v133, 0xffff0000, v196
	v_lshlrev_b32_e32 v134, 16, v195
	v_and_b32_e32 v135, 0xffff0000, v195
	v_pk_mul_f32 v[134:135], v[0:1], v[134:135] op_sel_hi:[0,1]
	v_pk_mul_f32 v[132:133], v[0:1], v[132:133] op_sel_hi:[0,1]
	v_pk_mul_f32 v[132:133], v[132:133], v[138:139]
	v_pk_mul_f32 v[134:135], v[134:135], v[168:169]
	v_pk_mul_f32 v[102:103], v[102:103], v[132:133]
	v_pk_mul_f32 v[104:105], v[104:105], v[134:135]
	v_lshlrev_b32_e32 v132, 16, v136
	v_and_b32_e32 v133, 0xffff0000, v136
	v_lshlrev_b32_e32 v134, 16, v137
	v_and_b32_e32 v135, 0xffff0000, v137
	v_lshlrev_b32_e32 v136, 16, v142
	v_and_b32_e32 v137, 0xffff0000, v142
	v_lshlrev_b32_e32 v138, 16, v143
	v_and_b32_e32 v139, 0xffff0000, v143
	v_max_f32_e32 v136, v136, v136
	v_max_f32_e32 v137, v137, v137
	v_max_f32_e32 v138, v138, v138
	v_max_f32_e32 v139, v139, v139
	v_max_f32_e32 v136, 0xda24260, v136
	v_max_f32_e32 v137, 0xda24260, v137
	v_max_f32_e32 v138, 0xda24260, v138
	v_max_f32_e32 v139, 0xda24260, v139
	v_rcp_f32_e32 v136, v136
	v_rcp_f32_e32 v137, v137
	v_rcp_f32_e32 v138, v138
	v_rcp_f32_e32 v139, v139
	v_pk_mul_f32 v[134:135], v[0:1], v[134:135] op_sel_hi:[0,1]
	v_pk_mul_f32 v[132:133], v[0:1], v[132:133] op_sel_hi:[0,1]
	v_pk_mul_f32 v[132:133], v[132:133], v[136:137]
	v_pk_mul_f32 v[134:135], v[134:135], v[138:139]
	s_and_b64 vcc, exec, s[6:7]
	v_pk_mul_f32 v[100:101], v[100:101], v[134:135]
	v_pk_mul_f32 v[98:99], v[98:99], v[132:133]
	s_cbranch_vccnz .LBB0_860
	v_add_u32_e32 v0, s90, v141
	v_lshlrev_b64 v[132:133], 11, v[0:1]
	v_lshl_add_u64 v[136:137], s[54:55], 0, v[132:133]
	v_cvt_pk_bf16_f32 v132, v122, v123
	v_cvt_pk_bf16_f32 v133, v124, v125
	v_cvt_pk_bf16_f32 v134, v110, v111
	v_cvt_pk_bf16_f32 v135, v112, v113
	s_nop 0
	v_permlane16_swap_b32_e32 v132, v134
	v_permlane16_swap_b32_e32 v133, v135
	v_lshl_add_u64 v[136:137], v[184:185], 1, v[136:137]
	global_store_dwordx4 v[136:137], v[132:135], off sc1
	s_nop 1
	v_cvt_pk_bf16_f32 v132, v102, v103
	v_cvt_pk_bf16_f32 v133, v104, v105
	v_cvt_pk_bf16_f32 v134, v98, v99
	v_cvt_pk_bf16_f32 v135, v100, v101
	s_nop 0
	v_permlane16_swap_b32_e32 v132, v134
	v_permlane16_swap_b32_e32 v133, v135
	global_store_dwordx4 v[136:137], v[132:135], off offset:256 sc1

; __device__ __forceinline__ u32x2 pack4(f32x4 v) { u32x2 r; r.x = cvt_pk(v[0], v[1]); r.y = cvt_pk(v[2], v[3]); return r; }
; __device__ __forceinline__ f32x4 unpack4(u32x2 w) { return (f32x4){bflo(w.x), bfhi(w.x), bflo(w.y), bfhi(w.y)}; }
; __device__ __forceinline__ void phaseD(const Params& p, const int wv, const int rep) {
;     ...
;       for (int g = 0; g < 8; ++g) {
;         __builtin_amdgcn_sched_barrier(0);
;         const int ai = g >> 2, m = g & 3, rrow = ai * 128 + wr * 64 + m * 16 + fr, row_ = brow + rrow;
;         const float rs0 = rs_l[rrow * 2], rs1 = rs_l[rrow * 2 + 1];
;         const float rsc = (br == 0) ? __builtin_amdgcn_rcpf(rs0) : (br == 1) ? rs0 * __builtin_amdgcn_rcpf(rs1) : (br == 2) ? rs1 : 1.f;
; #pragma unroll
;         for (int bj = 0; bj < 2; ++bj) {
;           u32x2 gnp[2], gdp[2];
;           unpair16(gw[g & 3][bj], gnp[0], gnp[1]); unpair16(dw[g & 3][bj], gdp[0], gdp[1]);
; #pragma unroll
;           for (int n = 0; n < 2; ++n) {
;             const f32x4 gn = unpack4(gnp[n]), gd = unpack4(gdp[n]);
;             f32x4 sc;
; #pragma unroll
;             for (int e = 0; e < 4; ++e) sc[e] = gn[e] * rsc * __builtin_amdgcn_rcpf(fmaxf(gd[e], 1e-30f));
;             acc[ai][bj][m][n] = acc[ai][bj][m][n] * sc;
;           }
;         }
;         if (br == 3) {
;           u16* mrow = MERGED + (size_t)row_ * 1024 + bcol + wc * 32;
;           store_pair16(mrow, pack4(acc[ai][0][m][0]), pack4(acc[ai][0][m][1]), fq);
;           store_pair16(mrow + 128, pack4(acc[ai][1][m][0]), pack4(acc[ai][1][m][1]), fq);
;         }
.LBB0_883:
	v_permlane16_swap_b32_e32 v198, v152
	v_lshlrev_b32_e32 v141, 16, v198
	v_max_f32_e32 v141, v141, v141
	v_and_b32_e32 v188, 0xffff0000, v198
	v_max_f32_e32 v141, 0xda24260, v141
	v_permlane16_swap_b32_e32 v197, v153
	v_rcp_f32_e32 v196, v141
	v_max_f32_e32 v141, v188, v188
	v_permlane16_swap_b32_e32 v199, v147
	v_lshlrev_b32_e32 v193, 16, v197
	v_max_f32_e32 v141, 0xda24260, v141
	v_lshlrev_b32_e32 v194, 16, v199
	v_and_b32_e32 v195, 0xffff0000, v199
	v_and_b32_e32 v199, 0xffff0000, v197
	v_rcp_f32_e32 v197, v141
	v_max_f32_e32 v141, v193, v193
	v_max_f32_e32 v141, 0xda24260, v141
	v_rcp_f32_e32 v198, v141
	v_max_f32_e32 v141, v199, v199
	v_max_f32_e32 v141, 0xda24260, v141
	v_rcp_f32_e32 v199, v141
	v_lshlrev_b32_e32 v141, 16, v152
	v_max_f32_e32 v141, v141, v141
	v_and_b32_e32 v188, 0xffff0000, v152
	v_max_f32_e32 v141, 0xda24260, v141
	v_pk_mul_f32 v[194:195], v[0:1], v[194:195] op_sel_hi:[0,1]
	v_rcp_f32_e32 v152, v141
	v_max_f32_e32 v141, v188, v188
	v_pk_mul_f32 v[194:195], v[194:195], v[198:199]
	v_lshlrev_b32_e32 v193, 16, v153
	v_max_f32_e32 v141, 0xda24260, v141
	v_pk_mul_f32 v[96:97], v[96:97], v[194:195]
	v_and_b32_e32 v195, 0xffff0000, v153
	v_rcp_f32_e32 v153, v141
	v_max_f32_e32 v141, v193, v193
	v_max_f32_e32 v141, 0xda24260, v141
	v_permlane16_swap_b32_e32 v200, v146
	v_rcp_f32_e32 v194, v141
	v_max_f32_e32 v141, v195, v195
	s_waitcnt lgkmcnt(0)
	v_lshlrev_b32_e32 v130, 16, v200
	v_and_b32_e32 v131, 0xffff0000, v200
	v_max_f32_e32 v141, 0xda24260, v141
	v_pk_mul_f32 v[130:131], v[0:1], v[130:131] op_sel_hi:[0,1]
	v_rcp_f32_e32 v195, v141
	v_pk_mul_f32 v[130:131], v[130:131], v[196:197]
	v_permlane16_swap_b32_e32 v145, v156
	v_pk_mul_f32 v[94:95], v[94:95], v[130:131]
	v_lshlrev_b32_e32 v130, 16, v146
	v_and_b32_e32 v131, 0xffff0000, v146
	v_lshlrev_b32_e32 v146, 16, v147
	v_and_b32_e32 v147, 0xffff0000, v147
	v_lshlrev_b32_e32 v141, 16, v145
	v_pk_mul_f32 v[146:147], v[0:1], v[146:147] op_sel_hi:[0,1]
	v_pk_mul_f32 v[130:131], v[0:1], v[130:131] op_sel_hi:[0,1]
	v_max_f32_e32 v141, v141, v141
	v_pk_mul_f32 v[130:131], v[130:131], v[152:153]
	v_pk_mul_f32 v[146:147], v[146:147], v[194:195]
	s_waitcnt vmcnt(0)
	v_permlane16_swap_b32_e32 v148, v150
	v_permlane16_swap_b32_e32 v149, v151
	v_permlane16_swap_b32_e32 v144, v157
	v_and_b32_e32 v145, 0xffff0000, v145
	v_max_f32_e32 v141, 0xda24260, v141
	v_pk_mul_f32 v[88:89], v[88:89], v[146:147]
	v_pk_mul_f32 v[86:87], v[86:87], v[130:131]
	v_lshlrev_b32_e32 v130, 16, v148
	v_and_b32_e32 v131, 0xffff0000, v148
	v_lshlrev_b32_e32 v146, 16, v149
	v_and_b32_e32 v147, 0xffff0000, v149
	v_lshlrev_b32_e32 v148, 16, v144
	v_and_b32_e32 v149, 0xffff0000, v144
	v_rcp_f32_e32 v144, v141
	v_max_f32_e32 v141, v145, v145
	v_max_f32_e32 v141, 0xda24260, v141
	v_rcp_f32_e32 v145, v141
	v_max_f32_e32 v141, v148, v148
	v_max_f32_e32 v141, 0xda24260, v141
	v_rcp_f32_e32 v148, v141
	v_max_f32_e32 v141, v149, v149
	v_max_f32_e32 v141, 0xda24260, v141
	v_rcp_f32_e32 v149, v141
	v_lshlrev_b32_e32 v141, 16, v156
	v_pk_mul_f32 v[146:147], v[0:1], v[146:147] op_sel_hi:[0,1]
	v_pk_mul_f32 v[130:131], v[0:1], v[130:131] op_sel_hi:[0,1]
	v_max_f32_e32 v141, v141, v141
	v_pk_mul_f32 v[130:131], v[130:131], v[144:145]
	v_pk_mul_f32 v[144:145], v[146:147], v[148:149]
	v_and_b32_e32 v147, 0xffff0000, v156
	v_max_f32_e32 v141, 0xda24260, v141
	v_rcp_f32_e32 v146, v141
	v_max_f32_e32 v141, v147, v147
	v_lshlrev_b32_e32 v148, 16, v157
	v_max_f32_e32 v141, 0xda24260, v141
	v_rcp_f32_e32 v147, v141
	v_max_f32_e32 v141, v148, v148
	v_and_b32_e32 v149, 0xffff0000, v157
	v_max_f32_e32 v141, 0xda24260, v141
	v_rcp_f32_e32 v148, v141
	v_max_f32_e32 v141, v149, v149
	v_max_f32_e32 v141, 0xda24260, v141
	v_rcp_f32_e32 v149, v141
	v_pk_mul_f32 v[76:77], v[76:77], v[144:145]
	v_pk_mul_f32 v[74:75], v[74:75], v[130:131]
	v_lshlrev_b32_e32 v130, 16, v150
	v_and_b32_e32 v131, 0xffff0000, v150
	v_lshlrev_b32_e32 v144, 16, v151
	v_and_b32_e32 v145, 0xffff0000, v151
	v_pk_mul_f32 v[144:145], v[0:1], v[144:145] op_sel_hi:[0,1]
	v_pk_mul_f32 v[130:131], v[0:1], v[130:131] op_sel_hi:[0,1]
	v_pk_mul_f32 v[130:131], v[130:131], v[146:147]
	v_pk_mul_f32 v[144:145], v[144:145], v[148:149]
	s_and_b64 vcc, exec, s[6:7]
	v_pk_mul_f32 v[68:69], v[68:69], v[144:145]
	v_pk_mul_f32 v[66:67], v[66:67], v[130:131]
	s_cbranch_vccnz .LBB0_885
	v_add_u32_e32 v0, s90, v140
	v_lshlrev_b64 v[130:131], 11, v[0:1]
	v_lshl_add_u64 v[130:131], s[54:55], 0, v[130:131]
	v_cvt_pk_bf16_f32 v144, v94, v95
	v_cvt_pk_bf16_f32 v145, v96, v97
	v_cvt_pk_bf16_f32 v146, v86, v87
	v_cvt_pk_bf16_f32 v147, v88, v89
	s_nop 0
	v_permlane16_swap_b32_e32 v144, v146
	v_permlane16_swap_b32_e32 v145, v147
	v_lshl_add_u64 v[130:131], v[184:185], 1, v[130:131]
	global_store_dwordx4 v[130:131], v[144:147], off sc1
	s_nop 1
	v_cvt_pk_bf16_f32 v144, v74, v75
	v_cvt_pk_bf16_f32 v145, v76, v77
	v_cvt_pk_bf16_f32 v146, v66, v67
	v_cvt_pk_bf16_f32 v147, v68, v69
	s_nop 0
	v_permlane16_swap_b32_e32 v144, v146
	v_permlane16_swap_b32_e32 v145, v147
	global_store_dwordx4 v[130:131], v[144:147], off offset:256 sc1

; __device__ __forceinline__ u32x2 pack4(f32x4 v) { u32x2 r; r.x = cvt_pk(v[0], v[1]); r.y = cvt_pk(v[2], v[3]); return r; }
; __device__ __forceinline__ f32x4 unpack4(u32x2 w) { return (f32x4){bflo(w.x), bfhi(w.x), bflo(w.y), bfhi(w.y)}; }
; __device__ __forceinline__ void phaseD(const Params& p, const int wv, const int rep) {
;     ...
;       for (int g = 0; g < 8; ++g) {
;         __builtin_amdgcn_sched_barrier(0);
;         const int ai = g >> 2, m = g & 3, rrow = ai * 128 + wr * 64 + m * 16 + fr, row_ = brow + rrow;
;         const float rs0 = rs_l[rrow * 2], rs1 = rs_l[rrow * 2 + 1];
;         const float rsc = (br == 0) ? __builtin_amdgcn_rcpf(rs0) : (br == 1) ? rs0 * __builtin_amdgcn_rcpf(rs1) : (br == 2) ? rs1 : 1.f;
; #pragma unroll
;         for (int bj = 0; bj < 2; ++bj) {
;           u32x2 gnp[2], gdp[2];
;           unpair16(gw[g & 3][bj], gnp[0], gnp[1]); unpair16(dw[g & 3][bj], gdp[0], gdp[1]);
; #pragma unroll
;           for (int n = 0; n < 2; ++n) {
;             const f32x4 gn = unpack4(gnp[n]), gd = unpack4(gdp[n]);
;             f32x4 sc;
; #pragma unroll
;             for (int e = 0; e < 4; ++e) sc[e] = gn[e] * rsc * __builtin_amdgcn_rcpf(fmaxf(gd[e], 1e-30f));
;             acc[ai][bj][m][n] = acc[ai][bj][m][n] * sc;
;           }
;         }
;         if (br == 3) {
;           u16* mrow = MERGED + (size_t)row_ * 1024 + bcol + wc * 32;
;           store_pair16(mrow, pack4(acc[ai][0][m][0]), pack4(acc[ai][0][m][1]), fq);
;           store_pair16(mrow + 128, pack4(acc[ai][1][m][0]), pack4(acc[ai][1][m][1]), fq);
;         }
.LBB0_893:
	v_permlane16_swap_b32_e32 v155, v178
	v_permlane16_swap_b32_e32 v154, v179
	v_lshlrev_b32_e32 v146, 16, v155
	v_and_b32_e32 v147, 0xffff0000, v155
	v_lshlrev_b32_e32 v148, 16, v154
	v_and_b32_e32 v149, 0xffff0000, v154
	v_max_f32_e32 v146, v146, v146
	v_max_f32_e32 v147, v147, v147
	v_max_f32_e32 v148, v148, v148
	v_max_f32_e32 v149, v149, v149
	v_max_f32_e32 v146, 0xda24260, v146
	v_max_f32_e32 v147, 0xda24260, v147
	v_max_f32_e32 v148, 0xda24260, v148
	v_max_f32_e32 v149, 0xda24260, v149
	v_rcp_f32_e32 v146, v146
	v_rcp_f32_e32 v147, v147
	v_rcp_f32_e32 v148, v148
	v_rcp_f32_e32 v149, v149
	v_permlane16_swap_b32_e32 v206, v172
	v_permlane16_swap_b32_e32 v205, v173
	s_waitcnt lgkmcnt(0)
	v_lshlrev_b32_e32 v130, 16, v206
	v_and_b32_e32 v131, 0xffff0000, v206
	v_lshlrev_b32_e32 v144, 16, v205
	v_and_b32_e32 v145, 0xffff0000, v205
	v_pk_mul_f32 v[144:145], v[0:1], v[144:145] op_sel_hi:[0,1]
	v_pk_mul_f32 v[130:131], v[0:1], v[130:131] op_sel_hi:[0,1]
	v_pk_mul_f32 v[130:131], v[130:131], v[146:147]
	v_pk_mul_f32 v[144:145], v[144:145], v[148:149]
	v_lshlrev_b32_e32 v146, 16, v178
	v_and_b32_e32 v147, 0xffff0000, v178
	v_lshlrev_b32_e32 v148, 16, v179
	v_and_b32_e32 v149, 0xffff0000, v179
	v_max_f32_e32 v146, v146, v146
	v_max_f32_e32 v147, v147, v147
	v_max_f32_e32 v148, v148, v148
	v_max_f32_e32 v149, v149, v149
	v_max_f32_e32 v146, 0xda24260, v146
	v_max_f32_e32 v147, 0xda24260, v147
	v_max_f32_e32 v148, 0xda24260, v148
	v_max_f32_e32 v149, 0xda24260, v149
	v_rcp_f32_e32 v146, v146
	v_rcp_f32_e32 v147, v147
	v_rcp_f32_e32 v148, v148
	v_rcp_f32_e32 v149, v149
	v_pk_mul_f32 v[64:65], v[64:65], v[144:145]
	v_pk_mul_f32 v[62:63], v[62:63], v[130:131]
	v_lshlrev_b32_e32 v130, 16, v172
	v_and_b32_e32 v131, 0xffff0000, v172
	v_lshlrev_b32_e32 v144, 16, v173
	v_and_b32_e32 v145, 0xffff0000, v173
	v_pk_mul_f32 v[144:145], v[0:1], v[144:145] op_sel_hi:[0,1]
	v_pk_mul_f32 v[130:131], v[0:1], v[130:131] op_sel_hi:[0,1]
	v_permlane16_swap_b32_e32 v180, v182
	v_permlane16_swap_b32_e32 v181, v183
	v_pk_mul_f32 v[130:131], v[130:131], v[146:147]
	v_pk_mul_f32 v[144:145], v[144:145], v[148:149]
	v_lshlrev_b32_e32 v146, 16, v180
	v_and_b32_e32 v147, 0xffff0000, v180
	v_lshlrev_b32_e32 v148, 16, v181
	v_and_b32_e32 v149, 0xffff0000, v181
	v_max_f32_e32 v146, v146, v146
	v_max_f32_e32 v147, v147, v147
	v_max_f32_e32 v148, v148, v148
	v_max_f32_e32 v149, v149, v149
	v_max_f32_e32 v146, 0xda24260, v146
	v_max_f32_e32 v147, 0xda24260, v147
	v_max_f32_e32 v148, 0xda24260, v148
	v_max_f32_e32 v149, 0xda24260, v149
	v_rcp_f32_e32 v146, v146
	v_rcp_f32_e32 v147, v147
	v_rcp_f32_e32 v148, v148
	v_rcp_f32_e32 v149, v149
	v_permlane16_swap_b32_e32 v174, v176
	v_permlane16_swap_b32_e32 v175, v177
	v_pk_mul_f32 v[60:61], v[60:61], v[144:145]
	v_pk_mul_f32 v[58:59], v[58:59], v[130:131]
	v_lshlrev_b32_e32 v130, 16, v174
	v_and_b32_e32 v131, 0xffff0000, v174
	v_lshlrev_b32_e32 v144, 16, v175
	v_and_b32_e32 v145, 0xffff0000, v175
	v_pk_mul_f32 v[144:145], v[0:1], v[144:145] op_sel_hi:[0,1]
	v_pk_mul_f32 v[130:131], v[0:1], v[130:131] op_sel_hi:[0,1]
	v_pk_mul_f32 v[130:131], v[130:131], v[146:147]
	v_pk_mul_f32 v[144:145], v[144:145], v[148:149]
	v_lshlrev_b32_e32 v146, 16, v182
	v_and_b32_e32 v147, 0xffff0000, v182
	v_lshlrev_b32_e32 v148, 16, v183
	v_and_b32_e32 v149, 0xffff0000, v183
	v_max_f32_e32 v146, v146, v146
	v_max_f32_e32 v147, v147, v147
	v_max_f32_e32 v148, v148, v148
	v_max_f32_e32 v149, v149, v149
	v_max_f32_e32 v146, 0xda24260, v146
	v_max_f32_e32 v147, 0xda24260, v147
	v_max_f32_e32 v148, 0xda24260, v148
	v_max_f32_e32 v149, 0xda24260, v149
	v_rcp_f32_e32 v146, v146
	v_rcp_f32_e32 v147, v147
	v_rcp_f32_e32 v148, v148
	v_rcp_f32_e32 v149, v149
	v_pk_mul_f32 v[56:57], v[56:57], v[144:145]
	v_pk_mul_f32 v[54:55], v[54:55], v[130:131]
	v_lshlrev_b32_e32 v130, 16, v176
	v_and_b32_e32 v131, 0xffff0000, v176
	v_lshlrev_b32_e32 v144, 16, v177
	v_and_b32_e32 v145, 0xffff0000, v177
	v_pk_mul_f32 v[144:145], v[0:1], v[144:145] op_sel_hi:[0,1]
	v_pk_mul_f32 v[130:131], v[0:1], v[130:131] op_sel_hi:[0,1]
	v_pk_mul_f32 v[130:131], v[130:131], v[146:147]
	v_pk_mul_f32 v[144:145], v[144:145], v[148:149]
	s_and_b64 vcc, exec, s[6:7]
	v_pk_mul_f32 v[52:53], v[52:53], v[144:145]
	v_pk_mul_f32 v[50:51], v[50:51], v[130:131]
	s_cbranch_vccnz .LBB0_895
	v_add_u32_e32 v0, s90, v141
	v_lshlrev_b64 v[130:131], 11, v[0:1]
	v_lshl_add_u64 v[130:131], s[54:55], 0, v[130:131]
	v_cvt_pk_bf16_f32 v144, v62, v63
	v_cvt_pk_bf16_f32 v145, v64, v65
	v_cvt_pk_bf16_f32 v146, v58, v59
	v_cvt_pk_bf16_f32 v147, v60, v61
	s_nop 0
	v_permlane16_swap_b32_e32 v144, v146
	v_permlane16_swap_b32_e32 v145, v147
	v_lshl_add_u64 v[130:131], v[184:185], 1, v[130:131]
	global_store_dwordx4 v[130:131], v[144:147], off sc1
	s_nop 1
	v_cvt_pk_bf16_f32 v144, v54, v55
	v_cvt_pk_bf16_f32 v145, v56, v57
	v_cvt_pk_bf16_f32 v146, v50, v51
	v_cvt_pk_bf16_f32 v147, v52, v53
	s_nop 0
	v_permlane16_swap_b32_e32 v144, v146
	v_permlane16_swap_b32_e32 v145, v147
	global_store_dwordx4 v[130:131], v[144:147], off offset:256 sc1

; __device__ __forceinline__ u32x2 pack4(f32x4 v) { u32x2 r; r.x = cvt_pk(v[0], v[1]); r.y = cvt_pk(v[2], v[3]); return r; }
; __device__ __forceinline__ f32x4 unpack4(u32x2 w) { return (f32x4){bflo(w.x), bfhi(w.x), bflo(w.y), bfhi(w.y)}; }
; __device__ __forceinline__ void phaseD(const Params& p, const int wv, const int rep) {
;     ...
;       for (int g = 0; g < 8; ++g) {
;         __builtin_amdgcn_sched_barrier(0);
;         const int ai = g >> 2, m = g & 3, rrow = ai * 128 + wr * 64 + m * 16 + fr, row_ = brow + rrow;
;         const float rs0 = rs_l[rrow * 2], rs1 = rs_l[rrow * 2 + 1];
;         const float rsc = (br == 0) ? __builtin_amdgcn_rcpf(rs0) : (br == 1) ? rs0 * __builtin_amdgcn_rcpf(rs1) : (br == 2) ? rs1 : 1.f;
; #pragma unroll
;         for (int bj = 0; bj < 2; ++bj) {
;           u32x2 gnp[2], gdp[2];
;           unpair16(gw[g & 3][bj], gnp[0], gnp[1]); unpair16(dw[g & 3][bj], gdp[0], gdp[1]);
; #pragma unroll
;           for (int n = 0; n < 2; ++n) {
;             const f32x4 gn = unpack4(gnp[n]), gd = unpack4(gdp[n]);
;             f32x4 sc;
; #pragma unroll
;             for (int e = 0; e < 4; ++e) sc[e] = gn[e] * rsc * __builtin_amdgcn_rcpf(fmaxf(gd[e], 1e-30f));
;             acc[ai][bj][m][n] = acc[ai][bj][m][n] * sc;
;           }
;         }
;         if (br == 3) {
;           u16* mrow = MERGED + (size_t)row_ * 1024 + bcol + wc * 32;
;           store_pair16(mrow, pack4(acc[ai][0][m][0]), pack4(acc[ai][0][m][1]), fq);
;           store_pair16(mrow + 128, pack4(acc[ai][1][m][0]), pack4(acc[ai][1][m][1]), fq);
;         }
.LBB0_903:
	v_permlane16_swap_b32_e32 v202, v166
	v_permlane16_swap_b32_e32 v201, v167
	v_lshlrev_b32_e32 v146, 16, v202
	v_and_b32_e32 v147, 0xffff0000, v202
	v_lshlrev_b32_e32 v148, 16, v201
	v_and_b32_e32 v149, 0xffff0000, v201
	v_max_f32_e32 v146, v146, v146
	v_max_f32_e32 v147, v147, v147
	v_max_f32_e32 v148, v148, v148
	v_max_f32_e32 v149, v149, v149
	v_max_f32_e32 v146, 0xda24260, v146
	v_max_f32_e32 v147, 0xda24260, v147
	v_max_f32_e32 v148, 0xda24260, v148
	v_max_f32_e32 v149, 0xda24260, v149
	v_rcp_f32_e32 v146, v146
	v_rcp_f32_e32 v147, v147
	v_rcp_f32_e32 v148, v148
	v_rcp_f32_e32 v149, v149
	v_permlane16_swap_b32_e32 v204, v160
	v_permlane16_swap_b32_e32 v203, v161
	s_waitcnt lgkmcnt(0)
	v_lshlrev_b32_e32 v130, 16, v204
	v_and_b32_e32 v131, 0xffff0000, v204
	v_lshlrev_b32_e32 v144, 16, v203
	v_and_b32_e32 v145, 0xffff0000, v203
	v_pk_mul_f32 v[144:145], v[0:1], v[144:145] op_sel_hi:[0,1]
	v_pk_mul_f32 v[130:131], v[0:1], v[130:131] op_sel_hi:[0,1]
	v_pk_mul_f32 v[130:131], v[130:131], v[146:147]
	v_pk_mul_f32 v[144:145], v[144:145], v[148:149]
	v_lshlrev_b32_e32 v146, 16, v166
	v_and_b32_e32 v147, 0xffff0000, v166
	v_lshlrev_b32_e32 v148, 16, v167
	v_and_b32_e32 v149, 0xffff0000, v167
	v_max_f32_e32 v146, v146, v146
	v_max_f32_e32 v147, v147, v147
	v_max_f32_e32 v148, v148, v148
	v_max_f32_e32 v149, v149, v149
	v_max_f32_e32 v146, 0xda24260, v146
	v_max_f32_e32 v147, 0xda24260, v147
	v_max_f32_e32 v148, 0xda24260, v148
	v_max_f32_e32 v149, 0xda24260, v149
	v_rcp_f32_e32 v146, v146
	v_rcp_f32_e32 v147, v147
	v_rcp_f32_e32 v148, v148
	v_rcp_f32_e32 v149, v149
	v_pk_mul_f32 v[36:37], v[36:37], v[144:145]
	v_pk_mul_f32 v[34:35], v[34:35], v[130:131]
	v_lshlrev_b32_e32 v130, 16, v160
	v_and_b32_e32 v131, 0xffff0000, v160
	v_lshlrev_b32_e32 v144, 16, v161
	v_and_b32_e32 v145, 0xffff0000, v161
	v_pk_mul_f32 v[144:145], v[0:1], v[144:145] op_sel_hi:[0,1]
	v_pk_mul_f32 v[130:131], v[0:1], v[130:131] op_sel_hi:[0,1]
	v_permlane16_swap_b32_e32 v159, v170
	v_permlane16_swap_b32_e32 v158, v171
	v_pk_mul_f32 v[130:131], v[130:131], v[146:147]
	v_pk_mul_f32 v[144:145], v[144:145], v[148:149]
	v_lshlrev_b32_e32 v146, 16, v159
	v_and_b32_e32 v147, 0xffff0000, v159
	v_lshlrev_b32_e32 v148, 16, v158
	v_and_b32_e32 v149, 0xffff0000, v158
	v_max_f32_e32 v146, v146, v146
	v_max_f32_e32 v147, v147, v147
	v_max_f32_e32 v148, v148, v148
	v_max_f32_e32 v149, v149, v149
	v_max_f32_e32 v146, 0xda24260, v146
	v_max_f32_e32 v147, 0xda24260, v147
	v_max_f32_e32 v148, 0xda24260, v148
	v_max_f32_e32 v149, 0xda24260, v149
	v_rcp_f32_e32 v146, v146
	v_rcp_f32_e32 v147, v147
	v_rcp_f32_e32 v148, v148
	v_rcp_f32_e32 v149, v149
	v_permlane16_swap_b32_e32 v162, v164
	v_permlane16_swap_b32_e32 v163, v165
	v_pk_mul_f32 v[28:29], v[28:29], v[144:145]
	v_pk_mul_f32 v[26:27], v[26:27], v[130:131]
	v_lshlrev_b32_e32 v130, 16, v162
	v_and_b32_e32 v131, 0xffff0000, v162
	v_lshlrev_b32_e32 v144, 16, v163
	v_and_b32_e32 v145, 0xffff0000, v163
	v_pk_mul_f32 v[144:145], v[0:1], v[144:145] op_sel_hi:[0,1]
	v_pk_mul_f32 v[130:131], v[0:1], v[130:131] op_sel_hi:[0,1]
	v_pk_mul_f32 v[130:131], v[130:131], v[146:147]
	v_pk_mul_f32 v[144:145], v[144:145], v[148:149]
	v_lshlrev_b32_e32 v146, 16, v170
	v_and_b32_e32 v147, 0xffff0000, v170
	v_lshlrev_b32_e32 v148, 16, v171
	v_and_b32_e32 v149, 0xffff0000, v171
	v_max_f32_e32 v146, v146, v146
	v_max_f32_e32 v147, v147, v147
	v_max_f32_e32 v148, v148, v148
	v_max_f32_e32 v149, v149, v149
	v_max_f32_e32 v146, 0xda24260, v146
	v_max_f32_e32 v147, 0xda24260, v147
	v_max_f32_e32 v148, 0xda24260, v148
	v_max_f32_e32 v149, 0xda24260, v149
	v_rcp_f32_e32 v146, v146
	v_rcp_f32_e32 v147, v147
	v_rcp_f32_e32 v148, v148
	v_rcp_f32_e32 v149, v149
	v_pk_mul_f32 v[24:25], v[24:25], v[144:145]
	v_pk_mul_f32 v[22:23], v[22:23], v[130:131]
	v_lshlrev_b32_e32 v130, 16, v164
	v_and_b32_e32 v131, 0xffff0000, v164
	v_lshlrev_b32_e32 v144, 16, v165
	v_and_b32_e32 v145, 0xffff0000, v165
	v_pk_mul_f32 v[144:145], v[0:1], v[144:145] op_sel_hi:[0,1]
	v_pk_mul_f32 v[130:131], v[0:1], v[130:131] op_sel_hi:[0,1]
	v_pk_mul_f32 v[130:131], v[130:131], v[146:147]
	v_pk_mul_f32 v[144:145], v[144:145], v[148:149]
	s_and_b64 vcc, exec, s[6:7]
	v_pk_mul_f32 v[20:21], v[20:21], v[144:145]
	v_pk_mul_f32 v[18:19], v[18:19], v[130:131]
	s_cbranch_vccnz .LBB0_905
	v_add_u32_e32 v0, s90, v141
	v_lshlrev_b64 v[130:131], 11, v[0:1]
	v_lshl_add_u64 v[130:131], s[54:55], 0, v[130:131]
	v_cvt_pk_bf16_f32 v144, v34, v35
	v_cvt_pk_bf16_f32 v145, v36, v37
	v_cvt_pk_bf16_f32 v146, v26, v27
	v_cvt_pk_bf16_f32 v147, v28, v29
	s_nop 0
	v_permlane16_swap_b32_e32 v144, v146
	v_permlane16_swap_b32_e32 v145, v147
	v_lshl_add_u64 v[130:131], v[184:185], 1, v[130:131]
	global_store_dwordx4 v[130:131], v[144:147], off sc1
	s_nop 1
	v_cvt_pk_bf16_f32 v144, v22, v23
	v_cvt_pk_bf16_f32 v145, v24, v25
	v_cvt_pk_bf16_f32 v146, v18, v19
	v_cvt_pk_bf16_f32 v147, v20, v21
	s_nop 0
	v_permlane16_swap_b32_e32 v144, v146
	v_permlane16_swap_b32_e32 v145, v147
	global_store_dwordx4 v[130:131], v[144:147], off offset:256 sc1

; __device__ __forceinline__ u32x2 pack4(f32x4 v) { u32x2 r; r.x = cvt_pk(v[0], v[1]); r.y = cvt_pk(v[2], v[3]); return r; }
; __device__ __forceinline__ f32x4 unpack4(u32x2 w) { return (f32x4){bflo(w.x), bfhi(w.x), bflo(w.y), bfhi(w.y)}; }
; __device__ __forceinline__ void phaseD(const Params& p, const int wv, const int rep) {
;     ...
;       for (int g = 0; g < 8; ++g) {
;         __builtin_amdgcn_sched_barrier(0);
;         const int ai = g >> 2, m = g & 3, rrow = ai * 128 + wr * 64 + m * 16 + fr, row_ = brow + rrow;
;         const float rs0 = rs_l[rrow * 2], rs1 = rs_l[rrow * 2 + 1];
;         const float rsc = (br == 0) ? __builtin_amdgcn_rcpf(rs0) : (br == 1) ? rs0 * __builtin_amdgcn_rcpf(rs1) : (br == 2) ? rs1 : 1.f;
; #pragma unroll
;         for (int bj = 0; bj < 2; ++bj) {
;           u32x2 gnp[2], gdp[2];
;           unpair16(gw[g & 3][bj], gnp[0], gnp[1]); unpair16(dw[g & 3][bj], gdp[0], gdp[1]);
; #pragma unroll
;           for (int n = 0; n < 2; ++n) {
;             const f32x4 gn = unpack4(gnp[n]), gd = unpack4(gdp[n]);
;             f32x4 sc;
; #pragma unroll
;             for (int e = 0; e < 4; ++e) sc[e] = gn[e] * rsc * __builtin_amdgcn_rcpf(fmaxf(gd[e], 1e-30f));
;             acc[ai][bj][m][n] = acc[ai][bj][m][n] * sc;
;           }
;         }
;         if (br == 3) {
;           u16* mrow = MERGED + (size_t)row_ * 1024 + bcol + wc * 32;
;           store_pair16(mrow, pack4(acc[ai][0][m][0]), pack4(acc[ai][0][m][1]), fq);
;           store_pair16(mrow + 128, pack4(acc[ai][1][m][0]), pack4(acc[ai][1][m][1]), fq);
;         }
.LBB0_913:
	v_permlane16_swap_b32_e32 v169, v138
	v_lshlrev_b32_e32 v141, 16, v169
	v_max_f32_e32 v141, v141, v141
	v_and_b32_e32 v147, 0xffff0000, v169
	v_max_f32_e32 v141, 0xda24260, v141
	v_permlane16_swap_b32_e32 v168, v139
	v_rcp_f32_e32 v146, v141
	v_max_f32_e32 v141, v147, v147
	v_lshlrev_b32_e32 v148, 16, v168
	v_max_f32_e32 v141, 0xda24260, v141
	v_rcp_f32_e32 v147, v141
	v_max_f32_e32 v141, v148, v148
	v_and_b32_e32 v149, 0xffff0000, v168
	v_max_f32_e32 v141, 0xda24260, v141
	v_rcp_f32_e32 v148, v141
	v_max_f32_e32 v141, v149, v149
	v_max_f32_e32 v141, 0xda24260, v141
	v_rcp_f32_e32 v149, v141
	v_permlane16_swap_b32_e32 v191, v133
	v_lshlrev_b32_e32 v144, 16, v191
	v_and_b32_e32 v145, 0xffff0000, v191
	v_pk_mul_f32 v[144:145], v[0:1], v[144:145] op_sel_hi:[0,1]
	v_permlane16_swap_b32_e32 v192, v132
	v_pk_mul_f32 v[144:145], v[144:145], v[148:149]
	s_waitcnt lgkmcnt(0)
	v_lshlrev_b32_e32 v130, 16, v192
	v_and_b32_e32 v131, 0xffff0000, v192
	v_pk_mul_f32 v[16:17], v[16:17], v[144:145]
	v_lshlrev_b32_e32 v141, 16, v138
	v_lshlrev_b32_e32 v145, 16, v139
	v_pk_mul_f32 v[130:131], v[0:1], v[130:131] op_sel_hi:[0,1]
	v_and_b32_e32 v144, 0xffff0000, v138
	v_max_f32_e32 v138, v141, v141
	v_max_f32_e32 v141, v145, v145
	v_pk_mul_f32 v[130:131], v[130:131], v[146:147]
	v_and_b32_e32 v146, 0xffff0000, v139
	v_max_f32_e32 v141, 0xda24260, v141
	v_max_f32_e32 v139, v144, v144
	v_rcp_f32_e32 v144, v141
	v_max_f32_e32 v141, v146, v146
	v_max_f32_e32 v138, 0xda24260, v138
	v_max_f32_e32 v139, 0xda24260, v139
	v_max_f32_e32 v141, 0xda24260, v141
	v_rcp_f32_e32 v138, v138
	v_rcp_f32_e32 v139, v139
	v_rcp_f32_e32 v145, v141
	v_pk_mul_f32 v[14:15], v[14:15], v[130:131]
	v_lshlrev_b32_e32 v130, 16, v132
	v_and_b32_e32 v131, 0xffff0000, v132
	v_lshlrev_b32_e32 v132, 16, v133
	v_and_b32_e32 v133, 0xffff0000, v133
	v_pk_mul_f32 v[132:133], v[0:1], v[132:133] op_sel_hi:[0,1]
	v_pk_mul_f32 v[130:131], v[0:1], v[130:131] op_sel_hi:[0,1]
	v_pk_mul_f32 v[130:131], v[130:131], v[138:139]
	v_pk_mul_f32 v[132:133], v[132:133], v[144:145]
	v_permlane16_swap_b32_e32 v134, v136
	v_permlane16_swap_b32_e32 v135, v137
	v_permlane16_swap_b32_e32 v190, v142
	v_permlane16_swap_b32_e32 v189, v143
	v_pk_mul_f32 v[12:13], v[12:13], v[132:133]
	v_pk_mul_f32 v[10:11], v[10:11], v[130:131]
	v_lshlrev_b32_e32 v130, 16, v134
	v_and_b32_e32 v131, 0xffff0000, v134
	v_lshlrev_b32_e32 v132, 16, v135
	v_and_b32_e32 v133, 0xffff0000, v135
	v_lshlrev_b32_e32 v134, 16, v190
	v_and_b32_e32 v135, 0xffff0000, v190
	v_lshlrev_b32_e32 v138, 16, v189
	v_and_b32_e32 v139, 0xffff0000, v189
	v_max_f32_e32 v134, v134, v134
	v_max_f32_e32 v135, v135, v135
	v_max_f32_e32 v138, v138, v138
	v_max_f32_e32 v139, v139, v139
	v_max_f32_e32 v134, 0xda24260, v134
	v_max_f32_e32 v135, 0xda24260, v135
	v_max_f32_e32 v138, 0xda24260, v138
	v_max_f32_e32 v139, 0xda24260, v139
	v_rcp_f32_e32 v134, v134
	v_rcp_f32_e32 v135, v135
	v_rcp_f32_e32 v138, v138
	v_rcp_f32_e32 v139, v139
	v_pk_mul_f32 v[132:133], v[0:1], v[132:133] op_sel_hi:[0,1]
	v_pk_mul_f32 v[130:131], v[0:1], v[130:131] op_sel_hi:[0,1]
	v_pk_mul_f32 v[130:131], v[130:131], v[134:135]
	v_pk_mul_f32 v[132:133], v[132:133], v[138:139]
	v_pk_mul_f32 v[6:7], v[6:7], v[130:131]
	v_pk_mul_f32 v[8:9], v[8:9], v[132:133]
	v_lshlrev_b32_e32 v130, 16, v136
	v_and_b32_e32 v131, 0xffff0000, v136
	v_lshlrev_b32_e32 v132, 16, v137
	v_and_b32_e32 v133, 0xffff0000, v137
	v_lshlrev_b32_e32 v134, 16, v142
	v_and_b32_e32 v135, 0xffff0000, v142
	v_lshlrev_b32_e32 v136, 16, v143
	v_and_b32_e32 v137, 0xffff0000, v143
	v_max_f32_e32 v134, v134, v134
	v_max_f32_e32 v135, v135, v135
	v_max_f32_e32 v136, v136, v136
	v_max_f32_e32 v137, v137, v137
	v_max_f32_e32 v134, 0xda24260, v134
	v_max_f32_e32 v135, 0xda24260, v135
	v_max_f32_e32 v136, 0xda24260, v136
	v_max_f32_e32 v137, 0xda24260, v137
	v_rcp_f32_e32 v134, v134
	v_rcp_f32_e32 v135, v135
	v_rcp_f32_e32 v136, v136
	v_rcp_f32_e32 v137, v137
	v_pk_mul_f32 v[132:133], v[0:1], v[132:133] op_sel_hi:[0,1]
	v_pk_mul_f32 v[130:131], v[0:1], v[130:131] op_sel_hi:[0,1]
	v_pk_mul_f32 v[130:131], v[130:131], v[134:135]
	v_pk_mul_f32 v[132:133], v[132:133], v[136:137]
	s_and_b64 vcc, exec, s[6:7]
	v_pk_mul_f32 v[4:5], v[4:5], v[132:133]
	v_pk_mul_f32 v[2:3], v[2:3], v[130:131]
	s_cbranch_vccnz .LBB0_691
	v_add_u32_e32 v0, s90, v140
	v_lshlrev_b64 v[130:131], 11, v[0:1]
	v_lshl_add_u64 v[134:135], s[54:55], 0, v[130:131]
	v_cvt_pk_bf16_f32 v130, v14, v15
	v_cvt_pk_bf16_f32 v131, v16, v17
	v_cvt_pk_bf16_f32 v132, v10, v11
	v_cvt_pk_bf16_f32 v133, v12, v13
	s_nop 0
	v_permlane16_swap_b32_e32 v130, v132
	v_permlane16_swap_b32_e32 v131, v133
	v_lshl_add_u64 v[134:135], v[184:185], 1, v[134:135]
	global_store_dwordx4 v[134:135], v[130:133], off sc1
	s_nop 1
	v_cvt_pk_bf16_f32 v130, v6, v7
	v_cvt_pk_bf16_f32 v131, v8, v9
	v_cvt_pk_bf16_f32 v132, v2, v3
	v_cvt_pk_bf16_f32 v133, v4, v5
	s_nop 0
	v_permlane16_swap_b32_e32 v130, v132
	v_permlane16_swap_b32_e32 v131, v133
	global_store_dwordx4 v[134:135], v[130:133], off offset:256 sc1
	s_branch .LBB0_691

; __device__ __forceinline__ u32x2 pack4(f32x4 v) { u32x2 r; r.x = cvt_pk(v[0], v[1]); r.y = cvt_pk(v[2], v[3]); return r; }
; __device__ __forceinline__ int lane_fresh() { int l; asm volatile("v_mbcnt_lo_u32_b32 %0, -1, 0\n\tv_mbcnt_hi_u32_b32 %0, -1, %0" : "=v"(l)); return l; }
; __device__ __forceinline__ float shfl_xor_f(float v, int mask) { const int l = lane_fresh(); return __int_as_float(__builtin_amdgcn_ds_bpermute((l ^ mask) << 2, __float_as_int(v))); }
; __device__ __forceinline__ void phaseE(const Params& p, const int wv, const int rep) {
;     ...
;     const int lane_e = lane_fresh(), fr = lane_e & 15, fq = lane_e >> 4; (void)fr; (void)fq;
; #pragma unroll
;     for (int ai = 0; ai < 2; ++ai)
; #pragma unroll
;       for (int m = 0; m < 4; ++m) {
;         const int row = brow + ai * 128 + wr * 64 + m * 16 + fr;
;         float ss = 0.f;
; #pragma unroll
;         for (int bj = 0; bj < 2; ++bj)
;           {
;             const int cb = bcol + bj * 128 + wc * 32;
;             f32x4 v0 = acc[ai][bj][m][0] + *(const f32x4*)(p.in[0] + (size_t)row * 1024 + cb + fq * 4);
;             f32x4 v1 = acc[ai][bj][m][1] + *(const f32x4*)(p.in[0] + (size_t)row * 1024 + cb + 16 + fq * 4);
;             store_pair16(H2B + (size_t)row * 1024 + cb, pack4(v0), pack4(v1), fq);
;             ss += v0[0] * v0[0] + v0[1] * v0[1] + v0[2] * v0[2] + v0[3] * v0[3] + v1[0] * v1[0] + v1[1] * v1[1] + v1[2] * v1[2] + v1[3] * v1[3];
;           }
;         ss += shfl_xor_f(ss, 16); ss += shfl_xor_f(ss, 32);
;         if (fq == 0) PS[(size_t)row * 16 + pn * 4 + wc] = ss;
;       }
.LBB0_983:
	s_lshl_b32 s30, s10, 8
	s_add_i32 s71, s71, s59
	v_mbcnt_lo_u32_b32 v135, -1, 0
	v_mbcnt_hi_u32_b32 v135, -1, v135
	s_or_b32 s34, s30, s60
	v_and_or_b32 v128, v135, 15, s71
	s_lshl_b32 s10, s10, 4
	v_readlane_b32 s72, v251, 6
	v_ashrrev_i32_e32 v146, 2, v135
	s_add_u32 s30, s61, s10
	v_lshlrev_b64 v[132:133], 12, v[128:129]
	v_readlane_b32 s73, v251, 7
	v_and_b32_e32 v130, -4, v146
	s_addc_u32 s31, s62, 0
	v_lshl_add_u64 v[132:133], s[72:73], 0, v[132:133]
	s_lshl_b32 s10, s34, 2
	v_ashrrev_i32_e32 v131, 31, v130
	v_lshl_add_u64 v[132:133], v[132:133], 0, s[10:11]
	v_lshl_add_u64 v[144:145], v[130:131], 2, v[132:133]
	global_load_dwordx4 v[136:139], v[144:145], off
	global_load_dwordx4 v[140:143], v[144:145], off offset:64
	v_and_b32_e32 v132, 16, v135
	v_and_b32_e32 v133, -8, v146
	v_add_u32_e32 v132, v133, v132
	v_ashrrev_i32_e32 v133, 31, v132
	v_lshlrev_b64 v[146:147], 11, v[128:129]
	v_lshl_add_u64 v[132:133], v[132:133], 1, s[8:9]
	s_mov_b32 s35, s11
	s_lshl_b32 s34, s34, 1
	v_lshl_add_u64 v[146:147], v[132:133], 0, v[146:147]
	v_lshl_add_u64 v[146:147], v[146:147], 0, s[34:35]
	v_cmp_gt_u32_e32 vcc, 16, v135
	v_readlane_b32 s74, v251, 8
	v_readlane_b32 s75, v251, 9
	v_readlane_b32 s76, v251, 10
	v_readlane_b32 s77, v251, 11
	v_readlane_b32 s78, v251, 12
	v_readlane_b32 s79, v251, 13
	v_readlane_b32 s80, v251, 14
	v_readlane_b32 s81, v251, 15
	v_readlane_b32 s82, v251, 16
	v_readlane_b32 s83, v251, 17
	v_readlane_b32 s84, v251, 18
	v_readlane_b32 s85, v251, 19
	v_readlane_b32 s86, v251, 20
	v_readlane_b32 s87, v251, 21
	s_waitcnt vmcnt(0)
	v_pk_add_f32 v[138:139], v[122:123], v[138:139]
	v_pk_add_f32 v[136:137], v[120:121], v[136:137]
	v_pk_add_f32 v[142:143], v[126:127], v[142:143]
	v_pk_add_f32 v[140:141], v[124:125], v[140:141]
	v_cvt_pk_bf16_f32 v120, v136, v137
	v_cvt_pk_bf16_f32 v121, v138, v139
	v_cvt_pk_bf16_f32 v122, v140, v141
	v_cvt_pk_bf16_f32 v123, v142, v143
	s_nop 0
	v_permlane16_swap_b32_e32 v120, v122
	v_permlane16_swap_b32_e32 v121, v123
	global_store_dwordx4 v[146:147], v[120:123], off sc1
	global_load_dwordx4 v[120:123], v[144:145], off offset:512
	s_nop 0
	global_load_dwordx4 v[124:127], v[144:145], off offset:576
	v_mul_f32_e32 v137, v137, v137
	v_fmac_f32_e32 v137, v136, v136
	v_fmac_f32_e32 v137, v138, v138
	v_fmac_f32_e32 v137, v139, v139
	v_fmac_f32_e32 v137, v140, v140
	v_fmac_f32_e32 v137, v141, v141
	v_fmac_f32_e32 v137, v142, v142
	v_fmac_f32_e32 v137, v143, v143
	s_waitcnt vmcnt(1)
	v_pk_add_f32 v[116:117], v[116:117], v[120:121]
	v_pk_add_f32 v[118:119], v[118:119], v[122:123]
	s_waitcnt vmcnt(0)
	v_pk_add_f32 v[122:123], v[112:113], v[124:125]
	v_cvt_pk_bf16_f32 v112, v116, v117
	v_mul_f32_e32 v117, v117, v117
	v_fmac_f32_e32 v117, v116, v116
	v_fmac_f32_e32 v117, v118, v118
	v_pk_add_f32 v[120:121], v[114:115], v[126:127]
	v_fmac_f32_e32 v117, v119, v119
	v_cvt_pk_bf16_f32 v113, v118, v119
	v_cvt_pk_bf16_f32 v114, v122, v123
	v_cvt_pk_bf16_f32 v115, v120, v121
	v_fmac_f32_e32 v117, v122, v122
	v_permlane16_swap_b32_e32 v112, v114
	v_permlane16_swap_b32_e32 v113, v115
	v_fmac_f32_e32 v117, v123, v123
	global_store_dwordx4 v[146:147], v[112:115], off offset:256 sc1
	v_fmac_f32_e32 v117, v120, v120
	v_fmac_f32_e32 v117, v121, v121
	v_mbcnt_lo_u32_b32 v112, -1, 0
	v_mbcnt_hi_u32_b32 v112, -1, v112
	v_add_f32_e32 v113, v137, v117
	v_lshlrev_b32_e32 v112, 2, v112
	v_xor_b32_e32 v112, 64, v112
	ds_bpermute_b32 v112, v112, v113
	v_mbcnt_lo_u32_b32 v114, -1, 0
	v_mbcnt_hi_u32_b32 v114, -1, v114
	s_waitcnt lgkmcnt(0)
	v_add_f32_e32 v112, v113, v112
	v_lshlrev_b32_e32 v114, 2, v114
	v_xor_b32_e32 v113, 0x80, v114
	ds_bpermute_b32 v113, v113, v112
	s_and_saveexec_b64 s[36:37], vcc
	s_cbranch_execz .LBB0_985
	s_waitcnt lgkmcnt(0)
	v_add_f32_e32 v114, v112, v113
	v_lshlrev_b64 v[112:113], 6, v[128:129]
	v_lshl_add_u64 v[112:113], s[30:31], 0, v[112:113]
	global_store_dword v[112:113], v114, off
.LBB0_985:
	s_or_b64 exec, exec, s[36:37]
	v_or_b32_e32 v112, 16, v128
	s_waitcnt lgkmcnt(0)
	v_mov_b32_e32 v113, v129
	v_readlane_b32 s72, v251, 6
	v_lshlrev_b64 v[114:115], 12, v[112:113]
	v_readlane_b32 s73, v251, 7
	v_lshlrev_b64 v[124:125], 11, v[112:113]
	v_lshl_add_u64 v[124:125], v[132:133], 0, v[124:125]
	v_lshl_add_u64 v[114:115], s[72:73], 0, v[114:115]
	v_lshl_add_u64 v[114:115], v[114:115], 0, s[10:11]
	v_lshl_add_u64 v[122:123], v[130:131], 2, v[114:115]
	global_load_dwordx4 v[114:117], v[122:123], off
	global_load_dwordx4 v[118:121], v[122:123], off offset:64
	v_lshl_add_u64 v[124:125], v[124:125], 0, s[34:35]
	v_readlane_b32 s74, v251, 8
	v_readlane_b32 s75, v251, 9
	v_readlane_b32 s76, v251, 10
	v_readlane_b32 s77, v251, 11
	v_readlane_b32 s78, v251, 12
	v_readlane_b32 s79, v251, 13
	v_readlane_b32 s80, v251, 14
	v_readlane_b32 s81, v251, 15
	v_readlane_b32 s82, v251, 16
	v_readlane_b32 s83, v251, 17
	v_readlane_b32 s84, v251, 18
	v_readlane_b32 s85, v251, 19
	v_readlane_b32 s86, v251, 20
	v_readlane_b32 s87, v251, 21
	s_waitcnt vmcnt(1)
	v_pk_add_f32 v[116:117], v[106:107], v[116:117]
	v_pk_add_f32 v[114:115], v[104:105], v[114:115]
	s_waitcnt vmcnt(0)
	v_pk_add_f32 v[120:121], v[110:111], v[120:121]
	v_pk_add_f32 v[118:119], v[108:109], v[118:119]
	v_cvt_pk_bf16_f32 v104, v114, v115
	v_cvt_pk_bf16_f32 v105, v116, v117
	v_cvt_pk_bf16_f32 v106, v118, v119
	v_cvt_pk_bf16_f32 v107, v120, v121
	s_nop 0
	v_permlane16_swap_b32_e32 v104, v106
	v_permlane16_swap_b32_e32 v105, v107
	global_store_dwordx4 v[124:125], v[104:107], off sc1
	global_load_dwordx4 v[104:107], v[122:123], off offset:512
	s_nop 0
	global_load_dwordx4 v[108:111], v[122:123], off offset:576
	v_mul_f32_e32 v115, v115, v115
	v_fmac_f32_e32 v115, v114, v114
	v_fmac_f32_e32 v115, v116, v116
	v_fmac_f32_e32 v115, v117, v117
	v_fmac_f32_e32 v115, v118, v118
	v_fmac_f32_e32 v115, v119, v119
	v_fmac_f32_e32 v115, v120, v120
	v_fmac_f32_e32 v115, v121, v121
	s_waitcnt vmcnt(1)
; __device__ __forceinline__ u32x2 pack4(f32x4 v) { u32x2 r; r.x = cvt_pk(v[0], v[1]); r.y = cvt_pk(v[2], v[3]); return r; }
; __device__ __forceinline__ int lane_fresh() { int l; asm volatile("v_mbcnt_lo_u32_b32 %0, -1, 0\n\tv_mbcnt_hi_u32_b32 %0, -1, %0" : "=v"(l)); return l; }
; __device__ __forceinline__ float shfl_xor_f(float v, int mask) { const int l = lane_fresh(); return __int_as_float(__builtin_amdgcn_ds_bpermute((l ^ mask) << 2, __float_as_int(v))); }
; __device__ __forceinline__ void phaseE(const Params& p, const int wv, const int rep) {
;     ...
;     const int lane_e = lane_fresh(), fr = lane_e & 15, fq = lane_e >> 4; (void)fr; (void)fq;
; #pragma unroll
;     for (int ai = 0; ai < 2; ++ai)
; #pragma unroll
;       for (int m = 0; m < 4; ++m) {
;         const int row = brow + ai * 128 + wr * 64 + m * 16 + fr;
;         float ss = 0.f;
; #pragma unroll
;         for (int bj = 0; bj < 2; ++bj)
;           {
;             const int cb = bcol + bj * 128 + wc * 32;
;             f32x4 v0 = acc[ai][bj][m][0] + *(const f32x4*)(p.in[0] + (size_t)row * 1024 + cb + fq * 4);
;             f32x4 v1 = acc[ai][bj][m][1] + *(const f32x4*)(p.in[0] + (size_t)row * 1024 + cb + 16 + fq * 4);
;             store_pair16(H2B + (size_t)row * 1024 + cb, pack4(v0), pack4(v1), fq);
;             ss += v0[0] * v0[0] + v0[1] * v0[1] + v0[2] * v0[2] + v0[3] * v0[3] + v1[0] * v1[0] + v1[1] * v1[1] + v1[2] * v1[2] + v1[3] * v1[3];
;           }
;         ss += shfl_xor_f(ss, 16); ss += shfl_xor_f(ss, 32);
;         if (fq == 0) PS[(size_t)row * 16 + pn * 4 + wc] = ss;
;       }
	v_pk_add_f32 v[100:101], v[100:101], v[104:105]
	v_pk_add_f32 v[102:103], v[102:103], v[106:107]
	s_waitcnt vmcnt(0)
	v_pk_add_f32 v[106:107], v[96:97], v[108:109]
	v_cvt_pk_bf16_f32 v96, v100, v101
	v_mul_f32_e32 v101, v101, v101
	v_fmac_f32_e32 v101, v100, v100
	v_fmac_f32_e32 v101, v102, v102
	v_pk_add_f32 v[104:105], v[98:99], v[110:111]
	v_fmac_f32_e32 v101, v103, v103
	v_cvt_pk_bf16_f32 v97, v102, v103
	v_cvt_pk_bf16_f32 v98, v106, v107
	v_cvt_pk_bf16_f32 v99, v104, v105
	v_fmac_f32_e32 v101, v106, v106
	v_permlane16_swap_b32_e32 v96, v98
	v_permlane16_swap_b32_e32 v97, v99
	v_fmac_f32_e32 v101, v107, v107
	global_store_dwordx4 v[124:125], v[96:99], off offset:256 sc1
	v_fmac_f32_e32 v101, v104, v104
	v_fmac_f32_e32 v101, v105, v105
	v_mbcnt_lo_u32_b32 v96, -1, 0
	v_mbcnt_hi_u32_b32 v96, -1, v96
	v_add_f32_e32 v97, v115, v101
	v_lshlrev_b32_e32 v96, 2, v96
	v_xor_b32_e32 v96, 64, v96
	ds_bpermute_b32 v96, v96, v97
	v_mbcnt_lo_u32_b32 v98, -1, 0
	v_mbcnt_hi_u32_b32 v98, -1, v98
	s_waitcnt lgkmcnt(0)
	v_add_f32_e32 v96, v97, v96
	v_lshlrev_b32_e32 v98, 2, v98
	v_xor_b32_e32 v97, 0x80, v98
	ds_bpermute_b32 v97, v97, v96
	s_and_saveexec_b64 s[36:37], vcc
	s_cbranch_execz .LBB0_987
	s_waitcnt lgkmcnt(0)
	v_add_f32_e32 v98, v96, v97
	v_lshlrev_b64 v[96:97], 6, v[112:113]
	v_lshl_add_u64 v[96:97], s[30:31], 0, v[96:97]
	global_store_dword v[96:97], v98, off
.LBB0_987:
	s_or_b64 exec, exec, s[36:37]
	v_or_b32_e32 v96, 32, v128
	s_waitcnt lgkmcnt(0)
	v_mov_b32_e32 v97, v129
	v_readlane_b32 s72, v251, 6
	v_lshlrev_b64 v[98:99], 12, v[96:97]
	v_readlane_b32 s73, v251, 7
	v_lshlrev_b64 v[108:109], 11, v[96:97]
	s_mov_b32 s35, s11
	v_lshl_add_u64 v[98:99], s[72:73], 0, v[98:99]
	v_lshl_add_u64 v[98:99], v[98:99], 0, s[10:11]
	v_lshl_add_u64 v[106:107], v[130:131], 2, v[98:99]
	global_load_dwordx4 v[98:101], v[106:107], off
	global_load_dwordx4 v[102:105], v[106:107], off offset:64
	v_lshl_add_u64 v[108:109], v[132:133], 0, v[108:109]
	v_lshl_add_u64 v[108:109], v[108:109], 0, s[34:35]
	v_readlane_b32 s74, v251, 8
	v_readlane_b32 s75, v251, 9
	v_readlane_b32 s76, v251, 10
	v_readlane_b32 s77, v251, 11
	v_readlane_b32 s78, v251, 12
	v_readlane_b32 s79, v251, 13
	v_readlane_b32 s80, v251, 14
	v_readlane_b32 s81, v251, 15
	v_readlane_b32 s82, v251, 16
	v_readlane_b32 s83, v251, 17
	v_readlane_b32 s84, v251, 18
	v_readlane_b32 s85, v251, 19
	v_readlane_b32 s86, v251, 20
	v_readlane_b32 s87, v251, 21
	s_waitcnt vmcnt(1)
	v_pk_add_f32 v[100:101], v[90:91], v[100:101]
	v_pk_add_f32 v[98:99], v[88:89], v[98:99]
	s_waitcnt vmcnt(0)
	v_pk_add_f32 v[104:105], v[94:95], v[104:105]
	v_pk_add_f32 v[102:103], v[92:93], v[102:103]
	v_cvt_pk_bf16_f32 v88, v98, v99
	v_cvt_pk_bf16_f32 v89, v100, v101
	v_cvt_pk_bf16_f32 v90, v102, v103
	v_cvt_pk_bf16_f32 v91, v104, v105
	s_nop 0
	v_permlane16_swap_b32_e32 v88, v90
	v_permlane16_swap_b32_e32 v89, v91
	global_store_dwordx4 v[108:109], v[88:91], off sc1
	global_load_dwordx4 v[88:91], v[106:107], off offset:512
	s_nop 0
	global_load_dwordx4 v[92:95], v[106:107], off offset:576
	v_mul_f32_e32 v99, v99, v99
	v_fmac_f32_e32 v99, v98, v98
	v_fmac_f32_e32 v99, v100, v100
	v_fmac_f32_e32 v99, v101, v101
	v_fmac_f32_e32 v99, v102, v102
	v_fmac_f32_e32 v99, v103, v103
	v_fmac_f32_e32 v99, v104, v104
	v_fmac_f32_e32 v99, v105, v105
	s_waitcnt vmcnt(1)
	v_pk_add_f32 v[84:85], v[84:85], v[88:89]
	v_pk_add_f32 v[86:87], v[86:87], v[90:91]
	s_waitcnt vmcnt(0)
	v_pk_add_f32 v[90:91], v[80:81], v[92:93]
	v_cvt_pk_bf16_f32 v80, v84, v85
	v_mul_f32_e32 v85, v85, v85
	v_fmac_f32_e32 v85, v84, v84
	v_fmac_f32_e32 v85, v86, v86
	v_pk_add_f32 v[88:89], v[82:83], v[94:95]
	v_fmac_f32_e32 v85, v87, v87
	v_cvt_pk_bf16_f32 v81, v86, v87
	v_cvt_pk_bf16_f32 v82, v90, v91
	v_cvt_pk_bf16_f32 v83, v88, v89
	v_fmac_f32_e32 v85, v90, v90
	v_permlane16_swap_b32_e32 v80, v82
	v_permlane16_swap_b32_e32 v81, v83
	v_fmac_f32_e32 v85, v91, v91
	global_store_dwordx4 v[108:109], v[80:83], off offset:256 sc1
	v_fmac_f32_e32 v85, v88, v88
	v_fmac_f32_e32 v85, v89, v89
	v_mbcnt_lo_u32_b32 v80, -1, 0
	v_mbcnt_hi_u32_b32 v80, -1, v80
	v_add_f32_e32 v81, v99, v85
	v_lshlrev_b32_e32 v80, 2, v80
	v_xor_b32_e32 v80, 64, v80
	ds_bpermute_b32 v80, v80, v81
	v_mbcnt_lo_u32_b32 v82, -1, 0
	v_mbcnt_hi_u32_b32 v82, -1, v82
	s_waitcnt lgkmcnt(0)
	v_add_f32_e32 v80, v81, v80
	v_lshlrev_b32_e32 v82, 2, v82
	v_xor_b32_e32 v81, 0x80, v82
	ds_bpermute_b32 v81, v81, v80
	s_and_saveexec_b64 s[36:37], vcc
	s_cbranch_execz .LBB0_989
	s_waitcnt lgkmcnt(0)
	v_add_f32_e32 v82, v80, v81
	v_lshlrev_b64 v[80:81], 6, v[96:97]
	v_lshl_add_u64 v[80:81], s[30:31], 0, v[80:81]
	global_store_dword v[80:81], v82, off
; __device__ __forceinline__ u32x2 pack4(f32x4 v) { u32x2 r; r.x = cvt_pk(v[0], v[1]); r.y = cvt_pk(v[2], v[3]); return r; }
; __device__ __forceinline__ int lane_fresh() { int l; asm volatile("v_mbcnt_lo_u32_b32 %0, -1, 0\n\tv_mbcnt_hi_u32_b32 %0, -1, %0" : "=v"(l)); return l; }
; __device__ __forceinline__ float shfl_xor_f(float v, int mask) { const int l = lane_fresh(); return __int_as_float(__builtin_amdgcn_ds_bpermute((l ^ mask) << 2, __float_as_int(v))); }
; __device__ __forceinline__ void phaseE(const Params& p, const int wv, const int rep) {
;     ...
;     const int lane_e = lane_fresh(), fr = lane_e & 15, fq = lane_e >> 4; (void)fr; (void)fq;
; #pragma unroll
;     for (int ai = 0; ai < 2; ++ai)
; #pragma unroll
;       for (int m = 0; m < 4; ++m) {
;         const int row = brow + ai * 128 + wr * 64 + m * 16 + fr;
;         float ss = 0.f;
; #pragma unroll
;         for (int bj = 0; bj < 2; ++bj)
;           {
;             const int cb = bcol + bj * 128 + wc * 32;
;             f32x4 v0 = acc[ai][bj][m][0] + *(const f32x4*)(p.in[0] + (size_t)row * 1024 + cb + fq * 4);
;             f32x4 v1 = acc[ai][bj][m][1] + *(const f32x4*)(p.in[0] + (size_t)row * 1024 + cb + 16 + fq * 4);
;             store_pair16(H2B + (size_t)row * 1024 + cb, pack4(v0), pack4(v1), fq);
;             ss += v0[0] * v0[0] + v0[1] * v0[1] + v0[2] * v0[2] + v0[3] * v0[3] + v1[0] * v1[0] + v1[1] * v1[1] + v1[2] * v1[2] + v1[3] * v1[3];
;           }
;         ss += shfl_xor_f(ss, 16); ss += shfl_xor_f(ss, 32);
;         if (fq == 0) PS[(size_t)row * 16 + pn * 4 + wc] = ss;
;       }
.LBB0_989:
	s_or_b64 exec, exec, s[36:37]
	v_or_b32_e32 v80, 48, v128
	s_waitcnt lgkmcnt(0)
	v_mov_b32_e32 v81, v129
	v_readlane_b32 s72, v251, 6
	v_lshlrev_b64 v[82:83], 12, v[80:81]
	v_readlane_b32 s73, v251, 7
	v_lshlrev_b64 v[92:93], 11, v[80:81]
	v_lshl_add_u64 v[92:93], v[132:133], 0, v[92:93]
	v_lshl_add_u64 v[82:83], s[72:73], 0, v[82:83]
	v_lshl_add_u64 v[82:83], v[82:83], 0, s[10:11]
	v_lshl_add_u64 v[90:91], v[130:131], 2, v[82:83]
	global_load_dwordx4 v[82:85], v[90:91], off
	global_load_dwordx4 v[86:89], v[90:91], off offset:64
	v_lshl_add_u64 v[92:93], v[92:93], 0, s[34:35]
	v_readlane_b32 s74, v251, 8
	v_readlane_b32 s75, v251, 9
	v_readlane_b32 s76, v251, 10
	v_readlane_b32 s77, v251, 11
	v_readlane_b32 s78, v251, 12
	v_readlane_b32 s79, v251, 13
	v_readlane_b32 s80, v251, 14
	v_readlane_b32 s81, v251, 15
	v_readlane_b32 s82, v251, 16
	v_readlane_b32 s83, v251, 17
	v_readlane_b32 s84, v251, 18
	v_readlane_b32 s85, v251, 19
	v_readlane_b32 s86, v251, 20
	v_readlane_b32 s87, v251, 21
	s_waitcnt vmcnt(1)
	v_pk_add_f32 v[84:85], v[74:75], v[84:85]
	v_pk_add_f32 v[82:83], v[72:73], v[82:83]
	s_waitcnt vmcnt(0)
	v_pk_add_f32 v[88:89], v[78:79], v[88:89]
	v_pk_add_f32 v[86:87], v[76:77], v[86:87]
	v_cvt_pk_bf16_f32 v72, v82, v83
	v_cvt_pk_bf16_f32 v73, v84, v85
	v_cvt_pk_bf16_f32 v74, v86, v87
	v_cvt_pk_bf16_f32 v75, v88, v89
	s_nop 0
	v_permlane16_swap_b32_e32 v72, v74
	v_permlane16_swap_b32_e32 v73, v75
	global_store_dwordx4 v[92:93], v[72:75], off sc1
	global_load_dwordx4 v[72:75], v[90:91], off offset:512
	s_nop 0
	global_load_dwordx4 v[76:79], v[90:91], off offset:576
	v_mul_f32_e32 v83, v83, v83
	v_fmac_f32_e32 v83, v82, v82
	v_fmac_f32_e32 v83, v84, v84
	v_fmac_f32_e32 v83, v85, v85
	v_fmac_f32_e32 v83, v86, v86
	v_fmac_f32_e32 v83, v87, v87
	v_fmac_f32_e32 v83, v88, v88
	v_fmac_f32_e32 v83, v89, v89
	s_waitcnt vmcnt(1)
	v_pk_add_f32 v[68:69], v[68:69], v[72:73]
	v_pk_add_f32 v[70:71], v[70:71], v[74:75]
	s_waitcnt vmcnt(0)
	v_pk_add_f32 v[74:75], v[64:65], v[76:77]
	v_cvt_pk_bf16_f32 v64, v68, v69
	v_mul_f32_e32 v69, v69, v69
	v_fmac_f32_e32 v69, v68, v68
	v_fmac_f32_e32 v69, v70, v70
	v_pk_add_f32 v[72:73], v[66:67], v[78:79]
	v_fmac_f32_e32 v69, v71, v71
	v_cvt_pk_bf16_f32 v65, v70, v71
	v_cvt_pk_bf16_f32 v66, v74, v75
	v_cvt_pk_bf16_f32 v67, v72, v73
	v_fmac_f32_e32 v69, v74, v74
	v_permlane16_swap_b32_e32 v64, v66
	v_permlane16_swap_b32_e32 v65, v67
	v_fmac_f32_e32 v69, v75, v75
	global_store_dwordx4 v[92:93], v[64:67], off offset:256 sc1
	v_fmac_f32_e32 v69, v72, v72
	v_fmac_f32_e32 v69, v73, v73
	v_mbcnt_lo_u32_b32 v64, -1, 0
	v_mbcnt_hi_u32_b32 v64, -1, v64
	v_add_f32_e32 v65, v83, v69
	v_lshlrev_b32_e32 v64, 2, v64
	v_xor_b32_e32 v64, 64, v64
	ds_bpermute_b32 v64, v64, v65
	v_mbcnt_lo_u32_b32 v66, -1, 0
	v_mbcnt_hi_u32_b32 v66, -1, v66
	s_waitcnt lgkmcnt(0)
	v_add_f32_e32 v64, v65, v64
	v_lshlrev_b32_e32 v66, 2, v66
	v_xor_b32_e32 v65, 0x80, v66
	ds_bpermute_b32 v65, v65, v64
	s_and_saveexec_b64 s[36:37], vcc
	s_cbranch_execz .LBB0_991
	s_waitcnt lgkmcnt(0)
	v_add_f32_e32 v66, v64, v65
	v_lshlrev_b64 v[64:65], 6, v[80:81]
	v_lshl_add_u64 v[64:65], s[30:31], 0, v[64:65]
	global_store_dword v[64:65], v66, off
.LBB0_991:
	s_or_b64 exec, exec, s[36:37]
	v_add_u32_e32 v64, 0x80, v128
	s_waitcnt lgkmcnt(0)
	v_mov_b32_e32 v65, v129
	v_readlane_b32 s72, v251, 6
	v_lshlrev_b64 v[66:67], 12, v[64:65]
	v_readlane_b32 s73, v251, 7
	v_lshlrev_b64 v[76:77], 11, v[64:65]
	s_mov_b32 s35, s11
	v_lshl_add_u64 v[66:67], s[72:73], 0, v[66:67]
	v_lshl_add_u64 v[66:67], v[66:67], 0, s[10:11]
	v_lshl_add_u64 v[74:75], v[130:131], 2, v[66:67]
	global_load_dwordx4 v[66:69], v[74:75], off
	global_load_dwordx4 v[70:73], v[74:75], off offset:64
	v_lshl_add_u64 v[76:77], v[132:133], 0, v[76:77]
	v_lshl_add_u64 v[76:77], v[76:77], 0, s[34:35]
	v_readlane_b32 s74, v251, 8
	v_readlane_b32 s75, v251, 9
	v_readlane_b32 s76, v251, 10
	v_readlane_b32 s77, v251, 11
	v_readlane_b32 s78, v251, 12
	v_readlane_b32 s79, v251, 13
	v_readlane_b32 s80, v251, 14
	v_readlane_b32 s81, v251, 15
	v_readlane_b32 s82, v251, 16
	v_readlane_b32 s83, v251, 17
	v_readlane_b32 s84, v251, 18
	v_readlane_b32 s85, v251, 19
	v_readlane_b32 s86, v251, 20
	v_readlane_b32 s87, v251, 21
	s_waitcnt vmcnt(1)
	v_pk_add_f32 v[68:69], v[58:59], v[68:69]
	v_pk_add_f32 v[66:67], v[56:57], v[66:67]
	s_waitcnt vmcnt(0)
	v_pk_add_f32 v[72:73], v[62:63], v[72:73]
	v_pk_add_f32 v[70:71], v[60:61], v[70:71]
	v_cvt_pk_bf16_f32 v56, v66, v67
	v_cvt_pk_bf16_f32 v57, v68, v69
	v_cvt_pk_bf16_f32 v58, v70, v71
	v_cvt_pk_bf16_f32 v59, v72, v73
	s_nop 0
	v_permlane16_swap_b32_e32 v56, v58
	v_permlane16_swap_b32_e32 v57, v59
	global_store_dwordx4 v[76:77], v[56:59], off sc1
	global_load_dwordx4 v[56:59], v[74:75], off offset:512
	s_nop 0
	global_load_dwordx4 v[60:63], v[74:75], off offset:576
	v_mul_f32_e32 v67, v67, v67
	v_fmac_f32_e32 v67, v66, v66
	v_fmac_f32_e32 v67, v68, v68
	v_fmac_f32_e32 v67, v69, v69
	v_fmac_f32_e32 v67, v70, v70
	v_fmac_f32_e32 v67, v71, v71
	v_fmac_f32_e32 v67, v72, v72
	v_fmac_f32_e32 v67, v73, v73
	s_waitcnt vmcnt(1)
	v_pk_add_f32 v[52:53], v[52:53], v[56:57]
	v_pk_add_f32 v[54:55], v[54:55], v[58:59]
	s_waitcnt vmcnt(0)
	v_pk_add_f32 v[58:59], v[48:49], v[60:61]
	v_cvt_pk_bf16_f32 v48, v52, v53
	v_mul_f32_e32 v53, v53, v53
	v_fmac_f32_e32 v53, v52, v52
	v_fmac_f32_e32 v53, v54, v54
	v_pk_add_f32 v[56:57], v[50:51], v[62:63]
	v_fmac_f32_e32 v53, v55, v55
	v_cvt_pk_bf16_f32 v49, v54, v55
	v_cvt_pk_bf16_f32 v50, v58, v59
	v_cvt_pk_bf16_f32 v51, v56, v57
	v_fmac_f32_e32 v53, v58, v58
	v_permlane16_swap_b32_e32 v48, v50
	v_permlane16_swap_b32_e32 v49, v51
	v_fmac_f32_e32 v53, v59, v59
	global_store_dwordx4 v[76:77], v[48:51], off offset:256 sc1
	v_fmac_f32_e32 v53, v56, v56
	v_fmac_f32_e32 v53, v57, v57
	v_mbcnt_lo_u32_b32 v48, -1, 0
	v_mbcnt_hi_u32_b32 v48, -1, v48
	v_add_f32_e32 v49, v67, v53
	v_lshlrev_b32_e32 v48, 2, v48
	v_xor_b32_e32 v48, 64, v48
	ds_bpermute_b32 v48, v48, v49
	v_mbcnt_lo_u32_b32 v50, -1, 0
	v_mbcnt_hi_u32_b32 v50, -1, v50
	s_waitcnt lgkmcnt(0)
	v_add_f32_e32 v48, v49, v48
	v_lshlrev_b32_e32 v50, 2, v50
	v_xor_b32_e32 v49, 0x80, v50
	ds_bpermute_b32 v49, v49, v48
	s_and_saveexec_b64 s[36:37], vcc
	s_cbranch_execz .LBB0_993
	s_waitcnt lgkmcnt(0)
	v_add_f32_e32 v50, v48, v49
	v_lshlrev_b64 v[48:49], 6, v[64:65]
	v_lshl_add_u64 v[48:49], s[30:31], 0, v[48:49]
	global_store_dword v[48:49], v50, off
; __device__ __forceinline__ u32x2 pack4(f32x4 v) { u32x2 r; r.x = cvt_pk(v[0], v[1]); r.y = cvt_pk(v[2], v[3]); return r; }
; __device__ __forceinline__ int lane_fresh() { int l; asm volatile("v_mbcnt_lo_u32_b32 %0, -1, 0\n\tv_mbcnt_hi_u32_b32 %0, -1, %0" : "=v"(l)); return l; }
; __device__ __forceinline__ float shfl_xor_f(float v, int mask) { const int l = lane_fresh(); return __int_as_float(__builtin_amdgcn_ds_bpermute((l ^ mask) << 2, __float_as_int(v))); }
; __device__ __forceinline__ void phaseE(const Params& p, const int wv, const int rep) {
;     ...
;     const int lane_e = lane_fresh(), fr = lane_e & 15, fq = lane_e >> 4; (void)fr; (void)fq;
; #pragma unroll
;     for (int ai = 0; ai < 2; ++ai)
; #pragma unroll
;       for (int m = 0; m < 4; ++m) {
;         const int row = brow + ai * 128 + wr * 64 + m * 16 + fr;
;         float ss = 0.f;
; #pragma unroll
;         for (int bj = 0; bj < 2; ++bj)
;           {
;             const int cb = bcol + bj * 128 + wc * 32;
;             f32x4 v0 = acc[ai][bj][m][0] + *(const f32x4*)(p.in[0] + (size_t)row * 1024 + cb + fq * 4);
;             f32x4 v1 = acc[ai][bj][m][1] + *(const f32x4*)(p.in[0] + (size_t)row * 1024 + cb + 16 + fq * 4);
;             store_pair16(H2B + (size_t)row * 1024 + cb, pack4(v0), pack4(v1), fq);
;             ss += v0[0] * v0[0] + v0[1] * v0[1] + v0[2] * v0[2] + v0[3] * v0[3] + v1[0] * v1[0] + v1[1] * v1[1] + v1[2] * v1[2] + v1[3] * v1[3];
;           }
;         ss += shfl_xor_f(ss, 16); ss += shfl_xor_f(ss, 32);
;         if (fq == 0) PS[(size_t)row * 16 + pn * 4 + wc] = ss;
;       }
.LBB0_993:
	s_or_b64 exec, exec, s[36:37]
	v_add_u32_e32 v48, 0x90, v128
	s_waitcnt lgkmcnt(0)
	v_mov_b32_e32 v49, v129
	v_readlane_b32 s72, v251, 6
	v_lshlrev_b64 v[50:51], 12, v[48:49]
	v_readlane_b32 s73, v251, 7
	v_lshlrev_b64 v[60:61], 11, v[48:49]
	v_lshl_add_u64 v[60:61], v[132:133], 0, v[60:61]
	v_lshl_add_u64 v[50:51], s[72:73], 0, v[50:51]
	v_lshl_add_u64 v[50:51], v[50:51], 0, s[10:11]
	v_lshl_add_u64 v[58:59], v[130:131], 2, v[50:51]
	global_load_dwordx4 v[50:53], v[58:59], off
	global_load_dwordx4 v[54:57], v[58:59], off offset:64
	v_lshl_add_u64 v[60:61], v[60:61], 0, s[34:35]
	v_readlane_b32 s74, v251, 8
	v_readlane_b32 s75, v251, 9
	v_readlane_b32 s76, v251, 10
	v_readlane_b32 s77, v251, 11
	v_readlane_b32 s78, v251, 12
	v_readlane_b32 s79, v251, 13
	v_readlane_b32 s80, v251, 14
	v_readlane_b32 s81, v251, 15
	v_readlane_b32 s82, v251, 16
	v_readlane_b32 s83, v251, 17
	v_readlane_b32 s84, v251, 18
	v_readlane_b32 s85, v251, 19
	v_readlane_b32 s86, v251, 20
	v_readlane_b32 s87, v251, 21
	s_waitcnt vmcnt(1)
	v_pk_add_f32 v[52:53], v[42:43], v[52:53]
	v_pk_add_f32 v[50:51], v[40:41], v[50:51]
	s_waitcnt vmcnt(0)
	v_pk_add_f32 v[56:57], v[46:47], v[56:57]
	v_pk_add_f32 v[54:55], v[44:45], v[54:55]
	v_cvt_pk_bf16_f32 v40, v50, v51
	v_cvt_pk_bf16_f32 v41, v52, v53
	v_cvt_pk_bf16_f32 v42, v54, v55
	v_cvt_pk_bf16_f32 v43, v56, v57
	s_nop 0
	v_permlane16_swap_b32_e32 v40, v42
	v_permlane16_swap_b32_e32 v41, v43
	global_store_dwordx4 v[60:61], v[40:43], off sc1
	global_load_dwordx4 v[40:43], v[58:59], off offset:512
	s_nop 0
	global_load_dwordx4 v[44:47], v[58:59], off offset:576
	v_mul_f32_e32 v51, v51, v51
	v_fmac_f32_e32 v51, v50, v50
	v_fmac_f32_e32 v51, v52, v52
	v_fmac_f32_e32 v51, v53, v53
	v_fmac_f32_e32 v51, v54, v54
	v_fmac_f32_e32 v51, v55, v55
	v_fmac_f32_e32 v51, v56, v56
	v_fmac_f32_e32 v51, v57, v57
	s_waitcnt vmcnt(1)
	v_pk_add_f32 v[36:37], v[36:37], v[40:41]
	v_pk_add_f32 v[38:39], v[38:39], v[42:43]
	s_waitcnt vmcnt(0)
	v_pk_add_f32 v[42:43], v[32:33], v[44:45]
	v_cvt_pk_bf16_f32 v32, v36, v37
	v_mul_f32_e32 v37, v37, v37
	v_fmac_f32_e32 v37, v36, v36
	v_fmac_f32_e32 v37, v38, v38
	v_pk_add_f32 v[40:41], v[34:35], v[46:47]
	v_fmac_f32_e32 v37, v39, v39
	v_cvt_pk_bf16_f32 v33, v38, v39
	v_cvt_pk_bf16_f32 v34, v42, v43
	v_cvt_pk_bf16_f32 v35, v40, v41
	v_fmac_f32_e32 v37, v42, v42
	v_permlane16_swap_b32_e32 v32, v34
	v_permlane16_swap_b32_e32 v33, v35
	v_fmac_f32_e32 v37, v43, v43
	global_store_dwordx4 v[60:61], v[32:35], off offset:256 sc1
	v_fmac_f32_e32 v37, v40, v40
	v_fmac_f32_e32 v37, v41, v41
	v_mbcnt_lo_u32_b32 v32, -1, 0
	v_mbcnt_hi_u32_b32 v32, -1, v32
	v_add_f32_e32 v33, v51, v37
	v_lshlrev_b32_e32 v32, 2, v32
	v_xor_b32_e32 v32, 64, v32
	ds_bpermute_b32 v32, v32, v33
	v_mbcnt_lo_u32_b32 v34, -1, 0
	v_mbcnt_hi_u32_b32 v34, -1, v34
	s_waitcnt lgkmcnt(0)
	v_add_f32_e32 v32, v33, v32
	v_lshlrev_b32_e32 v34, 2, v34
	v_xor_b32_e32 v33, 0x80, v34
	ds_bpermute_b32 v33, v33, v32
	s_and_saveexec_b64 s[36:37], vcc
	s_cbranch_execz .LBB0_995
	s_waitcnt lgkmcnt(0)
	v_add_f32_e32 v34, v32, v33
	v_lshlrev_b64 v[32:33], 6, v[48:49]
	v_lshl_add_u64 v[32:33], s[30:31], 0, v[32:33]
	global_store_dword v[32:33], v34, off
; __device__ __forceinline__ u32x2 pack4(f32x4 v) { u32x2 r; r.x = cvt_pk(v[0], v[1]); r.y = cvt_pk(v[2], v[3]); return r; }
; __device__ __forceinline__ int lane_fresh() { int l; asm volatile("v_mbcnt_lo_u32_b32 %0, -1, 0\n\tv_mbcnt_hi_u32_b32 %0, -1, %0" : "=v"(l)); return l; }
; __device__ __forceinline__ float shfl_xor_f(float v, int mask) { const int l = lane_fresh(); return __int_as_float(__builtin_amdgcn_ds_bpermute((l ^ mask) << 2, __float_as_int(v))); }
; __device__ __forceinline__ void phaseE(const Params& p, const int wv, const int rep) {
;     ...
;     const int lane_e = lane_fresh(), fr = lane_e & 15, fq = lane_e >> 4; (void)fr; (void)fq;
; #pragma unroll
;     for (int ai = 0; ai < 2; ++ai)
; #pragma unroll
;       for (int m = 0; m < 4; ++m) {
;         const int row = brow + ai * 128 + wr * 64 + m * 16 + fr;
;         float ss = 0.f;
; #pragma unroll
;         for (int bj = 0; bj < 2; ++bj)
;           {
;             const int cb = bcol + bj * 128 + wc * 32;
;             f32x4 v0 = acc[ai][bj][m][0] + *(const f32x4*)(p.in[0] + (size_t)row * 1024 + cb + fq * 4);
;             f32x4 v1 = acc[ai][bj][m][1] + *(const f32x4*)(p.in[0] + (size_t)row * 1024 + cb + 16 + fq * 4);
;             store_pair16(H2B + (size_t)row * 1024 + cb, pack4(v0), pack4(v1), fq);
;             ss += v0[0] * v0[0] + v0[1] * v0[1] + v0[2] * v0[2] + v0[3] * v0[3] + v1[0] * v1[0] + v1[1] * v1[1] + v1[2] * v1[2] + v1[3] * v1[3];
;           }
;         ss += shfl_xor_f(ss, 16); ss += shfl_xor_f(ss, 32);
;         if (fq == 0) PS[(size_t)row * 16 + pn * 4 + wc] = ss;
;       }
.LBB0_995:
	s_or_b64 exec, exec, s[36:37]
	v_add_u32_e32 v32, 0xa0, v128
	s_waitcnt lgkmcnt(0)
	v_mov_b32_e32 v33, v129
	v_readlane_b32 s72, v251, 6
	v_lshlrev_b64 v[34:35], 12, v[32:33]
	v_readlane_b32 s73, v251, 7
	v_lshlrev_b64 v[44:45], 11, v[32:33]
	s_mov_b32 s35, s11
	v_lshl_add_u64 v[34:35], s[72:73], 0, v[34:35]
	v_lshl_add_u64 v[34:35], v[34:35], 0, s[10:11]
	v_lshl_add_u64 v[42:43], v[130:131], 2, v[34:35]
	global_load_dwordx4 v[34:37], v[42:43], off
	global_load_dwordx4 v[38:41], v[42:43], off offset:64
	v_lshl_add_u64 v[44:45], v[132:133], 0, v[44:45]
	v_lshl_add_u64 v[44:45], v[44:45], 0, s[34:35]
	v_readlane_b32 s74, v251, 8
	v_readlane_b32 s75, v251, 9
	v_readlane_b32 s76, v251, 10
	v_readlane_b32 s77, v251, 11
	v_readlane_b32 s78, v251, 12
	v_readlane_b32 s79, v251, 13
	v_readlane_b32 s80, v251, 14
	v_readlane_b32 s81, v251, 15
	v_readlane_b32 s82, v251, 16
	v_readlane_b32 s83, v251, 17
	v_readlane_b32 s84, v251, 18
	v_readlane_b32 s85, v251, 19
	v_readlane_b32 s86, v251, 20
	v_readlane_b32 s87, v251, 21
	s_waitcnt vmcnt(1)
	v_pk_add_f32 v[36:37], v[26:27], v[36:37]
	v_pk_add_f32 v[34:35], v[24:25], v[34:35]
	s_waitcnt vmcnt(0)
	v_pk_add_f32 v[40:41], v[30:31], v[40:41]
	v_pk_add_f32 v[38:39], v[28:29], v[38:39]
	v_cvt_pk_bf16_f32 v24, v34, v35
	v_cvt_pk_bf16_f32 v25, v36, v37
	v_cvt_pk_bf16_f32 v26, v38, v39
	v_cvt_pk_bf16_f32 v27, v40, v41
	s_nop 0
	v_permlane16_swap_b32_e32 v24, v26
	v_permlane16_swap_b32_e32 v25, v27
	global_store_dwordx4 v[44:45], v[24:27], off sc1
	global_load_dwordx4 v[24:27], v[42:43], off offset:512
	s_nop 0
	global_load_dwordx4 v[28:31], v[42:43], off offset:576
	v_mul_f32_e32 v35, v35, v35
	v_fmac_f32_e32 v35, v34, v34
	v_fmac_f32_e32 v35, v36, v36
	v_fmac_f32_e32 v35, v37, v37
	v_fmac_f32_e32 v35, v38, v38
	v_fmac_f32_e32 v35, v39, v39
	v_fmac_f32_e32 v35, v40, v40
	v_fmac_f32_e32 v35, v41, v41
	s_waitcnt vmcnt(1)
	v_pk_add_f32 v[20:21], v[20:21], v[24:25]
	v_pk_add_f32 v[22:23], v[22:23], v[26:27]
	s_waitcnt vmcnt(0)
	v_pk_add_f32 v[26:27], v[16:17], v[28:29]
	v_cvt_pk_bf16_f32 v16, v20, v21
	v_mul_f32_e32 v21, v21, v21
	v_fmac_f32_e32 v21, v20, v20
	v_fmac_f32_e32 v21, v22, v22
	v_pk_add_f32 v[24:25], v[18:19], v[30:31]
	v_fmac_f32_e32 v21, v23, v23
	v_cvt_pk_bf16_f32 v17, v22, v23
	v_cvt_pk_bf16_f32 v18, v26, v27
	v_cvt_pk_bf16_f32 v19, v24, v25
	v_fmac_f32_e32 v21, v26, v26
	v_permlane16_swap_b32_e32 v16, v18
	v_permlane16_swap_b32_e32 v17, v19
	v_fmac_f32_e32 v21, v27, v27
	global_store_dwordx4 v[44:45], v[16:19], off offset:256 sc1
	v_fmac_f32_e32 v21, v24, v24
	v_fmac_f32_e32 v21, v25, v25
	v_mbcnt_lo_u32_b32 v16, -1, 0
	v_mbcnt_hi_u32_b32 v16, -1, v16
	v_add_f32_e32 v17, v35, v21
	v_lshlrev_b32_e32 v16, 2, v16
	v_xor_b32_e32 v16, 64, v16
	ds_bpermute_b32 v16, v16, v17
	v_mbcnt_lo_u32_b32 v18, -1, 0
	v_mbcnt_hi_u32_b32 v18, -1, v18
	s_waitcnt lgkmcnt(0)
	v_add_f32_e32 v16, v17, v16
	v_lshlrev_b32_e32 v18, 2, v18
	v_xor_b32_e32 v17, 0x80, v18
	ds_bpermute_b32 v17, v17, v16
	s_and_saveexec_b64 s[36:37], vcc
	s_cbranch_execz .LBB0_997
	s_waitcnt lgkmcnt(0)
	v_add_f32_e32 v18, v16, v17
	v_lshlrev_b64 v[16:17], 6, v[32:33]
	v_lshl_add_u64 v[16:17], s[30:31], 0, v[16:17]
	global_store_dword v[16:17], v18, off
.LBB0_997:
	s_or_b64 exec, exec, s[36:37]
	v_add_u32_e32 v128, 0xb0, v128
	v_readlane_b32 s72, v251, 6
	s_waitcnt lgkmcnt(0)
	v_lshlrev_b64 v[16:17], 12, v[128:129]
	v_readlane_b32 s73, v251, 7
	v_lshlrev_b64 v[26:27], 11, v[128:129]
	v_lshl_add_u64 v[26:27], v[132:133], 0, v[26:27]
	v_lshl_add_u64 v[16:17], s[72:73], 0, v[16:17]
	v_lshl_add_u64 v[16:17], v[16:17], 0, s[10:11]
	v_lshl_add_u64 v[24:25], v[130:131], 2, v[16:17]
	global_load_dwordx4 v[16:19], v[24:25], off
	global_load_dwordx4 v[20:23], v[24:25], off offset:64
	v_lshl_add_u64 v[26:27], v[26:27], 0, s[34:35]
	v_readlane_b32 s74, v251, 8
	v_readlane_b32 s75, v251, 9
	v_readlane_b32 s76, v251, 10
	v_readlane_b32 s77, v251, 11
	v_readlane_b32 s78, v251, 12
	v_readlane_b32 s79, v251, 13
	v_readlane_b32 s80, v251, 14
	v_readlane_b32 s81, v251, 15
	v_readlane_b32 s82, v251, 16
	v_readlane_b32 s83, v251, 17
	v_readlane_b32 s84, v251, 18
	v_readlane_b32 s85, v251, 19
	v_readlane_b32 s86, v251, 20
	v_readlane_b32 s87, v251, 21
	s_waitcnt vmcnt(1)
	v_pk_add_f32 v[18:19], v[10:11], v[18:19]
	v_pk_add_f32 v[16:17], v[8:9], v[16:17]
	s_waitcnt vmcnt(0)
	v_pk_add_f32 v[22:23], v[14:15], v[22:23]
	v_pk_add_f32 v[20:21], v[12:13], v[20:21]
	v_cvt_pk_bf16_f32 v8, v16, v17
	v_cvt_pk_bf16_f32 v9, v18, v19
	v_cvt_pk_bf16_f32 v10, v20, v21
	v_cvt_pk_bf16_f32 v11, v22, v23
	s_nop 0
	v_permlane16_swap_b32_e32 v8, v10
	v_permlane16_swap_b32_e32 v9, v11
	global_store_dwordx4 v[26:27], v[8:11], off sc1
	global_load_dwordx4 v[8:11], v[24:25], off offset:512
	s_nop 0
	global_load_dwordx4 v[12:15], v[24:25], off offset:576
	v_mul_f32_e32 v17, v17, v17
	v_fmac_f32_e32 v17, v16, v16
	v_fmac_f32_e32 v17, v18, v18
	v_fmac_f32_e32 v17, v19, v19
	v_fmac_f32_e32 v17, v20, v20
	v_fmac_f32_e32 v17, v21, v21
	v_fmac_f32_e32 v17, v22, v22
	v_fmac_f32_e32 v17, v23, v23
	s_waitcnt vmcnt(1)
	v_pk_add_f32 v[4:5], v[4:5], v[8:9]
	v_pk_add_f32 v[6:7], v[6:7], v[10:11]
	s_waitcnt vmcnt(0)
	v_pk_add_f32 v[10:11], v[0:1], v[12:13]
	v_cvt_pk_bf16_f32 v0, v4, v5
	v_mul_f32_e32 v5, v5, v5
	v_fmac_f32_e32 v5, v4, v4
	v_fmac_f32_e32 v5, v6, v6
	v_pk_add_f32 v[8:9], v[2:3], v[14:15]
	v_fmac_f32_e32 v5, v7, v7
	v_cvt_pk_bf16_f32 v1, v6, v7
	v_cvt_pk_bf16_f32 v2, v10, v11
	v_cvt_pk_bf16_f32 v3, v8, v9
	v_fmac_f32_e32 v5, v10, v10
	v_permlane16_swap_b32_e32 v0, v2
	v_permlane16_swap_b32_e32 v1, v3
	v_fmac_f32_e32 v5, v11, v11
	global_store_dwordx4 v[26:27], v[0:3], off offset:256 sc1
	v_fmac_f32_e32 v5, v8, v8
	v_fmac_f32_e32 v5, v9, v9
	v_mbcnt_lo_u32_b32 v0, -1, 0
	v_mbcnt_hi_u32_b32 v0, -1, v0
	v_add_f32_e32 v1, v17, v5
	v_lshlrev_b32_e32 v0, 2, v0
	v_xor_b32_e32 v0, 64, v0
	ds_bpermute_b32 v0, v0, v1
	v_mbcnt_lo_u32_b32 v2, -1, 0
	v_mbcnt_hi_u32_b32 v2, -1, v2
	s_waitcnt lgkmcnt(0)
	v_add_f32_e32 v0, v1, v0
	v_lshlrev_b32_e32 v2, 2, v2
	v_xor_b32_e32 v1, 0x80, v2
	ds_bpermute_b32 v1, v1, v0
	s_and_saveexec_b64 s[34:35], vcc
	s_cbranch_execz .LBB0_976
	s_waitcnt lgkmcnt(0)
	v_add_f32_e32 v2, v0, v1
	v_lshlrev_b64 v[0:1], 6, v[128:129]
	v_lshl_add_u64 v[0:1], s[30:31], 0, v[0:1]
	global_store_dword v[0:1], v2, off
	s_branch .LBB0_976

; __device__ __forceinline__ u32x2 pack4(f32x4 v) { u32x2 r; r.x = cvt_pk(v[0], v[1]); r.y = cvt_pk(v[2], v[3]); return r; }
; __device__ __forceinline__ void phaseF(const Params& p, const int wv, const int rep) {
;     ...
;       const float* rs_c = rs_l + (it & 1) * 256;
;       ACC_FOREACH_PAIR({
;         const float rstd = rs_c[rrow];
;         f32x4 o0 = v0 * rstd, o1 = v1 * rstd;
;         o0[0] = fmaxf(o0[0], 0.f); o0[1] = fmaxf(o0[1], 0.f); o0[2] = fmaxf(o0[2], 0.f); o0[3] = fmaxf(o0[3], 0.f);
;         o1[0] = fmaxf(o1[0], 0.f); o1[1] = fmaxf(o1[1], 0.f); o1[2] = fmaxf(o1[2], 0.f); o1[3] = fmaxf(o1[3], 0.f);
;         o0 = o0 * o0; o1 = o1 * o1;
;         store_pair16(ACT + (size_t)(brow + rrow) * 4096 + bcol + cb32, pack4(o0), pack4(o1), fq);
;       });
.LBB0_1065:
	s_lshl_b32 s38, s76, 10
	s_and_b32 s38, s38, 0x400
	s_add_i32 s38, s38, 16
	v_mbcnt_lo_u32_b32 v128, -1, 0
	v_mbcnt_hi_u32_b32 v128, -1, v128
	s_nop 0
	v_and_or_b32 v135, v128, 15, s66
	v_lshl_add_u32 v134, v135, 2, s38
	v_add_u32_e32 v134, 0x20000, v134
	s_waitcnt vmcnt(0)
	ds_read2_b32 v[136:137], v134 offset1:16
	v_and_b32_e32 v130, 16, v128
	v_ashrrev_i32_e32 v128, 2, v128
	s_lshl_b32 s38, s78, 1
	v_and_b32_e32 v128, -8, v128
	s_add_u32 s38, s2, s38
	v_add_u32_e32 v130, v128, v130
	s_waitcnt lgkmcnt(0)
	v_pk_mul_f32 v[126:127], v[126:127], v[136:137] op_sel_hi:[1,0]
	v_pk_mul_f32 v[124:125], v[124:125], v[136:137] op_sel_hi:[1,0]
	v_pk_mul_f32 v[122:123], v[122:123], v[136:137] op_sel_hi:[1,0]
	v_pk_mul_f32 v[120:121], v[120:121], v[136:137] op_sel_hi:[1,0]
	s_addc_u32 s39, s3, 0
	v_ashrrev_i32_e32 v131, 31, v130
	v_add_u32_e32 v128, s77, v135
	v_max_f32_e32 v124, 0, v124
	v_max_f32_e32 v125, 0, v125
	v_max_f32_e32 v126, 0, v126
	v_max_f32_e32 v127, 0, v127
	v_max_f32_e32 v120, 0, v120
	v_max_f32_e32 v121, 0, v121
	v_max_f32_e32 v122, 0, v122
	v_max_f32_e32 v123, 0, v123
	v_lshl_add_u64 v[130:131], v[130:131], 1, s[38:39]
	v_lshlrev_b64 v[138:139], 13, v[128:129]
	v_pk_mul_f32 v[126:127], v[126:127], v[126:127]
	v_pk_mul_f32 v[124:125], v[124:125], v[124:125]
	v_pk_mul_f32 v[140:141], v[122:123], v[122:123]
	v_pk_mul_f32 v[122:123], v[120:121], v[120:121]
	v_lshl_add_u64 v[138:139], v[130:131], 0, v[138:139]
	v_cvt_pk_bf16_f32 v120, v124, v125
	v_cvt_pk_bf16_f32 v121, v126, v127
	v_cvt_pk_bf16_f32 v122, v122, v123
	v_cvt_pk_bf16_f32 v123, v140, v141
	v_pk_mul_f32 v[118:119], v[118:119], v[136:137] op_sel_hi:[1,0]
	v_pk_mul_f32 v[116:117], v[116:117], v[136:137] op_sel_hi:[1,0]
	v_pk_mul_f32 v[114:115], v[114:115], v[136:137] op_sel_hi:[1,0]
	v_pk_mul_f32 v[112:113], v[112:113], v[136:137] op_sel_hi:[1,0]
	v_permlane16_swap_b32_e32 v120, v122
	v_permlane16_swap_b32_e32 v121, v123
	v_lshl_add_u64 v[124:125], v[138:139], 0, s[12:13]
	v_max_f32_e32 v116, 0, v116
	v_max_f32_e32 v117, 0, v117
	v_max_f32_e32 v118, 0, v118
	v_max_f32_e32 v119, 0, v119
	v_max_f32_e32 v112, 0, v112
	v_max_f32_e32 v113, 0, v113
	v_max_f32_e32 v114, 0, v114
	v_max_f32_e32 v115, 0, v115
	global_store_dwordx4 v[124:125], v[120:123], off sc1
	v_pk_mul_f32 v[118:119], v[118:119], v[118:119]
	v_pk_mul_f32 v[116:117], v[116:117], v[116:117]
	v_pk_mul_f32 v[120:121], v[114:115], v[114:115]
	v_pk_mul_f32 v[114:115], v[112:113], v[112:113]
	v_cvt_pk_bf16_f32 v112, v116, v117
	v_cvt_pk_bf16_f32 v113, v118, v119
	v_cvt_pk_bf16_f32 v114, v114, v115
	v_cvt_pk_bf16_f32 v115, v120, v121
	s_nop 0
	v_permlane16_swap_b32_e32 v112, v114
	v_permlane16_swap_b32_e32 v113, v115
	global_store_dwordx4 v[124:125], v[112:115], off offset:256 sc1
	s_add_i32 s76, s76, 1
	s_add_i32 s67, s67, s68
	v_mov_b32_e32 v114, v137
	v_pk_mul_f32 v[110:111], v[110:111], v[114:115] op_sel_hi:[1,0]
	v_pk_mul_f32 v[108:109], v[108:109], v[114:115] op_sel_hi:[1,0]
	v_pk_mul_f32 v[106:107], v[106:107], v[114:115] op_sel_hi:[1,0]
	v_pk_mul_f32 v[104:105], v[104:105], v[114:115] op_sel_hi:[1,0]
	v_add_u32_e32 v112, 16, v128
	v_mov_b32_e32 v113, v129
	v_max_f32_e32 v108, 0, v108
	v_max_f32_e32 v109, 0, v109
	v_max_f32_e32 v110, 0, v110
	v_max_f32_e32 v111, 0, v111
	v_max_f32_e32 v104, 0, v104
	v_max_f32_e32 v105, 0, v105
	v_max_f32_e32 v106, 0, v106
	v_max_f32_e32 v107, 0, v107
	v_lshlrev_b64 v[112:113], 13, v[112:113]
	v_pk_mul_f32 v[110:111], v[110:111], v[110:111]
	v_pk_mul_f32 v[108:109], v[108:109], v[108:109]
	v_pk_mul_f32 v[116:117], v[106:107], v[106:107]
	v_pk_mul_f32 v[106:107], v[104:105], v[104:105]
	v_lshl_add_u64 v[112:113], v[130:131], 0, v[112:113]
	v_cvt_pk_bf16_f32 v104, v108, v109
	v_cvt_pk_bf16_f32 v105, v110, v111
	v_cvt_pk_bf16_f32 v106, v106, v107
	v_cvt_pk_bf16_f32 v107, v116, v117
	v_pk_mul_f32 v[102:103], v[102:103], v[114:115] op_sel_hi:[1,0]
	v_pk_mul_f32 v[100:101], v[100:101], v[114:115] op_sel_hi:[1,0]
	v_pk_mul_f32 v[98:99], v[98:99], v[114:115] op_sel_hi:[1,0]
	v_pk_mul_f32 v[96:97], v[96:97], v[114:115] op_sel_hi:[1,0]
	v_permlane16_swap_b32_e32 v104, v106
	v_permlane16_swap_b32_e32 v105, v107
	v_lshl_add_u64 v[108:109], v[112:113], 0, s[12:13]
	v_max_f32_e32 v100, 0, v100
	v_max_f32_e32 v101, 0, v101
	v_max_f32_e32 v102, 0, v102
	v_max_f32_e32 v103, 0, v103
	v_max_f32_e32 v96, 0, v96
	v_max_f32_e32 v97, 0, v97
	v_max_f32_e32 v98, 0, v98
	v_max_f32_e32 v99, 0, v99
	global_store_dwordx4 v[108:109], v[104:107], off sc1
	v_pk_mul_f32 v[102:103], v[102:103], v[102:103]
	v_pk_mul_f32 v[100:101], v[100:101], v[100:101]
	v_pk_mul_f32 v[104:105], v[98:99], v[98:99]
	v_pk_mul_f32 v[98:99], v[96:97], v[96:97]
	v_cvt_pk_bf16_f32 v96, v100, v101
	v_cvt_pk_bf16_f32 v97, v102, v103
	v_cvt_pk_bf16_f32 v98, v98, v99
	v_cvt_pk_bf16_f32 v99, v104, v105
	s_nop 0
	v_permlane16_swap_b32_e32 v96, v98
	v_permlane16_swap_b32_e32 v97, v99
	global_store_dwordx4 v[108:109], v[96:99], off offset:256 sc1
	ds_read2_b32 v[96:97], v134 offset0:32 offset1:48
	s_andn2_b64 vcc, exec, s[36:37]
	v_add_u32_e32 v98, 32, v128
	v_mov_b32_e32 v99, v129
	v_lshlrev_b64 v[98:99], 13, v[98:99]
	s_waitcnt lgkmcnt(0)
; __device__ __forceinline__ u32x2 pack4(f32x4 v) { u32x2 r; r.x = cvt_pk(v[0], v[1]); r.y = cvt_pk(v[2], v[3]); return r; }
; __device__ __forceinline__ void phaseF(const Params& p, const int wv, const int rep) {
;     ...
;       const float* rs_c = rs_l + (it & 1) * 256;
;       ACC_FOREACH_PAIR({
;         const float rstd = rs_c[rrow];
;         f32x4 o0 = v0 * rstd, o1 = v1 * rstd;
;         o0[0] = fmaxf(o0[0], 0.f); o0[1] = fmaxf(o0[1], 0.f); o0[2] = fmaxf(o0[2], 0.f); o0[3] = fmaxf(o0[3], 0.f);
;         o1[0] = fmaxf(o1[0], 0.f); o1[1] = fmaxf(o1[1], 0.f); o1[2] = fmaxf(o1[2], 0.f); o1[3] = fmaxf(o1[3], 0.f);
;         o0 = o0 * o0; o1 = o1 * o1;
;         store_pair16(ACT + (size_t)(brow + rrow) * 4096 + bcol + cb32, pack4(o0), pack4(o1), fq);
;       });
	v_pk_mul_f32 v[94:95], v[94:95], v[96:97] op_sel_hi:[1,0]
	v_pk_mul_f32 v[92:93], v[92:93], v[96:97] op_sel_hi:[1,0]
	v_pk_mul_f32 v[90:91], v[90:91], v[96:97] op_sel_hi:[1,0]
	v_pk_mul_f32 v[88:89], v[88:89], v[96:97] op_sel_hi:[1,0]
	v_max_f32_e32 v92, 0, v92
	v_max_f32_e32 v93, 0, v93
	v_max_f32_e32 v94, 0, v94
	v_max_f32_e32 v95, 0, v95
	v_max_f32_e32 v88, 0, v88
	v_max_f32_e32 v89, 0, v89
	v_max_f32_e32 v90, 0, v90
	v_max_f32_e32 v91, 0, v91
	v_pk_mul_f32 v[94:95], v[94:95], v[94:95]
	v_pk_mul_f32 v[92:93], v[92:93], v[92:93]
	v_pk_mul_f32 v[100:101], v[90:91], v[90:91]
	v_pk_mul_f32 v[90:91], v[88:89], v[88:89]
	v_lshl_add_u64 v[98:99], v[130:131], 0, v[98:99]
	v_cvt_pk_bf16_f32 v88, v92, v93
	v_cvt_pk_bf16_f32 v89, v94, v95
	v_cvt_pk_bf16_f32 v90, v90, v91
	v_cvt_pk_bf16_f32 v91, v100, v101
	v_pk_mul_f32 v[86:87], v[86:87], v[96:97] op_sel_hi:[1,0]
	v_pk_mul_f32 v[84:85], v[84:85], v[96:97] op_sel_hi:[1,0]
	v_pk_mul_f32 v[82:83], v[82:83], v[96:97] op_sel_hi:[1,0]
	v_pk_mul_f32 v[80:81], v[80:81], v[96:97] op_sel_hi:[1,0]
	v_permlane16_swap_b32_e32 v88, v90
	v_permlane16_swap_b32_e32 v89, v91
	v_lshl_add_u64 v[92:93], v[98:99], 0, s[12:13]
	v_max_f32_e32 v84, 0, v84
	v_max_f32_e32 v85, 0, v85
	v_max_f32_e32 v86, 0, v86
	v_max_f32_e32 v87, 0, v87
	v_max_f32_e32 v80, 0, v80
	v_max_f32_e32 v81, 0, v81
	v_max_f32_e32 v82, 0, v82
	v_max_f32_e32 v83, 0, v83
	global_store_dwordx4 v[92:93], v[88:91], off sc1
	v_pk_mul_f32 v[86:87], v[86:87], v[86:87]
	v_pk_mul_f32 v[84:85], v[84:85], v[84:85]
	v_pk_mul_f32 v[88:89], v[82:83], v[82:83]
	v_pk_mul_f32 v[82:83], v[80:81], v[80:81]
	v_cvt_pk_bf16_f32 v80, v84, v85
	v_cvt_pk_bf16_f32 v81, v86, v87
	v_cvt_pk_bf16_f32 v82, v82, v83
	v_cvt_pk_bf16_f32 v83, v88, v89
	s_nop 0
	v_permlane16_swap_b32_e32 v80, v82
	v_permlane16_swap_b32_e32 v81, v83
	global_store_dwordx4 v[92:93], v[80:83], off offset:256 sc1
	s_add_i32 s69, s69, s70
	s_nop 0
	v_mov_b32_e32 v82, v97
	v_pk_mul_f32 v[78:79], v[78:79], v[82:83] op_sel_hi:[1,0]
	v_pk_mul_f32 v[76:77], v[76:77], v[82:83] op_sel_hi:[1,0]
	v_pk_mul_f32 v[74:75], v[74:75], v[82:83] op_sel_hi:[1,0]
	v_pk_mul_f32 v[72:73], v[72:73], v[82:83] op_sel_hi:[1,0]
	v_add_u32_e32 v80, 48, v128
	v_mov_b32_e32 v81, v129
	v_max_f32_e32 v76, 0, v76
	v_max_f32_e32 v77, 0, v77
	v_max_f32_e32 v78, 0, v78
	v_max_f32_e32 v79, 0, v79
	v_max_f32_e32 v72, 0, v72
	v_max_f32_e32 v73, 0, v73
	v_max_f32_e32 v74, 0, v74
	v_max_f32_e32 v75, 0, v75
	v_lshlrev_b64 v[80:81], 13, v[80:81]
	v_pk_mul_f32 v[78:79], v[78:79], v[78:79]
	v_pk_mul_f32 v[76:77], v[76:77], v[76:77]
	v_pk_mul_f32 v[84:85], v[74:75], v[74:75]
	v_pk_mul_f32 v[74:75], v[72:73], v[72:73]
	v_lshl_add_u64 v[80:81], v[130:131], 0, v[80:81]
	v_cvt_pk_bf16_f32 v72, v76, v77
	v_cvt_pk_bf16_f32 v73, v78, v79
	v_cvt_pk_bf16_f32 v74, v74, v75
	v_cvt_pk_bf16_f32 v75, v84, v85
	v_pk_mul_f32 v[70:71], v[70:71], v[82:83] op_sel_hi:[1,0]
	v_pk_mul_f32 v[68:69], v[68:69], v[82:83] op_sel_hi:[1,0]
	v_pk_mul_f32 v[66:67], v[66:67], v[82:83] op_sel_hi:[1,0]
	v_pk_mul_f32 v[64:65], v[64:65], v[82:83] op_sel_hi:[1,0]
	v_permlane16_swap_b32_e32 v72, v74
	v_permlane16_swap_b32_e32 v73, v75
	v_lshl_add_u64 v[76:77], v[80:81], 0, s[12:13]
	v_max_f32_e32 v68, 0, v68
	v_max_f32_e32 v69, 0, v69
	v_max_f32_e32 v70, 0, v70
	v_max_f32_e32 v71, 0, v71
	v_max_f32_e32 v64, 0, v64
	v_max_f32_e32 v65, 0, v65
	v_max_f32_e32 v66, 0, v66
	v_max_f32_e32 v67, 0, v67
	global_store_dwordx4 v[76:77], v[72:75], off sc1
	v_pk_mul_f32 v[70:71], v[70:71], v[70:71]
	v_pk_mul_f32 v[68:69], v[68:69], v[68:69]
	v_pk_mul_f32 v[72:73], v[66:67], v[66:67]
	v_pk_mul_f32 v[66:67], v[64:65], v[64:65]
	v_cvt_pk_bf16_f32 v64, v68, v69
	v_cvt_pk_bf16_f32 v65, v70, v71
	v_cvt_pk_bf16_f32 v66, v66, v67
	v_cvt_pk_bf16_f32 v67, v72, v73
	s_nop 0
	v_permlane16_swap_b32_e32 v64, v66
	v_permlane16_swap_b32_e32 v65, v67
	global_store_dwordx4 v[76:77], v[64:67], off offset:256 sc1
	ds_read2_b32 v[64:65], v134 offset0:128 offset1:144
	s_waitcnt lgkmcnt(0)
	v_pk_mul_f32 v[62:63], v[62:63], v[64:65] op_sel_hi:[1,0]
	v_pk_mul_f32 v[60:61], v[60:61], v[64:65] op_sel_hi:[1,0]
	v_pk_mul_f32 v[58:59], v[58:59], v[64:65] op_sel_hi:[1,0]
	v_pk_mul_f32 v[56:57], v[56:57], v[64:65] op_sel_hi:[1,0]
	v_add_u32_e32 v66, 0x80, v128
	v_mov_b32_e32 v67, v129
	v_max_f32_e32 v60, 0, v60
	v_max_f32_e32 v61, 0, v61
	v_max_f32_e32 v62, 0, v62
	v_max_f32_e32 v63, 0, v63
	v_max_f32_e32 v56, 0, v56
	v_max_f32_e32 v57, 0, v57
	v_max_f32_e32 v58, 0, v58
	v_max_f32_e32 v59, 0, v59
	v_lshlrev_b64 v[66:67], 13, v[66:67]
	v_pk_mul_f32 v[62:63], v[62:63], v[62:63]
	v_pk_mul_f32 v[60:61], v[60:61], v[60:61]
	v_pk_mul_f32 v[68:69], v[58:59], v[58:59]
	v_pk_mul_f32 v[58:59], v[56:57], v[56:57]
	v_lshl_add_u64 v[66:67], v[130:131], 0, v[66:67]
	v_cvt_pk_bf16_f32 v56, v60, v61
	v_cvt_pk_bf16_f32 v57, v62, v63
	v_cvt_pk_bf16_f32 v58, v58, v59
	v_cvt_pk_bf16_f32 v59, v68, v69
	v_pk_mul_f32 v[54:55], v[54:55], v[64:65] op_sel_hi:[1,0]
	v_pk_mul_f32 v[52:53], v[52:53], v[64:65] op_sel_hi:[1,0]
	v_pk_mul_f32 v[50:51], v[50:51], v[64:65] op_sel_hi:[1,0]
	v_pk_mul_f32 v[48:49], v[48:49], v[64:65] op_sel_hi:[1,0]
	v_permlane16_swap_b32_e32 v56, v58
	v_permlane16_swap_b32_e32 v57, v59
	v_lshl_add_u64 v[60:61], v[66:67], 0, s[12:13]
	v_max_f32_e32 v52, 0, v52
	v_max_f32_e32 v53, 0, v53
	v_max_f32_e32 v54, 0, v54
	v_max_f32_e32 v55, 0, v55
	v_max_f32_e32 v48, 0, v48
	v_max_f32_e32 v49, 0, v49
	v_max_f32_e32 v50, 0, v50
	v_max_f32_e32 v51, 0, v51
	global_store_dwordx4 v[60:61], v[56:59], off sc1
	v_pk_mul_f32 v[54:55], v[54:55], v[54:55]
	v_pk_mul_f32 v[52:53], v[52:53], v[52:53]
	v_pk_mul_f32 v[56:57], v[50:51], v[50:51]
; __device__ __forceinline__ u32x2 pack4(f32x4 v) { u32x2 r; r.x = cvt_pk(v[0], v[1]); r.y = cvt_pk(v[2], v[3]); return r; }
; __device__ __forceinline__ void phaseF(const Params& p, const int wv, const int rep) {
;     ...
;       const float* rs_c = rs_l + (it & 1) * 256;
;       ACC_FOREACH_PAIR({
;         const float rstd = rs_c[rrow];
;         f32x4 o0 = v0 * rstd, o1 = v1 * rstd;
;         o0[0] = fmaxf(o0[0], 0.f); o0[1] = fmaxf(o0[1], 0.f); o0[2] = fmaxf(o0[2], 0.f); o0[3] = fmaxf(o0[3], 0.f);
;         o1[0] = fmaxf(o1[0], 0.f); o1[1] = fmaxf(o1[1], 0.f); o1[2] = fmaxf(o1[2], 0.f); o1[3] = fmaxf(o1[3], 0.f);
;         o0 = o0 * o0; o1 = o1 * o1;
;         store_pair16(ACT + (size_t)(brow + rrow) * 4096 + bcol + cb32, pack4(o0), pack4(o1), fq);
;       });
	v_pk_mul_f32 v[50:51], v[48:49], v[48:49]
	v_cvt_pk_bf16_f32 v48, v52, v53
	v_cvt_pk_bf16_f32 v49, v54, v55
	v_cvt_pk_bf16_f32 v50, v50, v51
	v_cvt_pk_bf16_f32 v51, v56, v57
	s_nop 0
	v_permlane16_swap_b32_e32 v48, v50
	v_permlane16_swap_b32_e32 v49, v51
	global_store_dwordx4 v[60:61], v[48:51], off offset:256 sc1
	s_nop 1
	v_mov_b32_e32 v50, v65
	v_pk_mul_f32 v[46:47], v[46:47], v[50:51] op_sel_hi:[1,0]
	v_pk_mul_f32 v[44:45], v[44:45], v[50:51] op_sel_hi:[1,0]
	v_pk_mul_f32 v[42:43], v[42:43], v[50:51] op_sel_hi:[1,0]
	v_pk_mul_f32 v[40:41], v[40:41], v[50:51] op_sel_hi:[1,0]
	v_add_u32_e32 v48, 0x90, v128
	v_mov_b32_e32 v49, v129
	v_max_f32_e32 v44, 0, v44
	v_max_f32_e32 v45, 0, v45
	v_max_f32_e32 v46, 0, v46
	v_max_f32_e32 v47, 0, v47
	v_max_f32_e32 v40, 0, v40
	v_max_f32_e32 v41, 0, v41
	v_max_f32_e32 v42, 0, v42
	v_max_f32_e32 v43, 0, v43
	v_lshlrev_b64 v[48:49], 13, v[48:49]
	v_pk_mul_f32 v[46:47], v[46:47], v[46:47]
	v_pk_mul_f32 v[44:45], v[44:45], v[44:45]
	v_pk_mul_f32 v[52:53], v[42:43], v[42:43]
	v_pk_mul_f32 v[42:43], v[40:41], v[40:41]
	v_lshl_add_u64 v[48:49], v[130:131], 0, v[48:49]
	v_cvt_pk_bf16_f32 v40, v44, v45
	v_cvt_pk_bf16_f32 v41, v46, v47
	v_cvt_pk_bf16_f32 v42, v42, v43
	v_cvt_pk_bf16_f32 v43, v52, v53
	v_pk_mul_f32 v[38:39], v[38:39], v[50:51] op_sel_hi:[1,0]
	v_pk_mul_f32 v[36:37], v[36:37], v[50:51] op_sel_hi:[1,0]
	v_pk_mul_f32 v[34:35], v[34:35], v[50:51] op_sel_hi:[1,0]
	v_pk_mul_f32 v[32:33], v[32:33], v[50:51] op_sel_hi:[1,0]
	v_permlane16_swap_b32_e32 v40, v42
	v_permlane16_swap_b32_e32 v41, v43
	v_lshl_add_u64 v[44:45], v[48:49], 0, s[12:13]
	v_max_f32_e32 v36, 0, v36
	v_max_f32_e32 v37, 0, v37
	v_max_f32_e32 v38, 0, v38
	v_max_f32_e32 v39, 0, v39
	v_max_f32_e32 v32, 0, v32
	v_max_f32_e32 v33, 0, v33
	v_max_f32_e32 v34, 0, v34
	v_max_f32_e32 v35, 0, v35
	global_store_dwordx4 v[44:45], v[40:43], off sc1
	v_pk_mul_f32 v[38:39], v[38:39], v[38:39]
	v_pk_mul_f32 v[36:37], v[36:37], v[36:37]
	v_pk_mul_f32 v[40:41], v[34:35], v[34:35]
	v_pk_mul_f32 v[34:35], v[32:33], v[32:33]
	v_cvt_pk_bf16_f32 v32, v36, v37
	v_cvt_pk_bf16_f32 v33, v38, v39
	v_cvt_pk_bf16_f32 v34, v34, v35
	v_cvt_pk_bf16_f32 v35, v40, v41
	s_nop 0
	v_permlane16_swap_b32_e32 v32, v34
	v_permlane16_swap_b32_e32 v33, v35
	global_store_dwordx4 v[44:45], v[32:35], off offset:256 sc1
	ds_read2_b32 v[32:33], v134 offset0:160 offset1:176
	s_waitcnt lgkmcnt(0)
	v_pk_mul_f32 v[30:31], v[30:31], v[32:33] op_sel_hi:[1,0]
	v_pk_mul_f32 v[28:29], v[28:29], v[32:33] op_sel_hi:[1,0]
	v_pk_mul_f32 v[26:27], v[26:27], v[32:33] op_sel_hi:[1,0]
	v_pk_mul_f32 v[24:25], v[24:25], v[32:33] op_sel_hi:[1,0]
	v_add_u32_e32 v34, 0xa0, v128
	v_mov_b32_e32 v35, v129
	v_max_f32_e32 v28, 0, v28
	v_max_f32_e32 v29, 0, v29
	v_max_f32_e32 v30, 0, v30
	v_max_f32_e32 v31, 0, v31
	v_max_f32_e32 v24, 0, v24
	v_max_f32_e32 v25, 0, v25
	v_max_f32_e32 v26, 0, v26
	v_max_f32_e32 v27, 0, v27
	v_lshlrev_b64 v[34:35], 13, v[34:35]
	v_pk_mul_f32 v[30:31], v[30:31], v[30:31]
	v_pk_mul_f32 v[28:29], v[28:29], v[28:29]
	v_pk_mul_f32 v[36:37], v[26:27], v[26:27]
	v_pk_mul_f32 v[26:27], v[24:25], v[24:25]
	v_lshl_add_u64 v[34:35], v[130:131], 0, v[34:35]
	v_cvt_pk_bf16_f32 v24, v28, v29
	v_cvt_pk_bf16_f32 v25, v30, v31
	v_cvt_pk_bf16_f32 v26, v26, v27
	v_cvt_pk_bf16_f32 v27, v36, v37
	v_pk_mul_f32 v[22:23], v[22:23], v[32:33] op_sel_hi:[1,0]
	v_pk_mul_f32 v[20:21], v[20:21], v[32:33] op_sel_hi:[1,0]
	v_pk_mul_f32 v[18:19], v[18:19], v[32:33] op_sel_hi:[1,0]
	v_pk_mul_f32 v[16:17], v[16:17], v[32:33] op_sel_hi:[1,0]
	v_permlane16_swap_b32_e32 v24, v26
	v_permlane16_swap_b32_e32 v25, v27
	v_lshl_add_u64 v[28:29], v[34:35], 0, s[12:13]
	v_max_f32_e32 v20, 0, v20
	v_max_f32_e32 v21, 0, v21
	v_max_f32_e32 v22, 0, v22
	v_max_f32_e32 v23, 0, v23
	v_max_f32_e32 v16, 0, v16
	v_max_f32_e32 v17, 0, v17
	v_max_f32_e32 v18, 0, v18
	v_max_f32_e32 v19, 0, v19
	global_store_dwordx4 v[28:29], v[24:27], off sc1
	v_pk_mul_f32 v[22:23], v[22:23], v[22:23]
	v_pk_mul_f32 v[20:21], v[20:21], v[20:21]
	v_pk_mul_f32 v[24:25], v[18:19], v[18:19]
	v_pk_mul_f32 v[18:19], v[16:17], v[16:17]
	v_cvt_pk_bf16_f32 v16, v20, v21
	v_cvt_pk_bf16_f32 v17, v22, v23
	v_cvt_pk_bf16_f32 v18, v18, v19
	v_cvt_pk_bf16_f32 v19, v24, v25
	s_nop 0
	v_permlane16_swap_b32_e32 v16, v18
	v_permlane16_swap_b32_e32 v17, v19
	global_store_dwordx4 v[28:29], v[16:19], off offset:256 sc1
	v_add_u32_e32 v128, 0xb0, v128
	s_nop 0
	v_mov_b32_e32 v18, v33
	v_pk_mul_f32 v[14:15], v[14:15], v[18:19] op_sel_hi:[1,0]
	v_pk_mul_f32 v[12:13], v[12:13], v[18:19] op_sel_hi:[1,0]
	v_pk_mul_f32 v[10:11], v[10:11], v[18:19] op_sel_hi:[1,0]
	v_pk_mul_f32 v[8:9], v[8:9], v[18:19] op_sel_hi:[1,0]
	v_max_f32_e32 v12, 0, v12
	v_max_f32_e32 v13, 0, v13
	v_max_f32_e32 v14, 0, v14
	v_max_f32_e32 v15, 0, v15
	v_max_f32_e32 v8, 0, v8
	v_max_f32_e32 v9, 0, v9
	v_max_f32_e32 v10, 0, v10
	v_max_f32_e32 v11, 0, v11
	v_lshlrev_b64 v[16:17], 13, v[128:129]
	v_pk_mul_f32 v[14:15], v[14:15], v[14:15]
	v_pk_mul_f32 v[12:13], v[12:13], v[12:13]
	v_pk_mul_f32 v[20:21], v[10:11], v[10:11]
	v_pk_mul_f32 v[10:11], v[8:9], v[8:9]
	v_lshl_add_u64 v[16:17], v[130:131], 0, v[16:17]
	v_cvt_pk_bf16_f32 v8, v12, v13
	v_cvt_pk_bf16_f32 v9, v14, v15
	v_cvt_pk_bf16_f32 v10, v10, v11
	v_cvt_pk_bf16_f32 v11, v20, v21
	v_pk_mul_f32 v[6:7], v[6:7], v[18:19] op_sel_hi:[1,0]
	v_pk_mul_f32 v[4:5], v[4:5], v[18:19] op_sel_hi:[1,0]
	v_pk_mul_f32 v[2:3], v[2:3], v[18:19] op_sel_hi:[1,0]
	v_pk_mul_f32 v[0:1], v[0:1], v[18:19] op_sel_hi:[1,0]
	v_permlane16_swap_b32_e32 v8, v10
	v_permlane16_swap_b32_e32 v9, v11
	v_lshl_add_u64 v[12:13], v[16:17], 0, s[12:13]
	v_max_f32_e32 v4, 0, v4
	v_max_f32_e32 v5, 0, v5
	v_max_f32_e32 v6, 0, v6
	v_max_f32_e32 v7, 0, v7
	v_max_f32_e32 v0, 0, v0
	v_max_f32_e32 v1, 0, v1
	v_max_f32_e32 v2, 0, v2
	v_max_f32_e32 v3, 0, v3
	global_store_dwordx4 v[12:13], v[8:11], off sc1
	v_pk_mul_f32 v[6:7], v[6:7], v[6:7]
	v_pk_mul_f32 v[4:5], v[4:5], v[4:5]
	v_pk_mul_f32 v[8:9], v[2:3], v[2:3]
	v_pk_mul_f32 v[2:3], v[0:1], v[0:1]
	v_cvt_pk_bf16_f32 v0, v4, v5
	v_cvt_pk_bf16_f32 v1, v6, v7
	v_cvt_pk_bf16_f32 v2, v2, v3
	v_cvt_pk_bf16_f32 v3, v8, v9
	s_nop 0
	v_permlane16_swap_b32_e32 v0, v2
	v_permlane16_swap_b32_e32 v1, v3
	global_store_dwordx4 v[12:13], v[0:3], off offset:256 sc1
	s_cbranch_vccz .LBB0_1075

; __device__ __forceinline__ void phaseG(const Params& p, const int wv, const int rep, unsigned* bar, const bool fused) {
;     ...
;       ACC_FOREACH({
;         const float rs = rstd_l[rrow];
;         const f32x4 wv4 = *(const f32x4*)(wfin + bcol + rcol);
;         *(f32x4*)(p.out + O_Y + (size_t)(brow + rrow) * 1024 + bcol + rcol) = v * rs * wv4;
;       });
.LBB0_1134:
	s_or_b64 exec, exec, s[42:43]
	s_waitcnt lgkmcnt(0)
	s_barrier
	v_mbcnt_lo_u32_b32 v128, -1, 0
	v_mbcnt_hi_u32_b32 v128, -1, v128
	s_lshl_b32 s18, s86, 2
	v_ashrrev_i32_e32 v8, 2, v128
	v_and_b32_e32 v8, -4, v8
	v_add_u32_e32 v8, s74, v8
	s_add_u32 s4, s46, s18
	v_ashrrev_i32_e32 v9, 31, v8
	s_addc_u32 s5, s47, 0
	v_lshlrev_b64 v[10:11], 2, v[8:9]
	v_lshl_add_u64 v[8:9], s[4:5], 0, v[10:11]
	global_load_dwordx4 v[12:15], v[8:9], off
	v_and_or_b32 v128, v128, 15, s65
	v_lshl_add_u32 v138, v128, 2, 16
	v_add_u32_e32 v144, 0x1000, v138
	ds_read2_b32 v[138:139], v144 offset1:16
	v_add_u32_e32 v128, s87, v128
	v_lshlrev_b64 v[142:143], 12, v[128:129]
	v_lshl_add_u64 v[142:143], s[48:49], 0, v[142:143]
	v_lshl_add_u64 v[142:143], v[142:143], 0, s[18:19]
	s_waitcnt lgkmcnt(0)
	v_pk_mul_f32 v[134:135], v[134:135], v[138:139] op_sel_hi:[1,0]
	v_pk_mul_f32 v[136:137], v[136:137], v[138:139] op_sel_hi:[1,0]
	v_lshl_add_u64 v[142:143], v[142:143], 0, v[10:11]
	v_pk_mul_f32 v[130:131], v[130:131], v[138:139] op_sel_hi:[1,0]
	v_pk_mul_f32 v[132:133], v[132:133], v[138:139] op_sel_hi:[1,0]
	v_pk_mul_f32 v[116:117], v[116:117], v[138:139] op_sel_hi:[1,0]
	v_pk_mul_f32 v[118:119], v[118:119], v[138:139] op_sel_hi:[1,0]
	v_pk_mul_f32 v[112:113], v[112:113], v[138:139] op_sel_hi:[1,0]
	v_pk_mul_f32 v[114:115], v[114:115], v[138:139] op_sel_hi:[1,0]
	s_waitcnt vmcnt(0)
	v_pk_mul_f32 v[12:13], v[12:13], v[136:137]
	v_pk_mul_f32 v[14:15], v[14:15], v[134:135]
	global_store_dwordx4 v[142:143], v[12:15], off sc1
	global_load_dwordx4 v[12:15], v[8:9], off offset:64
	s_waitcnt vmcnt(0)
	v_pk_mul_f32 v[12:13], v[12:13], v[132:133]
	v_pk_mul_f32 v[14:15], v[14:15], v[130:131]
	global_store_dwordx4 v[142:143], v[12:15], off offset:64 sc1
	global_load_dwordx4 v[12:15], v[8:9], off offset:512
	s_waitcnt vmcnt(0)
	v_pk_mul_f32 v[12:13], v[12:13], v[118:119]
	v_pk_mul_f32 v[14:15], v[14:15], v[116:117]
	global_store_dwordx4 v[142:143], v[12:15], off offset:512 sc1
	global_load_dwordx4 v[12:15], v[8:9], off offset:576
	s_waitcnt vmcnt(0)
	v_pk_mul_f32 v[12:13], v[12:13], v[114:115]
	v_pk_mul_f32 v[14:15], v[14:15], v[112:113]
	global_store_dwordx4 v[142:143], v[12:15], off offset:576 sc1
	global_load_dwordx4 v[12:15], v[8:9], off
	v_mov_b32_e32 v113, v129
	v_add_u32_e32 v112, 16, v128
	v_lshlrev_b64 v[112:113], 12, v[112:113]
	v_lshl_add_u64 v[112:113], s[48:49], 0, v[112:113]
	v_mov_b32_e32 v114, v139
	v_lshl_add_u64 v[112:113], v[112:113], 0, s[18:19]
	v_pk_mul_f32 v[116:117], v[124:125], v[114:115] op_sel_hi:[1,0]
	v_pk_mul_f32 v[118:119], v[126:127], v[114:115] op_sel_hi:[1,0]
	v_lshl_add_u64 v[112:113], v[112:113], 0, v[10:11]
	v_pk_mul_f32 v[100:101], v[100:101], v[114:115] op_sel_hi:[1,0]
	v_pk_mul_f32 v[102:103], v[102:103], v[114:115] op_sel_hi:[1,0]
	v_pk_mul_f32 v[96:97], v[96:97], v[114:115] op_sel_hi:[1,0]
	v_pk_mul_f32 v[98:99], v[98:99], v[114:115] op_sel_hi:[1,0]
	s_waitcnt vmcnt(0)
	v_pk_mul_f32 v[12:13], v[12:13], v[118:119]
	v_pk_mul_f32 v[14:15], v[14:15], v[116:117]
	global_store_dwordx4 v[112:113], v[12:15], off sc1
	global_load_dwordx4 v[12:15], v[8:9], off offset:64
	v_pk_mul_f32 v[116:117], v[120:121], v[114:115] op_sel_hi:[1,0]
	v_pk_mul_f32 v[118:119], v[122:123], v[114:115] op_sel_hi:[1,0]
	s_waitcnt vmcnt(0)
	v_pk_mul_f32 v[14:15], v[14:15], v[116:117]
	v_pk_mul_f32 v[12:13], v[12:13], v[118:119]
	global_store_dwordx4 v[112:113], v[12:15], off offset:64 sc1
	global_load_dwordx4 v[12:15], v[8:9], off offset:512
	s_waitcnt vmcnt(0)
	v_pk_mul_f32 v[12:13], v[12:13], v[102:103]
	v_pk_mul_f32 v[14:15], v[14:15], v[100:101]
	global_store_dwordx4 v[112:113], v[12:15], off offset:512 sc1
	global_load_dwordx4 v[12:15], v[8:9], off offset:576
	s_waitcnt vmcnt(0)
	v_pk_mul_f32 v[12:13], v[12:13], v[98:99]
	v_pk_mul_f32 v[14:15], v[14:15], v[96:97]
	global_store_dwordx4 v[112:113], v[12:15], off offset:576 sc1
	global_load_dwordx4 v[12:15], v[8:9], off
	ds_read2_b32 v[98:99], v144 offset0:32 offset1:48
	v_mov_b32_e32 v97, v129
	v_add_u32_e32 v96, 32, v128
	v_lshlrev_b64 v[96:97], 12, v[96:97]
	v_lshl_add_u64 v[96:97], s[48:49], 0, v[96:97]
	v_lshl_add_u64 v[96:97], v[96:97], 0, s[18:19]
	s_waitcnt lgkmcnt(0)
	v_pk_mul_f32 v[100:101], v[110:111], v[98:99] op_sel_hi:[1,0]
	v_pk_mul_f32 v[102:103], v[108:109], v[98:99] op_sel_hi:[1,0]
	v_lshl_add_u64 v[96:97], v[96:97], 0, v[10:11]
	v_pk_mul_f32 v[84:85], v[84:85], v[98:99] op_sel_hi:[1,0]
	v_pk_mul_f32 v[86:87], v[86:87], v[98:99] op_sel_hi:[1,0]
	v_pk_mul_f32 v[80:81], v[80:81], v[98:99] op_sel_hi:[1,0]
	v_pk_mul_f32 v[82:83], v[82:83], v[98:99] op_sel_hi:[1,0]
	s_waitcnt vmcnt(0)
	v_pk_mul_f32 v[14:15], v[14:15], v[102:103]
	v_pk_mul_f32 v[12:13], v[12:13], v[100:101]
	global_store_dwordx4 v[96:97], v[12:15], off sc1
	global_load_dwordx4 v[12:15], v[8:9], off offset:64
	v_pk_mul_f32 v[100:101], v[104:105], v[98:99] op_sel_hi:[1,0]
	v_pk_mul_f32 v[102:103], v[106:107], v[98:99] op_sel_hi:[1,0]
	s_waitcnt vmcnt(0)
	v_pk_mul_f32 v[14:15], v[14:15], v[100:101]
	v_pk_mul_f32 v[12:13], v[12:13], v[102:103]
	global_store_dwordx4 v[96:97], v[12:15], off offset:64 sc1
	global_load_dwordx4 v[12:15], v[8:9], off offset:512
	s_waitcnt vmcnt(0)
	v_pk_mul_f32 v[12:13], v[12:13], v[86:87]
	v_pk_mul_f32 v[14:15], v[14:15], v[84:85]
	global_store_dwordx4 v[96:97], v[12:15], off offset:512 sc1
	global_load_dwordx4 v[12:15], v[8:9], off offset:576
	s_waitcnt vmcnt(0)
; __device__ __forceinline__ void phaseG(const Params& p, const int wv, const int rep, unsigned* bar, const bool fused) {
;     ...
;       ACC_FOREACH({
;         const float rs = rstd_l[rrow];
;         const f32x4 wv4 = *(const f32x4*)(wfin + bcol + rcol);
;         *(f32x4*)(p.out + O_Y + (size_t)(brow + rrow) * 1024 + bcol + rcol) = v * rs * wv4;
;       });
	v_pk_mul_f32 v[12:13], v[12:13], v[82:83]
	v_pk_mul_f32 v[14:15], v[14:15], v[80:81]
	global_store_dwordx4 v[96:97], v[12:15], off offset:576 sc1
	global_load_dwordx4 v[12:15], v[8:9], off
	v_mov_b32_e32 v81, v129
	v_add_u32_e32 v80, 48, v128
	v_lshlrev_b64 v[80:81], 12, v[80:81]
	v_lshl_add_u64 v[80:81], s[48:49], 0, v[80:81]
	v_mov_b32_e32 v82, v99
	v_lshl_add_u64 v[80:81], v[80:81], 0, s[18:19]
	v_pk_mul_f32 v[84:85], v[94:95], v[82:83] op_sel_hi:[1,0]
	v_pk_mul_f32 v[86:87], v[92:93], v[82:83] op_sel_hi:[1,0]
	v_lshl_add_u64 v[80:81], v[80:81], 0, v[10:11]
	v_pk_mul_f32 v[68:69], v[68:69], v[82:83] op_sel_hi:[1,0]
	v_pk_mul_f32 v[70:71], v[70:71], v[82:83] op_sel_hi:[1,0]
	v_pk_mul_f32 v[64:65], v[64:65], v[82:83] op_sel_hi:[1,0]
	v_pk_mul_f32 v[66:67], v[66:67], v[82:83] op_sel_hi:[1,0]
	s_waitcnt vmcnt(0)
	v_pk_mul_f32 v[14:15], v[14:15], v[86:87]
	v_pk_mul_f32 v[12:13], v[12:13], v[84:85]
	global_store_dwordx4 v[80:81], v[12:15], off sc1
	global_load_dwordx4 v[12:15], v[8:9], off offset:64
	v_pk_mul_f32 v[84:85], v[88:89], v[82:83] op_sel_hi:[1,0]
	v_pk_mul_f32 v[86:87], v[90:91], v[82:83] op_sel_hi:[1,0]
	s_waitcnt vmcnt(0)
	v_pk_mul_f32 v[14:15], v[14:15], v[84:85]
	v_pk_mul_f32 v[12:13], v[12:13], v[86:87]
	global_store_dwordx4 v[80:81], v[12:15], off offset:64 sc1
	global_load_dwordx4 v[12:15], v[8:9], off offset:512
	s_waitcnt vmcnt(0)
	v_pk_mul_f32 v[12:13], v[12:13], v[70:71]
	v_pk_mul_f32 v[14:15], v[14:15], v[68:69]
	global_store_dwordx4 v[80:81], v[12:15], off offset:512 sc1
	global_load_dwordx4 v[12:15], v[8:9], off offset:576
	s_waitcnt vmcnt(0)
	v_pk_mul_f32 v[12:13], v[12:13], v[66:67]
	v_pk_mul_f32 v[14:15], v[14:15], v[64:65]
	global_store_dwordx4 v[80:81], v[12:15], off offset:576 sc1
	global_load_dwordx4 v[12:15], v[8:9], off
	ds_read2_b32 v[66:67], v144 offset0:128 offset1:144
	v_mov_b32_e32 v65, v129
	v_add_u32_e32 v64, 0x80, v128
	v_lshlrev_b64 v[64:65], 12, v[64:65]
	v_lshl_add_u64 v[64:65], s[48:49], 0, v[64:65]
	v_lshl_add_u64 v[64:65], v[64:65], 0, s[18:19]
	s_waitcnt lgkmcnt(0)
	v_pk_mul_f32 v[68:69], v[78:79], v[66:67] op_sel_hi:[1,0]
	v_pk_mul_f32 v[70:71], v[76:77], v[66:67] op_sel_hi:[1,0]
	v_lshl_add_u64 v[64:65], v[64:65], 0, v[10:11]
	v_pk_mul_f32 v[52:53], v[52:53], v[66:67] op_sel_hi:[1,0]
	v_pk_mul_f32 v[54:55], v[54:55], v[66:67] op_sel_hi:[1,0]
	v_pk_mul_f32 v[48:49], v[48:49], v[66:67] op_sel_hi:[1,0]
	v_pk_mul_f32 v[50:51], v[50:51], v[66:67] op_sel_hi:[1,0]
	s_waitcnt vmcnt(0)
	v_pk_mul_f32 v[14:15], v[14:15], v[70:71]
	v_pk_mul_f32 v[12:13], v[12:13], v[68:69]
	global_store_dwordx4 v[64:65], v[12:15], off sc1
	global_load_dwordx4 v[12:15], v[8:9], off offset:64
	v_pk_mul_f32 v[68:69], v[72:73], v[66:67] op_sel_hi:[1,0]
	v_pk_mul_f32 v[70:71], v[74:75], v[66:67] op_sel_hi:[1,0]
	s_waitcnt vmcnt(0)
	v_pk_mul_f32 v[14:15], v[14:15], v[68:69]
	v_pk_mul_f32 v[12:13], v[12:13], v[70:71]
	global_store_dwordx4 v[64:65], v[12:15], off offset:64 sc1
	global_load_dwordx4 v[12:15], v[8:9], off offset:512
	s_waitcnt vmcnt(0)
	v_pk_mul_f32 v[12:13], v[12:13], v[54:55]
	v_pk_mul_f32 v[14:15], v[14:15], v[52:53]
	global_store_dwordx4 v[64:65], v[12:15], off offset:512 sc1
	global_load_dwordx4 v[12:15], v[8:9], off offset:576
	s_waitcnt vmcnt(0)
	v_pk_mul_f32 v[12:13], v[12:13], v[50:51]
	v_pk_mul_f32 v[14:15], v[14:15], v[48:49]
	global_store_dwordx4 v[64:65], v[12:15], off offset:576 sc1
	global_load_dwordx4 v[12:15], v[8:9], off
	v_mov_b32_e32 v49, v129
	v_add_u32_e32 v48, 0x90, v128
	v_lshlrev_b64 v[48:49], 12, v[48:49]
	v_lshl_add_u64 v[48:49], s[48:49], 0, v[48:49]
	v_mov_b32_e32 v50, v67
	v_lshl_add_u64 v[48:49], v[48:49], 0, s[18:19]
	v_pk_mul_f32 v[52:53], v[62:63], v[50:51] op_sel_hi:[1,0]
	v_pk_mul_f32 v[54:55], v[60:61], v[50:51] op_sel_hi:[1,0]
	v_lshl_add_u64 v[48:49], v[48:49], 0, v[10:11]
	v_pk_mul_f32 v[36:37], v[36:37], v[50:51] op_sel_hi:[1,0]
	v_pk_mul_f32 v[38:39], v[38:39], v[50:51] op_sel_hi:[1,0]
	v_pk_mul_f32 v[32:33], v[32:33], v[50:51] op_sel_hi:[1,0]
	v_pk_mul_f32 v[34:35], v[34:35], v[50:51] op_sel_hi:[1,0]
	s_waitcnt vmcnt(0)
; __device__ __forceinline__ void phaseG(const Params& p, const int wv, const int rep, unsigned* bar, const bool fused) {
;     ...
;       ACC_FOREACH({
;         const float rs = rstd_l[rrow];
;         const f32x4 wv4 = *(const f32x4*)(wfin + bcol + rcol);
;         *(f32x4*)(p.out + O_Y + (size_t)(brow + rrow) * 1024 + bcol + rcol) = v * rs * wv4;
;       });
	v_pk_mul_f32 v[14:15], v[14:15], v[54:55]
	v_pk_mul_f32 v[12:13], v[12:13], v[52:53]
	global_store_dwordx4 v[48:49], v[12:15], off sc1
	global_load_dwordx4 v[12:15], v[8:9], off offset:64
	v_pk_mul_f32 v[52:53], v[56:57], v[50:51] op_sel_hi:[1,0]
	v_pk_mul_f32 v[54:55], v[58:59], v[50:51] op_sel_hi:[1,0]
	s_waitcnt vmcnt(0)
	v_pk_mul_f32 v[14:15], v[14:15], v[52:53]
	v_pk_mul_f32 v[12:13], v[12:13], v[54:55]
	global_store_dwordx4 v[48:49], v[12:15], off offset:64 sc1
	global_load_dwordx4 v[12:15], v[8:9], off offset:512
	s_waitcnt vmcnt(0)
	v_pk_mul_f32 v[12:13], v[12:13], v[38:39]
	v_pk_mul_f32 v[14:15], v[14:15], v[36:37]
	global_store_dwordx4 v[48:49], v[12:15], off offset:512 sc1
	global_load_dwordx4 v[12:15], v[8:9], off offset:576
	s_waitcnt vmcnt(0)
	v_pk_mul_f32 v[12:13], v[12:13], v[34:35]
	v_pk_mul_f32 v[14:15], v[14:15], v[32:33]
	global_store_dwordx4 v[48:49], v[12:15], off offset:576 sc1
	global_load_dwordx4 v[12:15], v[8:9], off
	ds_read2_b32 v[34:35], v144 offset0:160 offset1:176
	v_mov_b32_e32 v33, v129
	v_add_u32_e32 v32, 0xa0, v128
	v_lshlrev_b64 v[32:33], 12, v[32:33]
	v_lshl_add_u64 v[32:33], s[48:49], 0, v[32:33]
	v_lshl_add_u64 v[32:33], v[32:33], 0, s[18:19]
	s_waitcnt lgkmcnt(0)
	v_pk_mul_f32 v[36:37], v[46:47], v[34:35] op_sel_hi:[1,0]
	v_pk_mul_f32 v[38:39], v[44:45], v[34:35] op_sel_hi:[1,0]
	v_lshl_add_u64 v[32:33], v[32:33], 0, v[10:11]
	v_pk_mul_f32 v[20:21], v[20:21], v[34:35] op_sel_hi:[1,0]
	v_pk_mul_f32 v[22:23], v[22:23], v[34:35] op_sel_hi:[1,0]
	v_pk_mul_f32 v[16:17], v[16:17], v[34:35] op_sel_hi:[1,0]
	v_pk_mul_f32 v[18:19], v[18:19], v[34:35] op_sel_hi:[1,0]
	v_add_u32_e32 v128, 0xb0, v128
	s_waitcnt vmcnt(0)
	v_pk_mul_f32 v[14:15], v[14:15], v[38:39]
	v_pk_mul_f32 v[12:13], v[12:13], v[36:37]
	global_store_dwordx4 v[32:33], v[12:15], off sc1
	global_load_dwordx4 v[12:15], v[8:9], off offset:64
	v_pk_mul_f32 v[36:37], v[40:41], v[34:35] op_sel_hi:[1,0]
	v_pk_mul_f32 v[38:39], v[42:43], v[34:35] op_sel_hi:[1,0]
	s_waitcnt vmcnt(0)
	v_pk_mul_f32 v[14:15], v[14:15], v[36:37]
	v_pk_mul_f32 v[12:13], v[12:13], v[38:39]
	global_store_dwordx4 v[32:33], v[12:15], off offset:64 sc1
	global_load_dwordx4 v[12:15], v[8:9], off offset:512
	s_waitcnt vmcnt(0)
	v_pk_mul_f32 v[12:13], v[12:13], v[22:23]
	v_pk_mul_f32 v[14:15], v[14:15], v[20:21]
	global_store_dwordx4 v[32:33], v[12:15], off offset:512 sc1
	global_load_dwordx4 v[12:15], v[8:9], off offset:576
	s_waitcnt vmcnt(0)
	v_pk_mul_f32 v[12:13], v[12:13], v[18:19]
	v_pk_mul_f32 v[14:15], v[14:15], v[16:17]
	global_store_dwordx4 v[32:33], v[12:15], off offset:576 sc1
	global_load_dwordx4 v[12:15], v[8:9], off
	v_lshlrev_b64 v[16:17], 12, v[128:129]
	v_lshl_add_u64 v[16:17], s[48:49], 0, v[16:17]
	v_lshl_add_u64 v[16:17], v[16:17], 0, s[18:19]
	v_mov_b32_e32 v18, v35
	v_lshl_add_u64 v[16:17], v[16:17], 0, v[10:11]
	v_pk_mul_f32 v[10:11], v[30:31], v[18:19] op_sel_hi:[1,0]
	v_pk_mul_f32 v[20:21], v[28:29], v[18:19] op_sel_hi:[1,0]
	s_waitcnt vmcnt(0)
	v_pk_mul_f32 v[12:13], v[12:13], v[10:11]
	v_pk_mul_f32 v[14:15], v[14:15], v[20:21]
	global_store_dwordx4 v[16:17], v[12:15], off sc1
	global_load_dwordx4 v[10:13], v[8:9], off offset:64
	v_pk_mul_f32 v[20:21], v[26:27], v[18:19] op_sel_hi:[1,0]
	v_pk_mul_f32 v[14:15], v[24:25], v[18:19] op_sel_hi:[1,0]
	s_waitcnt vmcnt(0)
	v_pk_mul_f32 v[10:11], v[10:11], v[20:21]
	v_pk_mul_f32 v[12:13], v[12:13], v[14:15]
	global_store_dwordx4 v[16:17], v[10:13], off offset:64 sc1
	global_load_dwordx4 v[10:13], v[8:9], off offset:512
	v_pk_mul_f32 v[14:15], v[4:5], v[18:19] op_sel_hi:[1,0]
	v_pk_mul_f32 v[4:5], v[6:7], v[18:19] op_sel_hi:[1,0]
	s_waitcnt vmcnt(0)
	v_pk_mul_f32 v[6:7], v[12:13], v[14:15]
	v_pk_mul_f32 v[4:5], v[10:11], v[4:5]
	global_store_dwordx4 v[16:17], v[4:7], off offset:512 sc1
	global_load_dwordx4 v[4:7], v[8:9], off offset:576
	v_pk_mul_f32 v[8:9], v[0:1], v[18:19] op_sel_hi:[1,0]
	v_pk_mul_f32 v[0:1], v[2:3], v[18:19] op_sel_hi:[1,0]
	s_waitcnt vmcnt(0)
	v_pk_mul_f32 v[2:3], v[6:7], v[8:9]
	v_pk_mul_f32 v[0:1], v[4:5], v[0:1]
	global_store_dwordx4 v[16:17], v[0:3], off offset:576 sc1

; __device__ __forceinline__ f32x4 unpack4(u32x2 w) { return (f32x4){bflo(w.x), bfhi(w.x), bflo(w.y), bfhi(w.y)}; }
; __device__ __forceinline__ void phaseG(const Params& p, const int wv, const int rep, unsigned* bar, const bool fused) {
;     ...
;       ACC_FOREACH({
;         const size_t o = (size_t)(brow + rrow) * 1024 + bcol + rcol;
;         *(f32x4*)(p.out + O_Y + o) = v + unpack4(*(const u32x2*)(H2 + o));
;       });
.LBB0_1142:
	s_lshl_b32 s87, s54, 8
	s_andn2_b64 vcc, exec, s[12:13]
	s_mov_b64 s[4:5], -1
	s_cbranch_vccnz .LBB0_1144
	v_mbcnt_lo_u32_b32 v128, -1, 0
	v_mbcnt_hi_u32_b32 v128, -1, v128
	s_add_i32 s4, s87, s65
	v_ashrrev_i32_e32 v130, 2, v128
	v_and_b32_e32 v130, -4, v130
	v_and_or_b32 v128, v128, 15, s4
	v_add_u32_e32 v132, s74, v130
	v_lshlrev_b64 v[142:143], 10, v[128:129]
	v_or_b32_e32 v142, s86, v142
	v_ashrrev_i32_e32 v133, 31, v132
	v_lshl_add_u64 v[130:131], v[142:143], 0, v[132:133]
	v_lshl_add_u64 v[134:135], v[130:131], 1, s[8:9]
	global_load_dwordx2 v[136:137], v[134:135], off
	v_add_u32_e32 v134, 16, v132
	v_ashrrev_i32_e32 v135, 31, v134
	v_lshl_add_u64 v[146:147], v[130:131], 2, s[48:49]
	v_lshl_add_u64 v[130:131], v[142:143], 0, v[134:135]
	v_lshl_add_u64 v[130:131], v[130:131], 1, s[8:9]
	s_mov_b64 s[4:5], 0
	s_waitcnt vmcnt(0)
	v_lshlrev_b32_e32 v144, 16, v136
	v_and_b32_e32 v145, 0xffff0000, v136
	v_lshlrev_b32_e32 v136, 16, v137
	v_and_b32_e32 v137, 0xffff0000, v137
	v_pk_add_f32 v[138:139], v[114:115], v[136:137]
	v_pk_add_f32 v[136:137], v[112:113], v[144:145]
	global_store_dwordx4 v[146:147], v[136:139], off sc1
	global_load_dwordx2 v[136:137], v[130:131], off
	v_add_u32_e32 v130, 0x80, v132
	v_ashrrev_i32_e32 v131, 31, v130
	v_lshl_add_u64 v[138:139], v[142:143], 0, v[130:131]
	v_lshl_add_u64 v[144:145], v[138:139], 1, s[8:9]
	s_waitcnt vmcnt(0)
	v_lshlrev_b32_e32 v148, 16, v136
	v_and_b32_e32 v149, 0xffff0000, v136
	v_lshlrev_b32_e32 v136, 16, v137
	v_and_b32_e32 v137, 0xffff0000, v137
	v_pk_add_f32 v[138:139], v[118:119], v[136:137]
	v_pk_add_f32 v[136:137], v[116:117], v[148:149]
	global_store_dwordx4 v[146:147], v[136:139], off offset:64 sc1
	global_load_dwordx2 v[138:139], v[144:145], off
	s_nop 0
	v_add_u32_e32 v136, 0x90, v132
	v_ashrrev_i32_e32 v137, 31, v136
	v_lshl_add_u64 v[142:143], v[142:143], 0, v[136:137]
	v_lshl_add_u64 v[148:149], v[142:143], 1, s[8:9]
	s_waitcnt vmcnt(0)
	v_lshlrev_b32_e32 v142, 16, v138
	v_and_b32_e32 v143, 0xffff0000, v138
	v_lshlrev_b32_e32 v138, 16, v139
	v_and_b32_e32 v139, 0xffff0000, v139
	v_pk_add_f32 v[144:145], v[122:123], v[138:139]
	v_pk_add_f32 v[142:143], v[120:121], v[142:143]
	global_store_dwordx4 v[146:147], v[142:145], off offset:512 sc1
	global_load_dwordx2 v[138:139], v[148:149], off
	s_nop 0
	v_mov_b32_e32 v143, v129
	v_or_b32_e32 v142, 16, v128
	v_lshlrev_b64 v[148:149], 10, v[142:143]
	v_or_b32_e32 v148, s86, v148
	v_lshl_add_u64 v[150:151], v[148:149], 0, v[132:133]
	v_lshl_add_u64 v[152:153], v[150:151], 1, s[8:9]
	s_waitcnt vmcnt(0)
	v_lshlrev_b32_e32 v142, 16, v138
	v_and_b32_e32 v143, 0xffff0000, v138
	v_lshlrev_b32_e32 v138, 16, v139
	v_and_b32_e32 v139, 0xffff0000, v139
	v_pk_add_f32 v[144:145], v[126:127], v[138:139]
	v_pk_add_f32 v[142:143], v[124:125], v[142:143]
	global_store_dwordx4 v[146:147], v[142:145], off offset:576 sc1
	global_load_dwordx2 v[138:139], v[152:153], off
	v_lshl_add_u64 v[146:147], v[150:151], 2, s[48:49]
	v_lshl_add_u64 v[142:143], v[148:149], 0, v[134:135]
	v_lshl_add_u64 v[150:151], v[142:143], 1, s[8:9]
	s_waitcnt vmcnt(0)
	v_lshlrev_b32_e32 v142, 16, v138
	v_and_b32_e32 v143, 0xffff0000, v138
	v_lshlrev_b32_e32 v138, 16, v139
	v_and_b32_e32 v139, 0xffff0000, v139
	v_pk_add_f32 v[144:145], v[98:99], v[138:139]
	v_pk_add_f32 v[142:143], v[96:97], v[142:143]
	global_store_dwordx4 v[146:147], v[142:145], off sc1
	global_load_dwordx2 v[138:139], v[150:151], off
	s_nop 0
	v_lshl_add_u64 v[142:143], v[148:149], 0, v[130:131]
	v_lshl_add_u64 v[150:151], v[142:143], 1, s[8:9]
	s_waitcnt vmcnt(0)
	v_lshlrev_b32_e32 v142, 16, v138
	v_and_b32_e32 v143, 0xffff0000, v138
	v_lshlrev_b32_e32 v138, 16, v139
	v_and_b32_e32 v139, 0xffff0000, v139
	v_pk_add_f32 v[144:145], v[102:103], v[138:139]
	v_pk_add_f32 v[142:143], v[100:101], v[142:143]
	global_store_dwordx4 v[146:147], v[142:145], off offset:64 sc1
	global_load_dwordx2 v[138:139], v[150:151], off
	s_nop 0
	v_lshl_add_u64 v[142:143], v[148:149], 0, v[136:137]
	v_lshl_add_u64 v[148:149], v[142:143], 1, s[8:9]
	s_waitcnt vmcnt(0)
	v_lshlrev_b32_e32 v142, 16, v138
	v_and_b32_e32 v143, 0xffff0000, v138
	v_lshlrev_b32_e32 v138, 16, v139
	v_and_b32_e32 v139, 0xffff0000, v139
	v_pk_add_f32 v[144:145], v[106:107], v[138:139]
	v_pk_add_f32 v[142:143], v[104:105], v[142:143]
	global_store_dwordx4 v[146:147], v[142:145], off offset:512 sc1
	global_load_dwordx2 v[138:139], v[148:149], off
	s_nop 0
	v_mov_b32_e32 v143, v129
	v_or_b32_e32 v142, 32, v128
	v_lshlrev_b64 v[148:149], 10, v[142:143]
	v_or_b32_e32 v148, s86, v148
	v_lshl_add_u64 v[150:151], v[148:149], 0, v[132:133]
	v_lshl_add_u64 v[152:153], v[150:151], 1, s[8:9]
	s_waitcnt vmcnt(0)
	v_lshlrev_b32_e32 v142, 16, v138
	v_and_b32_e32 v143, 0xffff0000, v138
	v_lshlrev_b32_e32 v138, 16, v139
	v_and_b32_e32 v139, 0xffff0000, v139
	v_pk_add_f32 v[144:145], v[110:111], v[138:139]
	v_pk_add_f32 v[142:143], v[108:109], v[142:143]
	global_store_dwordx4 v[146:147], v[142:145], off offset:576 sc1
	global_load_dwordx2 v[138:139], v[152:153], off
	v_lshl_add_u64 v[146:147], v[150:151], 2, s[48:49]
	v_lshl_add_u64 v[142:143], v[148:149], 0, v[134:135]
	v_lshl_add_u64 v[150:151], v[142:143], 1, s[8:9]
	s_waitcnt vmcnt(0)
	v_lshlrev_b32_e32 v142, 16, v138
	v_and_b32_e32 v143, 0xffff0000, v138
	v_lshlrev_b32_e32 v138, 16, v139
	v_and_b32_e32 v139, 0xffff0000, v139
	v_pk_add_f32 v[144:145], v[82:83], v[138:139]
	v_pk_add_f32 v[142:143], v[80:81], v[142:143]
	global_store_dwordx4 v[146:147], v[142:145], off sc1
	global_load_dwordx2 v[138:139], v[150:151], off
	s_nop 0
	v_lshl_add_u64 v[142:143], v[148:149], 0, v[130:131]
	v_lshl_add_u64 v[150:151], v[142:143], 1, s[8:9]
	s_waitcnt vmcnt(0)
; __device__ __forceinline__ f32x4 unpack4(u32x2 w) { return (f32x4){bflo(w.x), bfhi(w.x), bflo(w.y), bfhi(w.y)}; }
; __device__ __forceinline__ void phaseG(const Params& p, const int wv, const int rep, unsigned* bar, const bool fused) {
;     ...
;       ACC_FOREACH({
;         const size_t o = (size_t)(brow + rrow) * 1024 + bcol + rcol;
;         *(f32x4*)(p.out + O_Y + o) = v + unpack4(*(const u32x2*)(H2 + o));
;       });
	v_lshlrev_b32_e32 v142, 16, v138
	v_and_b32_e32 v143, 0xffff0000, v138
	v_lshlrev_b32_e32 v138, 16, v139
	v_and_b32_e32 v139, 0xffff0000, v139
	v_pk_add_f32 v[144:145], v[86:87], v[138:139]
	v_pk_add_f32 v[142:143], v[84:85], v[142:143]
	global_store_dwordx4 v[146:147], v[142:145], off offset:64 sc1
	global_load_dwordx2 v[138:139], v[150:151], off
	s_nop 0
	v_lshl_add_u64 v[142:143], v[148:149], 0, v[136:137]
	v_lshl_add_u64 v[148:149], v[142:143], 1, s[8:9]
	s_waitcnt vmcnt(0)
	v_lshlrev_b32_e32 v142, 16, v138
	v_and_b32_e32 v143, 0xffff0000, v138
	v_lshlrev_b32_e32 v138, 16, v139
	v_and_b32_e32 v139, 0xffff0000, v139
	v_pk_add_f32 v[144:145], v[90:91], v[138:139]
	v_pk_add_f32 v[142:143], v[88:89], v[142:143]
	global_store_dwordx4 v[146:147], v[142:145], off offset:512 sc1
	global_load_dwordx2 v[138:139], v[148:149], off
	s_nop 0
	v_mov_b32_e32 v143, v129
	v_or_b32_e32 v142, 48, v128
	v_lshlrev_b64 v[148:149], 10, v[142:143]
	v_or_b32_e32 v148, s86, v148
	v_lshl_add_u64 v[150:151], v[148:149], 0, v[132:133]
	v_lshl_add_u64 v[152:153], v[150:151], 1, s[8:9]
	s_waitcnt vmcnt(0)
	v_lshlrev_b32_e32 v142, 16, v138
	v_and_b32_e32 v143, 0xffff0000, v138
	v_lshlrev_b32_e32 v138, 16, v139
	v_and_b32_e32 v139, 0xffff0000, v139
	v_pk_add_f32 v[144:145], v[94:95], v[138:139]
	v_pk_add_f32 v[142:143], v[92:93], v[142:143]
	global_store_dwordx4 v[146:147], v[142:145], off offset:576 sc1
	global_load_dwordx2 v[138:139], v[152:153], off
	v_lshl_add_u64 v[146:147], v[150:151], 2, s[48:49]
	v_lshl_add_u64 v[142:143], v[148:149], 0, v[134:135]
	v_lshl_add_u64 v[150:151], v[142:143], 1, s[8:9]
	s_waitcnt vmcnt(0)
	v_lshlrev_b32_e32 v142, 16, v138
	v_and_b32_e32 v143, 0xffff0000, v138
	v_lshlrev_b32_e32 v138, 16, v139
	v_and_b32_e32 v139, 0xffff0000, v139
	v_pk_add_f32 v[144:145], v[66:67], v[138:139]
	v_pk_add_f32 v[142:143], v[64:65], v[142:143]
	global_store_dwordx4 v[146:147], v[142:145], off sc1
	global_load_dwordx2 v[138:139], v[150:151], off
	s_nop 0
	v_lshl_add_u64 v[142:143], v[148:149], 0, v[130:131]
	v_lshl_add_u64 v[150:151], v[142:143], 1, s[8:9]
	s_waitcnt vmcnt(0)
	v_lshlrev_b32_e32 v142, 16, v138
	v_and_b32_e32 v143, 0xffff0000, v138
	v_lshlrev_b32_e32 v138, 16, v139
	v_and_b32_e32 v139, 0xffff0000, v139
	v_pk_add_f32 v[144:145], v[70:71], v[138:139]
	v_pk_add_f32 v[142:143], v[68:69], v[142:143]
	global_store_dwordx4 v[146:147], v[142:145], off offset:64 sc1
	global_load_dwordx2 v[138:139], v[150:151], off
	s_nop 0
	v_lshl_add_u64 v[142:143], v[148:149], 0, v[136:137]
	v_lshl_add_u64 v[148:149], v[142:143], 1, s[8:9]
	s_waitcnt vmcnt(0)
	v_lshlrev_b32_e32 v142, 16, v138
	v_and_b32_e32 v143, 0xffff0000, v138
	v_lshlrev_b32_e32 v138, 16, v139
	v_and_b32_e32 v139, 0xffff0000, v139
	v_pk_add_f32 v[144:145], v[74:75], v[138:139]
	v_pk_add_f32 v[142:143], v[72:73], v[142:143]
	global_store_dwordx4 v[146:147], v[142:145], off offset:512 sc1
	global_load_dwordx2 v[138:139], v[148:149], off
	s_nop 0
	v_mov_b32_e32 v143, v129
	v_add_u32_e32 v142, 0x80, v128
	v_lshlrev_b64 v[148:149], 10, v[142:143]
	v_or_b32_e32 v148, s86, v148
	v_lshl_add_u64 v[150:151], v[148:149], 0, v[132:133]
	v_lshl_add_u64 v[152:153], v[150:151], 1, s[8:9]
	s_waitcnt vmcnt(0)
	v_lshlrev_b32_e32 v142, 16, v138
	v_and_b32_e32 v143, 0xffff0000, v138
	v_lshlrev_b32_e32 v138, 16, v139
	v_and_b32_e32 v139, 0xffff0000, v139
	v_pk_add_f32 v[144:145], v[78:79], v[138:139]
	v_pk_add_f32 v[142:143], v[76:77], v[142:143]
	global_store_dwordx4 v[146:147], v[142:145], off offset:576 sc1
	global_load_dwordx2 v[138:139], v[152:153], off
	v_lshl_add_u64 v[146:147], v[150:151], 2, s[48:49]
	v_lshl_add_u64 v[142:143], v[148:149], 0, v[134:135]
	v_lshl_add_u64 v[150:151], v[142:143], 1, s[8:9]
	s_waitcnt vmcnt(0)
	v_lshlrev_b32_e32 v142, 16, v138
	v_and_b32_e32 v143, 0xffff0000, v138
	v_lshlrev_b32_e32 v138, 16, v139
	v_and_b32_e32 v139, 0xffff0000, v139
	v_pk_add_f32 v[144:145], v[50:51], v[138:139]
	v_pk_add_f32 v[142:143], v[48:49], v[142:143]
	global_store_dwordx4 v[146:147], v[142:145], off sc1
	global_load_dwordx2 v[138:139], v[150:151], off
	s_nop 0
	v_lshl_add_u64 v[142:143], v[148:149], 0, v[130:131]
	v_lshl_add_u64 v[150:151], v[142:143], 1, s[8:9]
	s_waitcnt vmcnt(0)
	v_lshlrev_b32_e32 v142, 16, v138
	v_and_b32_e32 v143, 0xffff0000, v138
	v_lshlrev_b32_e32 v138, 16, v139
	v_and_b32_e32 v139, 0xffff0000, v139
	v_pk_add_f32 v[144:145], v[54:55], v[138:139]
	v_pk_add_f32 v[142:143], v[52:53], v[142:143]
	global_store_dwordx4 v[146:147], v[142:145], off offset:64 sc1
	global_load_dwordx2 v[138:139], v[150:151], off
	s_nop 0
	v_lshl_add_u64 v[142:143], v[148:149], 0, v[136:137]
	v_lshl_add_u64 v[148:149], v[142:143], 1, s[8:9]
	s_waitcnt vmcnt(0)
	v_lshlrev_b32_e32 v142, 16, v138
	v_and_b32_e32 v143, 0xffff0000, v138
	v_lshlrev_b32_e32 v138, 16, v139
	v_and_b32_e32 v139, 0xffff0000, v139
	v_pk_add_f32 v[144:145], v[58:59], v[138:139]
	v_pk_add_f32 v[142:143], v[56:57], v[142:143]
	global_store_dwordx4 v[146:147], v[142:145], off offset:512 sc1
	global_load_dwordx2 v[138:139], v[148:149], off
	s_nop 0
	v_mov_b32_e32 v143, v129
	v_add_u32_e32 v142, 0x90, v128
	v_lshlrev_b64 v[148:149], 10, v[142:143]
	v_or_b32_e32 v148, s86, v148
	v_lshl_add_u64 v[150:151], v[148:149], 0, v[132:133]
	v_lshl_add_u64 v[152:153], v[150:151], 1, s[8:9]
	s_waitcnt vmcnt(0)
	v_lshlrev_b32_e32 v142, 16, v138
	v_and_b32_e32 v143, 0xffff0000, v138
	v_lshlrev_b32_e32 v138, 16, v139
	v_and_b32_e32 v139, 0xffff0000, v139
	v_pk_add_f32 v[144:145], v[62:63], v[138:139]
	v_pk_add_f32 v[142:143], v[60:61], v[142:143]
	global_store_dwordx4 v[146:147], v[142:145], off offset:576 sc1
	global_load_dwordx2 v[138:139], v[152:153], off
	v_lshl_add_u64 v[146:147], v[150:151], 2, s[48:49]
	v_lshl_add_u64 v[142:143], v[148:149], 0, v[134:135]
	v_lshl_add_u64 v[150:151], v[142:143], 1, s[8:9]
	s_waitcnt vmcnt(0)
; __device__ __forceinline__ f32x4 unpack4(u32x2 w) { return (f32x4){bflo(w.x), bfhi(w.x), bflo(w.y), bfhi(w.y)}; }
; __device__ __forceinline__ void phaseG(const Params& p, const int wv, const int rep, unsigned* bar, const bool fused) {
;     ...
;       ACC_FOREACH({
;         const size_t o = (size_t)(brow + rrow) * 1024 + bcol + rcol;
;         *(f32x4*)(p.out + O_Y + o) = v + unpack4(*(const u32x2*)(H2 + o));
;       });
	v_lshlrev_b32_e32 v142, 16, v138
	v_and_b32_e32 v143, 0xffff0000, v138
	v_lshlrev_b32_e32 v138, 16, v139
	v_and_b32_e32 v139, 0xffff0000, v139
	v_pk_add_f32 v[144:145], v[34:35], v[138:139]
	v_pk_add_f32 v[142:143], v[32:33], v[142:143]
	global_store_dwordx4 v[146:147], v[142:145], off sc1
	global_load_dwordx2 v[138:139], v[150:151], off
	s_nop 0
	v_lshl_add_u64 v[142:143], v[148:149], 0, v[130:131]
	v_lshl_add_u64 v[150:151], v[142:143], 1, s[8:9]
	s_waitcnt vmcnt(0)
	v_lshlrev_b32_e32 v142, 16, v138
	v_and_b32_e32 v143, 0xffff0000, v138
	v_lshlrev_b32_e32 v138, 16, v139
	v_and_b32_e32 v139, 0xffff0000, v139
	v_pk_add_f32 v[144:145], v[38:39], v[138:139]
	v_pk_add_f32 v[142:143], v[36:37], v[142:143]
	global_store_dwordx4 v[146:147], v[142:145], off offset:64 sc1
	global_load_dwordx2 v[138:139], v[150:151], off
	s_nop 0
	v_lshl_add_u64 v[142:143], v[148:149], 0, v[136:137]
	v_lshl_add_u64 v[148:149], v[142:143], 1, s[8:9]
	s_waitcnt vmcnt(0)
	v_lshlrev_b32_e32 v142, 16, v138
	v_and_b32_e32 v143, 0xffff0000, v138
	v_lshlrev_b32_e32 v138, 16, v139
	v_and_b32_e32 v139, 0xffff0000, v139
	v_pk_add_f32 v[144:145], v[42:43], v[138:139]
	v_pk_add_f32 v[142:143], v[40:41], v[142:143]
	global_store_dwordx4 v[146:147], v[142:145], off offset:512 sc1
	global_load_dwordx2 v[138:139], v[148:149], off
	s_nop 0
	v_mov_b32_e32 v143, v129
	v_add_u32_e32 v142, 0xa0, v128
	v_lshlrev_b64 v[148:149], 10, v[142:143]
	v_or_b32_e32 v148, s86, v148
	v_lshl_add_u64 v[150:151], v[148:149], 0, v[132:133]
	v_lshl_add_u64 v[152:153], v[150:151], 1, s[8:9]
	v_add_u32_e32 v128, 0xb0, v128
	s_waitcnt vmcnt(0)
	v_lshlrev_b32_e32 v142, 16, v138
	v_and_b32_e32 v143, 0xffff0000, v138
	v_lshlrev_b32_e32 v138, 16, v139
	v_and_b32_e32 v139, 0xffff0000, v139
	v_pk_add_f32 v[144:145], v[46:47], v[138:139]
	v_pk_add_f32 v[142:143], v[44:45], v[142:143]
	global_store_dwordx4 v[146:147], v[142:145], off offset:576 sc1
	global_load_dwordx2 v[138:139], v[152:153], off
	v_lshl_add_u64 v[146:147], v[150:151], 2, s[48:49]
	v_lshl_add_u64 v[142:143], v[148:149], 0, v[134:135]
	v_lshl_add_u64 v[150:151], v[142:143], 1, s[8:9]
	s_waitcnt vmcnt(0)
	v_lshlrev_b32_e32 v142, 16, v138
	v_and_b32_e32 v143, 0xffff0000, v138
	v_lshlrev_b32_e32 v138, 16, v139
	v_and_b32_e32 v139, 0xffff0000, v139
	v_pk_add_f32 v[144:145], v[18:19], v[138:139]
	v_pk_add_f32 v[142:143], v[16:17], v[142:143]
	global_store_dwordx4 v[146:147], v[142:145], off sc1
	global_load_dwordx2 v[138:139], v[150:151], off
	s_nop 0
	v_lshl_add_u64 v[142:143], v[148:149], 0, v[130:131]
	v_lshl_add_u64 v[150:151], v[142:143], 1, s[8:9]
	s_waitcnt vmcnt(0)
	v_lshlrev_b32_e32 v142, 16, v138
	v_and_b32_e32 v143, 0xffff0000, v138
	v_lshlrev_b32_e32 v138, 16, v139
	v_and_b32_e32 v139, 0xffff0000, v139
	v_pk_add_f32 v[144:145], v[22:23], v[138:139]
	v_pk_add_f32 v[142:143], v[20:21], v[142:143]
	global_store_dwordx4 v[146:147], v[142:145], off offset:64 sc1
	global_load_dwordx2 v[138:139], v[150:151], off
	s_nop 0
	v_lshl_add_u64 v[142:143], v[148:149], 0, v[136:137]
	v_lshl_add_u64 v[148:149], v[142:143], 1, s[8:9]
	s_waitcnt vmcnt(0)
	v_lshlrev_b32_e32 v142, 16, v138
	v_and_b32_e32 v143, 0xffff0000, v138
	v_lshlrev_b32_e32 v138, 16, v139
	v_and_b32_e32 v139, 0xffff0000, v139
	v_pk_add_f32 v[144:145], v[26:27], v[138:139]
	v_pk_add_f32 v[142:143], v[24:25], v[142:143]
	global_store_dwordx4 v[146:147], v[142:145], off offset:512 sc1
	global_load_dwordx2 v[138:139], v[148:149], off
	v_lshlrev_b64 v[148:149], 10, v[128:129]
	v_or_b32_e32 v148, s86, v148
	v_lshl_add_u64 v[132:133], v[148:149], 0, v[132:133]
	v_lshl_add_u64 v[150:151], v[132:133], 1, s[8:9]
	v_lshl_add_u64 v[130:131], v[148:149], 0, v[130:131]
	s_waitcnt vmcnt(0)
	v_lshlrev_b32_e32 v142, 16, v138
	v_and_b32_e32 v143, 0xffff0000, v138
	v_lshlrev_b32_e32 v138, 16, v139
	v_and_b32_e32 v139, 0xffff0000, v139
	v_pk_add_f32 v[144:145], v[30:31], v[138:139]
	v_pk_add_f32 v[142:143], v[28:29], v[142:143]
	global_store_dwordx4 v[146:147], v[142:145], off offset:576 sc1
	global_load_dwordx2 v[138:139], v[150:151], off
	s_nop 0
	v_lshl_add_u64 v[142:143], v[132:133], 2, s[48:49]
	v_lshl_add_u64 v[132:133], v[148:149], 0, v[134:135]
	v_lshl_add_u64 v[144:145], v[132:133], 1, s[8:9]
	s_waitcnt vmcnt(0)
	v_lshlrev_b32_e32 v132, 16, v138
	v_and_b32_e32 v133, 0xffff0000, v138
	v_lshlrev_b32_e32 v134, 16, v139
	v_and_b32_e32 v135, 0xffff0000, v139
	v_pk_add_f32 v[134:135], v[2:3], v[134:135]
	v_pk_add_f32 v[132:133], v[0:1], v[132:133]
	global_store_dwordx4 v[142:143], v[132:135], off sc1
	global_load_dwordx2 v[132:133], v[144:145], off
	s_nop 0
	v_lshl_add_u64 v[134:135], v[130:131], 1, s[8:9]
	s_waitcnt vmcnt(0)
	v_lshlrev_b32_e32 v130, 16, v132
	v_and_b32_e32 v131, 0xffff0000, v132
	v_lshlrev_b32_e32 v132, 16, v133
	v_and_b32_e32 v133, 0xffff0000, v133
	v_pk_add_f32 v[132:133], v[6:7], v[132:133]
	v_pk_add_f32 v[130:131], v[4:5], v[130:131]
	global_store_dwordx4 v[142:143], v[130:133], off offset:64 sc1
	global_load_dwordx2 v[130:131], v[134:135], off
	s_nop 0
	v_lshl_add_u64 v[132:133], v[148:149], 0, v[136:137]
	v_lshl_add_u64 v[134:135], v[132:133], 1, s[8:9]
	s_waitcnt vmcnt(0)
	v_lshlrev_b32_e32 v136, 16, v130
	v_and_b32_e32 v137, 0xffff0000, v130
	v_lshlrev_b32_e32 v130, 16, v131
	v_and_b32_e32 v131, 0xffff0000, v131
	v_pk_add_f32 v[132:133], v[10:11], v[130:131]
	v_pk_add_f32 v[130:131], v[8:9], v[136:137]
	global_store_dwordx4 v[142:143], v[130:133], off offset:512 sc1
	global_load_dwordx2 v[130:131], v[134:135], off
	s_waitcnt vmcnt(0)
	v_lshlrev_b32_e32 v134, 16, v130
	v_and_b32_e32 v135, 0xffff0000, v130
	v_lshlrev_b32_e32 v130, 16, v131
	v_and_b32_e32 v131, 0xffff0000, v131
	v_pk_add_f32 v[132:133], v[14:15], v[130:131]
	v_pk_add_f32 v[130:131], v[12:13], v[134:135]
	global_store_dwordx4 v[142:143], v[130:133], off offset:576 sc1
